# strategy 4: static s_setprio 1 for waves 4-7 at kernel start, all per-segment flips deleted (on v67)
# baseline (speedup 1.0000x reference)
_Z6mk_fwd4Args:
	s_load_dword s33, s[0:1], 0xa8
	s_mov_b32 s10, s2
	s_add_u32 s2, s0, 0xa8
	s_addc_u32 s3, s1, 0
	v_cmp_gt_u32_e32 vcc, 64, v0
	v_writelane_b32 v254, s2, 0
	s_nop 1
	v_writelane_b32 v254, s3, 1
	s_and_saveexec_b64 s[2:3], vcc
	v_lshl_add_u32 v1, v0, 2, 0
	v_add_u32_e32 v1, 0x25f00, v1
	v_mov_b32_e32 v2, 0
	ds_write_b32 v1, v2
	s_or_b64 exec, exec, s[2:3]
	s_load_dwordx2 s[60:61], s[0:1], 0xa0
	s_waitcnt lgkmcnt(0)
	s_barrier
	v_readfirstlane_b32 s11, v0
	s_lshr_b32 s11, s11, 6
	s_cmp_ge_u32 s11, 4
	s_cbranch_scc0 .Lmy_prio_done
	s_setprio 1
.Lmy_prio_done:
	s_getreg_b32 s2, hwreg(HW_REG_XCC_ID, 0, 4)
	s_and_b32 s62, s2, 15
	v_cmp_eq_u32_e64 s[96:97], 0, v0
	s_and_saveexec_b64 s[2:3], s[96:97]
	s_cbranch_execz .LBB0_5
	s_mov_b64 s[4:5], exec
	v_mbcnt_lo_u32_b32 v1, s4, 0
	v_mbcnt_hi_u32_b32 v1, s5, v1
	v_cmp_eq_u32_e32 vcc, 0, v1
	s_and_b64 s[6:7], exec, vcc
	s_mov_b64 exec, s[6:7]
	s_cbranch_execz .LBB0_5
	s_lshl_b32 s6, s62, 8
	s_bcnt1_i32_b64 s7, s[4:5]
	s_getpc_b64 s[4:5]
	s_add_u32 s4, s4, g_ctl@rel32@lo+5124
	s_addc_u32 s5, s5, g_ctl@rel32@hi+5132
	v_mov_b32_e32 v1, s6
	v_mov_b32_e32 v2, s7
	global_atomic_add v1, v2, s[4:5]

.LBB0_124:
	s_ashr_i32 s29, s28, 31
	s_lshl_b64 s[8:9], s[28:29], 19
	s_add_u32 s30, s16, s8
	s_addc_u32 s31, s79, s9
	s_and_b64 s[8:9], s[2:3], exec
	ds_read_b128 v[2:5], v141
	ds_read_b128 v[6:9], v141 offset:1024
	ds_read_b128 v[10:13], v141 offset:2048
	ds_read_b128 v[14:17], v141 offset:3072
	ds_read_b128 v[18:21], v142
	ds_read_b128 v[22:25], v142 offset:1024
	ds_read_b128 v[26:29], v142 offset:2048
	ds_read_b128 v[30:33], v142 offset:3072
	s_cselect_b32 s29, s31, s73
	s_cselect_b32 s93, s30, s72
	s_ashr_i32 s21, s20, 31
	s_lshl_b64 s[8:9], s[20:21], 19
	s_add_u32 s64, s17, s8
	s_addc_u32 s65, s19, s9
	s_and_b64 s[8:9], s[2:3], exec
	s_cselect_b32 s21, s65, s69
	s_cselect_b32 s94, s64, s68
	s_add_u32 s70, s72, 0x100
	s_addc_u32 s71, s73, 0
	s_add_u32 s8, s68, 0x100
	s_addc_u32 s9, s69, 0
	s_add_u32 s74, s72, 0x180
	s_addc_u32 s75, s73, 0
	s_add_u32 s12, s72, 0x40080
	s_addc_u32 s13, s73, 0
	s_add_i32 s95, s67, 0xc000
	v_mov_b32_e32 v232, v134
	s_mov_b32 m0, s95
	s_add_i32 s96, s67, 0xe000
	ds_read_b128 v[34:37], v143
	ds_read_b128 v[38:41], v143 offset:1024
	ds_read_b128 v[42:45], v143 offset:2048
	ds_read_b128 v[46:49], v143 offset:3072
	ds_read_b128 v[50:53], v143 offset:4096
	ds_read_b128 v[54:57], v143 offset:5120
	ds_read_b128 v[58:61], v143 offset:6144
	ds_read_b128 v[62:65], v143 offset:7168
	v_mov_b32_e32 v233, v136
	global_load_lds_dwordx4 v232, s[12:13]
	s_mov_b32 m0, s96
	s_add_u32 s76, s68, 0x180
	global_load_lds_dwordx4 v233, s[12:13]
	s_waitcnt vmcnt(8)
	s_waitcnt lgkmcnt(0)
	s_addc_u32 s77, s69, 0
	s_barrier
	s_waitcnt lgkmcnt(0)
	v_mfma_f32_16x16x32_bf16 v[66:69], v[2:5], v[34:37], 0
	v_mfma_f32_16x16x32_bf16 v[70:73], v[10:13], v[34:37], 0
	v_mfma_f32_16x16x32_bf16 v[74:77], v[2:5], v[42:45], 0
	v_mfma_f32_16x16x32_bf16 v[78:81], v[10:13], v[42:45], 0
	v_mfma_f32_16x16x32_bf16 v[82:85], v[2:5], v[50:53], 0
	v_mfma_f32_16x16x32_bf16 v[86:89], v[10:13], v[50:53], 0
	v_mfma_f32_16x16x32_bf16 v[90:93], v[2:5], v[58:61], 0
	v_mfma_f32_16x16x32_bf16 v[94:97], v[10:13], v[58:61], 0
	v_mfma_f32_16x16x32_bf16 v[66:69], v[6:9], v[38:41], v[66:69]
	v_mfma_f32_16x16x32_bf16 v[70:73], v[14:17], v[38:41], v[70:73]
	v_mfma_f32_16x16x32_bf16 v[74:77], v[6:9], v[46:49], v[74:77]
	v_mfma_f32_16x16x32_bf16 v[78:81], v[14:17], v[46:49], v[78:81]
	v_mfma_f32_16x16x32_bf16 v[82:85], v[6:9], v[54:57], v[82:85]
	v_mfma_f32_16x16x32_bf16 v[86:89], v[14:17], v[54:57], v[86:89]
	v_mfma_f32_16x16x32_bf16 v[90:93], v[6:9], v[62:65], v[90:93]
	v_mfma_f32_16x16x32_bf16 v[94:97], v[14:17], v[62:65], v[94:97]
	v_mfma_f32_16x16x32_bf16 v[98:101], v[18:21], v[34:37], 0
	v_mfma_f32_16x16x32_bf16 v[34:37], v[26:29], v[34:37], 0
	v_mfma_f32_16x16x32_bf16 v[102:105], v[18:21], v[42:45], 0
	v_mfma_f32_16x16x32_bf16 v[42:45], v[26:29], v[42:45], 0
	v_mfma_f32_16x16x32_bf16 v[106:109], v[18:21], v[50:53], 0
	v_mfma_f32_16x16x32_bf16 v[50:53], v[26:29], v[50:53], 0
	v_mfma_f32_16x16x32_bf16 v[110:113], v[18:21], v[58:61], 0
	v_mfma_f32_16x16x32_bf16 v[58:61], v[26:29], v[58:61], 0
	v_mfma_f32_16x16x32_bf16 v[118:121], v[22:25], v[38:41], v[98:101]
	v_mfma_f32_16x16x32_bf16 v[34:37], v[30:33], v[38:41], v[34:37]
	v_mfma_f32_16x16x32_bf16 v[38:41], v[22:25], v[46:49], v[102:105]
	v_mfma_f32_16x16x32_bf16 v[42:45], v[30:33], v[46:49], v[42:45]
	v_mfma_f32_16x16x32_bf16 v[46:49], v[22:25], v[54:57], v[106:109]
	v_mfma_f32_16x16x32_bf16 v[50:53], v[30:33], v[54:57], v[50:53]
	v_mfma_f32_16x16x32_bf16 v[54:57], v[22:25], v[62:65], v[110:113]
	v_mfma_f32_16x16x32_bf16 v[62:65], v[30:33], v[62:65], v[58:61]
	s_barrier
	s_add_i32 s97, s90, s63
	v_mov_b32_e32 v234, v135
	s_mov_b32 m0, s97
	s_add_i32 vcc_lo, s97, 0x2000
	ds_read_b128 v[58:61], v143 offset:16384
	ds_read_b128 v[98:101], v143 offset:17408
	ds_read_b128 v[102:105], v143 offset:18432
	ds_read_b128 v[106:109], v143 offset:19456
	ds_read_b128 v[110:113], v143 offset:20480
	ds_read_b128 v[114:117], v143 offset:21504
	ds_read_b128 v[122:125], v143 offset:22528
	ds_read_b128 v[126:129], v143 offset:23552
	v_mov_b32_e32 v235, v137
	global_load_lds_dwordx4 v234, s[8:9]
	s_mov_b32 m0, vcc_lo
	s_nop 0
	global_load_lds_dwordx4 v235, s[8:9]
	s_add_u32 s8, s68, 0x40100
	s_addc_u32 s9, s69, 0
	s_add_i32 vcc_hi, s91, s63
	s_mov_b32 m0, vcc_hi
	s_add_i32 s34, vcc_hi, 0x2000
	s_nop 0
	global_load_lds_dwordx4 v234, s[8:9]
	s_mov_b32 m0, s34
	s_nop 0
	global_load_lds_dwordx4 v235, s[8:9]
	s_mov_b64 s[8:9], s[70:71]
	s_mov_b32 m0, s67
	s_nop 0
	global_load_lds_dwordx4 v232, s[8:9]
	s_mov_b32 m0, s83
	s_nop 0
	global_load_lds_dwordx4 v233, s[8:9]
	s_waitcnt vmcnt(8)
	s_waitcnt lgkmcnt(0)
	s_barrier
	s_waitcnt lgkmcnt(0)
	v_mfma_f32_16x16x32_bf16 v[144:147], v[2:5], v[58:61], 0
	v_mfma_f32_16x16x32_bf16 v[148:151], v[10:13], v[58:61], 0
	v_mfma_f32_16x16x32_bf16 v[152:155], v[2:5], v[102:105], 0
	v_mfma_f32_16x16x32_bf16 v[156:159], v[10:13], v[102:105], 0
	v_mfma_f32_16x16x32_bf16 v[160:163], v[2:5], v[110:113], 0
	v_mfma_f32_16x16x32_bf16 v[164:167], v[10:13], v[110:113], 0
	v_mfma_f32_16x16x32_bf16 v[2:5], v[2:5], v[122:125], 0
	v_mfma_f32_16x16x32_bf16 v[10:13], v[10:13], v[122:125], 0
	v_mfma_f32_16x16x32_bf16 v[168:171], v[6:9], v[98:101], v[144:147]
	v_mfma_f32_16x16x32_bf16 v[146:149], v[14:17], v[98:101], v[148:151]
	v_mfma_f32_16x16x32_bf16 v[150:153], v[6:9], v[106:109], v[152:155]
	v_mfma_f32_16x16x32_bf16 v[154:157], v[14:17], v[106:109], v[156:159]
	v_mfma_f32_16x16x32_bf16 v[158:161], v[6:9], v[114:117], v[160:163]
	v_mfma_f32_16x16x32_bf16 v[2:5], v[6:9], v[126:129], v[2:5]
	v_mfma_f32_16x16x32_bf16 v[6:9], v[14:17], v[126:129], v[10:13]
	v_mfma_f32_16x16x32_bf16 v[162:165], v[14:17], v[114:117], v[164:167]
	v_mfma_f32_16x16x32_bf16 v[10:13], v[18:21], v[58:61], 0
	v_mfma_f32_16x16x32_bf16 v[14:17], v[26:29], v[58:61], 0
	v_mfma_f32_16x16x32_bf16 v[58:61], v[18:21], v[102:105], 0
	v_mfma_f32_16x16x32_bf16 v[102:105], v[26:29], v[102:105], 0
	v_mfma_f32_16x16x32_bf16 v[172:175], v[18:21], v[110:113], 0
	v_mfma_f32_16x16x32_bf16 v[110:113], v[26:29], v[110:113], 0
	v_mfma_f32_16x16x32_bf16 v[18:21], v[18:21], v[122:125], 0
	v_mfma_f32_16x16x32_bf16 v[26:29], v[26:29], v[122:125], 0
	v_mfma_f32_16x16x32_bf16 v[176:179], v[22:25], v[98:101], v[10:13]
	v_mfma_f32_16x16x32_bf16 v[14:17], v[30:33], v[98:101], v[14:17]
	v_mfma_f32_16x16x32_bf16 v[180:183], v[22:25], v[106:109], v[58:61]
	v_mfma_f32_16x16x32_bf16 v[184:187], v[30:33], v[106:109], v[102:105]
	v_mfma_f32_16x16x32_bf16 v[172:175], v[22:25], v[114:117], v[172:175]
	v_mfma_f32_16x16x32_bf16 v[188:191], v[30:33], v[114:117], v[110:113]
	v_mfma_f32_16x16x32_bf16 v[22:25], v[22:25], v[126:129], v[18:21]
	v_mfma_f32_16x16x32_bf16 v[30:33], v[30:33], v[126:129], v[26:29]
	s_barrier
	s_add_i32 s35, 0, 0x18000
	s_add_i32 s80, 0, 0x1c000
	v_add_u32_e32 v144, s35, v139
	v_add_u32_e32 v145, s80, v139
	ds_read_b128 v[10:13], v144
	ds_read_b128 v[192:195], v144 offset:1024
	ds_read_b128 v[18:21], v144 offset:2048
	ds_read_b128 v[196:199], v144 offset:3072
	ds_read_b128 v[200:203], v145
	ds_read_b128 v[204:207], v145 offset:1024
	ds_read_b128 v[208:211], v145 offset:2048
	ds_read_b128 v[212:215], v145 offset:3072
	s_add_u32 s8, s72, 0x40100
	s_addc_u32 s9, s73, 0
	s_mov_b32 m0, s84
	ds_read_b128 v[26:29], v143 offset:32768
	ds_read_b128 v[102:105], v143 offset:33792
	ds_read_b128 v[110:113], v143 offset:34816
	ds_read_b128 v[216:219], v143 offset:35840
	ds_read_b128 v[126:129], v143 offset:36864
	ds_read_b128 v[220:223], v143 offset:37888
	ds_read_b128 v[224:227], v143 offset:38912
	ds_read_b128 v[228:231], v143 offset:39936
	s_nop 0
	global_load_lds_dwordx4 v232, s[8:9]
	s_mov_b32 m0, s85
	s_nop 0
	global_load_lds_dwordx4 v233, s[8:9]
	s_waitcnt vmcnt(8)
	s_waitcnt lgkmcnt(0)
	s_barrier
	s_waitcnt lgkmcnt(0)
	v_mfma_f32_16x16x32_bf16 v[58:61], v[10:13], v[26:29], v[66:69]
	v_mfma_f32_16x16x32_bf16 v[66:69], v[18:21], v[26:29], v[70:73]
	v_mfma_f32_16x16x32_bf16 v[70:73], v[10:13], v[110:113], v[74:77]
	v_mfma_f32_16x16x32_bf16 v[74:77], v[18:21], v[110:113], v[78:81]
	v_mfma_f32_16x16x32_bf16 v[78:81], v[10:13], v[126:129], v[82:85]
	v_mfma_f32_16x16x32_bf16 v[82:85], v[18:21], v[126:129], v[86:89]
	v_mfma_f32_16x16x32_bf16 v[86:89], v[10:13], v[224:227], v[90:93]
	v_mfma_f32_16x16x32_bf16 v[94:97], v[18:21], v[224:227], v[94:97]
	v_mfma_f32_16x16x32_bf16 v[122:125], v[192:195], v[102:105], v[58:61]
	v_mfma_f32_16x16x32_bf16 v[114:117], v[196:199], v[102:105], v[66:69]
	v_mfma_f32_16x16x32_bf16 v[106:109], v[192:195], v[216:219], v[70:73]
	v_mfma_f32_16x16x32_bf16 v[98:101], v[196:199], v[216:219], v[74:77]
	v_mfma_f32_16x16x32_bf16 v[90:93], v[192:195], v[220:223], v[78:81]
	v_mfma_f32_16x16x32_bf16 v[82:85], v[196:199], v[220:223], v[82:85]
	v_mfma_f32_16x16x32_bf16 v[74:77], v[192:195], v[228:231], v[86:89]
	v_mfma_f32_16x16x32_bf16 v[58:61], v[196:199], v[228:231], v[94:97]
	v_mfma_f32_16x16x32_bf16 v[66:69], v[200:203], v[26:29], v[118:121]
	v_mfma_f32_16x16x32_bf16 v[26:29], v[208:211], v[26:29], v[34:37]
	v_mfma_f32_16x16x32_bf16 v[34:37], v[200:203], v[110:113], v[38:41]
	v_mfma_f32_16x16x32_bf16 v[38:41], v[208:211], v[110:113], v[42:45]
	v_mfma_f32_16x16x32_bf16 v[42:45], v[200:203], v[126:129], v[46:49]
	v_mfma_f32_16x16x32_bf16 v[46:49], v[208:211], v[126:129], v[50:53]
	v_mfma_f32_16x16x32_bf16 v[50:53], v[200:203], v[224:227], v[54:57]
	v_mfma_f32_16x16x32_bf16 v[54:57], v[208:211], v[224:227], v[62:65]
	v_mfma_f32_16x16x32_bf16 v[126:129], v[204:207], v[102:105], v[66:69]
	v_mfma_f32_16x16x32_bf16 v[118:121], v[212:215], v[102:105], v[26:29]
	v_mfma_f32_16x16x32_bf16 v[110:113], v[204:207], v[216:219], v[34:37]
	v_mfma_f32_16x16x32_bf16 v[102:105], v[212:215], v[216:219], v[38:41]
	v_mfma_f32_16x16x32_bf16 v[94:97], v[204:207], v[220:223], v[42:45]
	v_mfma_f32_16x16x32_bf16 v[86:89], v[212:215], v[220:223], v[46:49]
	v_mfma_f32_16x16x32_bf16 v[78:81], v[204:207], v[228:231], v[50:53]
	v_mfma_f32_16x16x32_bf16 v[66:69], v[212:215], v[228:231], v[54:57]
	s_barrier
	s_add_i32 s35, s35, s63
	s_add_i32 s11, s35, 0x2000
	s_mov_b32 m0, s35
	s_add_u32 s12, s68, 0x40180
	ds_read_b128 v[38:41], v143 offset:49152
	ds_read_b128 v[46:49], v143 offset:50176
	ds_read_b128 v[54:57], v143 offset:51200
	ds_read_b128 v[216:219], v143 offset:52224
	ds_read_b128 v[70:73], v143 offset:53248
	ds_read_b128 v[220:223], v143 offset:54272
	ds_read_b128 v[224:227], v143 offset:55296
	ds_read_b128 v[228:231], v143 offset:56320
	s_addc_u32 s13, s69, 0
	global_load_lds_dwordx4 v234, s[76:77]
	s_mov_b32 m0, s11
	s_add_i32 s80, s80, s63
	global_load_lds_dwordx4 v235, s[76:77]
	s_mov_b32 m0, s80
	s_add_i32 s8, s80, 0x2000
	s_nop 0
	global_load_lds_dwordx4 v234, s[12:13]
	s_mov_b32 m0, s8
	s_nop 0
	global_load_lds_dwordx4 v235, s[12:13]
	s_mov_b32 m0, s87
	s_nop 0
	global_load_lds_dwordx4 v232, s[74:75]
	s_mov_b32 m0, s88
	s_nop 0
	global_load_lds_dwordx4 v233, s[74:75]
	s_waitcnt vmcnt(8)
	s_waitcnt lgkmcnt(0)
	s_barrier
	s_waitcnt lgkmcnt(0)
	v_mfma_f32_16x16x32_bf16 v[26:29], v[10:13], v[38:41], v[168:171]
	v_mfma_f32_16x16x32_bf16 v[34:37], v[18:21], v[38:41], v[146:149]
	v_mfma_f32_16x16x32_bf16 v[42:45], v[10:13], v[54:57], v[150:153]
	v_mfma_f32_16x16x32_bf16 v[146:149], v[18:21], v[54:57], v[154:157]
	v_mfma_f32_16x16x32_bf16 v[150:153], v[10:13], v[70:73], v[158:161]
	v_mfma_f32_16x16x32_bf16 v[154:157], v[18:21], v[70:73], v[162:165]
	v_mfma_f32_16x16x32_bf16 v[2:5], v[10:13], v[224:227], v[2:5]
	v_mfma_f32_16x16x32_bf16 v[6:9], v[18:21], v[224:227], v[6:9]
	v_mfma_f32_16x16x32_bf16 v[62:65], v[192:195], v[46:49], v[26:29]
	v_mfma_f32_16x16x32_bf16 v[50:53], v[196:199], v[46:49], v[34:37]
	v_mfma_f32_16x16x32_bf16 v[42:45], v[192:195], v[216:219], v[42:45]
	v_mfma_f32_16x16x32_bf16 v[34:37], v[196:199], v[216:219], v[146:149]
	v_mfma_f32_16x16x32_bf16 v[26:29], v[192:195], v[220:223], v[150:153]
	v_mfma_f32_16x16x32_bf16 v[18:21], v[196:199], v[220:223], v[154:157]
	v_mfma_f32_16x16x32_bf16 v[10:13], v[192:195], v[228:231], v[2:5]
	v_mfma_f32_16x16x32_bf16 v[2:5], v[196:199], v[228:231], v[6:9]
	v_mfma_f32_16x16x32_bf16 v[6:9], v[200:203], v[38:41], v[176:179]
	v_mfma_f32_16x16x32_bf16 v[14:17], v[208:211], v[38:41], v[14:17]
	v_mfma_f32_16x16x32_bf16 v[38:41], v[200:203], v[54:57], v[180:183]
	v_mfma_f32_16x16x32_bf16 v[146:149], v[208:211], v[54:57], v[184:187]
	v_mfma_f32_16x16x32_bf16 v[150:153], v[200:203], v[70:73], v[172:175]
	v_mfma_f32_16x16x32_bf16 v[154:157], v[208:211], v[70:73], v[188:191]
	v_mfma_f32_16x16x32_bf16 v[158:161], v[200:203], v[224:227], v[22:25]
	v_mfma_f32_16x16x32_bf16 v[162:165], v[208:211], v[224:227], v[30:33]
	v_mfma_f32_16x16x32_bf16 v[70:73], v[204:207], v[46:49], v[6:9]
	v_mfma_f32_16x16x32_bf16 v[54:57], v[212:215], v[46:49], v[14:17]
	v_mfma_f32_16x16x32_bf16 v[46:49], v[204:207], v[216:219], v[38:41]
	v_mfma_f32_16x16x32_bf16 v[38:41], v[212:215], v[216:219], v[146:149]
	v_mfma_f32_16x16x32_bf16 v[30:33], v[204:207], v[220:223], v[150:153]
	v_mfma_f32_16x16x32_bf16 v[22:25], v[212:215], v[220:223], v[154:157]
	v_mfma_f32_16x16x32_bf16 v[14:17], v[204:207], v[228:231], v[158:161]
	v_mfma_f32_16x16x32_bf16 v[6:9], v[212:215], v[228:231], v[162:165]
	s_barrier
	s_add_u32 s9, s68, 0x200
	s_addc_u32 s78, s69, 0
	s_mov_b32 s62, 0
.LBB0_125:
	ds_read_b128 v[146:149], v141
	ds_read_b128 v[150:153], v141 offset:1024
	ds_read_b128 v[154:157], v141 offset:2048
	ds_read_b128 v[158:161], v141 offset:3072
	ds_read_b128 v[162:165], v142
	ds_read_b128 v[166:169], v142 offset:1024
	ds_read_b128 v[170:173], v142 offset:2048
	ds_read_b128 v[174:177], v142 offset:3072
	s_add_u32 s68, s70, 0x100
	s_addc_u32 s69, s71, 0
	s_cmp_eq_u32 s62, 12
	s_cselect_b32 s76, s93, s68
	s_cselect_b32 s77, s29, s69
	s_cselect_b32 s74, s94, s9
	s_cselect_b32 s75, s21, s78
	s_add_u32 s72, s76, 0x80
	s_addc_u32 s73, s77, 0
	s_add_u32 s12, s70, 0x40080
	s_mov_b32 m0, s95
	s_addc_u32 s13, s71, 0
	v_mov_b32_e32 v210, v134
	ds_read_b128 v[178:181], v143
	ds_read_b128 v[182:185], v143 offset:1024
	ds_read_b128 v[186:189], v143 offset:2048
	ds_read_b128 v[190:193], v143 offset:3072
	ds_read_b128 v[194:197], v143 offset:4096
	ds_read_b128 v[198:201], v143 offset:5120
	ds_read_b128 v[202:205], v143 offset:6144
	ds_read_b128 v[206:209], v143 offset:7168
	v_mov_b32_e32 v211, v136
	global_load_lds_dwordx4 v210, s[12:13]
	s_mov_b32 m0, s96
	s_add_u32 s70, s74, 0x80
	global_load_lds_dwordx4 v211, s[12:13]
	s_waitcnt vmcnt(8)
	s_waitcnt lgkmcnt(0)
	s_addc_u32 s71, s75, 0
	s_barrier
	s_waitcnt lgkmcnt(0)
	v_mfma_f32_16x16x32_bf16 v[122:125], v[146:149], v[178:181], v[122:125]
	v_mfma_f32_16x16x32_bf16 v[114:117], v[154:157], v[178:181], v[114:117]
	v_mfma_f32_16x16x32_bf16 v[106:109], v[146:149], v[186:189], v[106:109]
	v_mfma_f32_16x16x32_bf16 v[98:101], v[154:157], v[186:189], v[98:101]
	v_mfma_f32_16x16x32_bf16 v[90:93], v[146:149], v[194:197], v[90:93]
	v_mfma_f32_16x16x32_bf16 v[82:85], v[154:157], v[194:197], v[82:85]
	v_mfma_f32_16x16x32_bf16 v[74:77], v[146:149], v[202:205], v[74:77]
	v_mfma_f32_16x16x32_bf16 v[58:61], v[154:157], v[202:205], v[58:61]
	v_mfma_f32_16x16x32_bf16 v[122:125], v[150:153], v[182:185], v[122:125]
	v_mfma_f32_16x16x32_bf16 v[114:117], v[158:161], v[182:185], v[114:117]
	v_mfma_f32_16x16x32_bf16 v[106:109], v[150:153], v[190:193], v[106:109]
	v_mfma_f32_16x16x32_bf16 v[98:101], v[158:161], v[190:193], v[98:101]
	v_mfma_f32_16x16x32_bf16 v[90:93], v[150:153], v[198:201], v[90:93]
	v_mfma_f32_16x16x32_bf16 v[82:85], v[158:161], v[198:201], v[82:85]
	v_mfma_f32_16x16x32_bf16 v[74:77], v[150:153], v[206:209], v[74:77]
	v_mfma_f32_16x16x32_bf16 v[58:61], v[158:161], v[206:209], v[58:61]
	v_mfma_f32_16x16x32_bf16 v[126:129], v[162:165], v[178:181], v[126:129]
	v_mfma_f32_16x16x32_bf16 v[118:121], v[170:173], v[178:181], v[118:121]
	v_mfma_f32_16x16x32_bf16 v[110:113], v[162:165], v[186:189], v[110:113]
	v_mfma_f32_16x16x32_bf16 v[102:105], v[170:173], v[186:189], v[102:105]
	v_mfma_f32_16x16x32_bf16 v[94:97], v[162:165], v[194:197], v[94:97]
	v_mfma_f32_16x16x32_bf16 v[86:89], v[170:173], v[194:197], v[86:89]
	v_mfma_f32_16x16x32_bf16 v[78:81], v[162:165], v[202:205], v[78:81]
	v_mfma_f32_16x16x32_bf16 v[66:69], v[170:173], v[202:205], v[66:69]
	v_mfma_f32_16x16x32_bf16 v[126:129], v[166:169], v[182:185], v[126:129]
	v_mfma_f32_16x16x32_bf16 v[118:121], v[174:177], v[182:185], v[118:121]
	v_mfma_f32_16x16x32_bf16 v[110:113], v[166:169], v[190:193], v[110:113]
	v_mfma_f32_16x16x32_bf16 v[102:105], v[174:177], v[190:193], v[102:105]
	v_mfma_f32_16x16x32_bf16 v[94:97], v[166:169], v[198:201], v[94:97]
	v_mfma_f32_16x16x32_bf16 v[86:89], v[174:177], v[198:201], v[86:89]
	v_mfma_f32_16x16x32_bf16 v[78:81], v[166:169], v[206:209], v[78:81]
	v_mfma_f32_16x16x32_bf16 v[66:69], v[174:177], v[206:209], v[66:69]
	s_barrier
	s_mov_b32 m0, s97
	s_mov_b64 s[12:13], s[74:75]
	v_mov_b32_e32 v212, v135
	ds_read_b128 v[178:181], v143 offset:16384
	ds_read_b128 v[182:185], v143 offset:17408
	ds_read_b128 v[186:189], v143 offset:18432
	ds_read_b128 v[190:193], v143 offset:19456
	ds_read_b128 v[194:197], v143 offset:20480
	ds_read_b128 v[198:201], v143 offset:21504
	ds_read_b128 v[202:205], v143 offset:22528
	ds_read_b128 v[206:209], v143 offset:23552
	v_mov_b32_e32 v213, v137
	global_load_lds_dwordx4 v212, s[12:13]
	s_mov_b32 m0, vcc_lo
	s_nop 0
	global_load_lds_dwordx4 v213, s[12:13]
	s_add_u32 s12, s74, 0x40000
	s_addc_u32 s13, s75, 0
	s_mov_b32 m0, vcc_hi
	s_nop 0
	global_load_lds_dwordx4 v212, s[12:13]
	s_mov_b32 m0, s34
	s_nop 0
	global_load_lds_dwordx4 v213, s[12:13]
	s_mov_b64 s[12:13], s[76:77]
	s_mov_b32 m0, s67
	s_nop 0
	global_load_lds_dwordx4 v210, s[12:13]
	s_mov_b32 m0, s83
	s_nop 0
	global_load_lds_dwordx4 v211, s[12:13]
	s_waitcnt vmcnt(8)
	s_waitcnt lgkmcnt(0)
	s_barrier
	s_waitcnt lgkmcnt(0)
	v_mfma_f32_16x16x32_bf16 v[62:65], v[146:149], v[178:181], v[62:65]
	v_mfma_f32_16x16x32_bf16 v[50:53], v[154:157], v[178:181], v[50:53]
	v_mfma_f32_16x16x32_bf16 v[42:45], v[146:149], v[186:189], v[42:45]
	v_mfma_f32_16x16x32_bf16 v[34:37], v[154:157], v[186:189], v[34:37]
	v_mfma_f32_16x16x32_bf16 v[26:29], v[146:149], v[194:197], v[26:29]
	v_mfma_f32_16x16x32_bf16 v[18:21], v[154:157], v[194:197], v[18:21]
	v_mfma_f32_16x16x32_bf16 v[10:13], v[146:149], v[202:205], v[10:13]
	v_mfma_f32_16x16x32_bf16 v[2:5], v[154:157], v[202:205], v[2:5]
	v_mfma_f32_16x16x32_bf16 v[62:65], v[150:153], v[182:185], v[62:65]
	v_mfma_f32_16x16x32_bf16 v[50:53], v[158:161], v[182:185], v[50:53]
	v_mfma_f32_16x16x32_bf16 v[42:45], v[150:153], v[190:193], v[42:45]
	v_mfma_f32_16x16x32_bf16 v[34:37], v[158:161], v[190:193], v[34:37]
	v_mfma_f32_16x16x32_bf16 v[26:29], v[150:153], v[198:201], v[26:29]
	v_mfma_f32_16x16x32_bf16 v[18:21], v[158:161], v[198:201], v[18:21]
	v_mfma_f32_16x16x32_bf16 v[10:13], v[150:153], v[206:209], v[10:13]
	v_mfma_f32_16x16x32_bf16 v[2:5], v[158:161], v[206:209], v[2:5]
	v_mfma_f32_16x16x32_bf16 v[70:73], v[162:165], v[178:181], v[70:73]
	v_mfma_f32_16x16x32_bf16 v[54:57], v[170:173], v[178:181], v[54:57]
	v_mfma_f32_16x16x32_bf16 v[46:49], v[162:165], v[186:189], v[46:49]
	v_mfma_f32_16x16x32_bf16 v[38:41], v[170:173], v[186:189], v[38:41]
	v_mfma_f32_16x16x32_bf16 v[30:33], v[162:165], v[194:197], v[30:33]
	v_mfma_f32_16x16x32_bf16 v[22:25], v[170:173], v[194:197], v[22:25]
	v_mfma_f32_16x16x32_bf16 v[14:17], v[162:165], v[202:205], v[14:17]
	v_mfma_f32_16x16x32_bf16 v[6:9], v[170:173], v[202:205], v[6:9]
	v_mfma_f32_16x16x32_bf16 v[70:73], v[166:169], v[182:185], v[70:73]
	v_mfma_f32_16x16x32_bf16 v[54:57], v[174:177], v[182:185], v[54:57]
	v_mfma_f32_16x16x32_bf16 v[46:49], v[166:169], v[190:193], v[46:49]
	v_mfma_f32_16x16x32_bf16 v[38:41], v[174:177], v[190:193], v[38:41]
	v_mfma_f32_16x16x32_bf16 v[30:33], v[166:169], v[198:201], v[30:33]
	v_mfma_f32_16x16x32_bf16 v[22:25], v[174:177], v[198:201], v[22:25]
	v_mfma_f32_16x16x32_bf16 v[14:17], v[166:169], v[206:209], v[14:17]
	v_mfma_f32_16x16x32_bf16 v[6:9], v[174:177], v[206:209], v[6:9]
	s_barrier
	ds_read_b128 v[146:149], v144
	ds_read_b128 v[150:153], v144 offset:1024
	ds_read_b128 v[154:157], v144 offset:2048
	ds_read_b128 v[158:161], v144 offset:3072
	ds_read_b128 v[162:165], v145
	ds_read_b128 v[166:169], v145 offset:1024
	ds_read_b128 v[170:173], v145 offset:2048
	ds_read_b128 v[174:177], v145 offset:3072
	s_add_u32 s12, s76, 0x40000
	s_addc_u32 s13, s77, 0
	s_mov_b32 m0, s84
	ds_read_b128 v[178:181], v143 offset:32768
	ds_read_b128 v[182:185], v143 offset:33792
	ds_read_b128 v[186:189], v143 offset:34816
	ds_read_b128 v[190:193], v143 offset:35840
	ds_read_b128 v[194:197], v143 offset:36864
	ds_read_b128 v[198:201], v143 offset:37888
	ds_read_b128 v[202:205], v143 offset:38912
	ds_read_b128 v[206:209], v143 offset:39936
	s_nop 0
	global_load_lds_dwordx4 v210, s[12:13]
	s_mov_b32 m0, s85
	s_nop 0
	global_load_lds_dwordx4 v211, s[12:13]
	s_waitcnt vmcnt(8)
	s_waitcnt lgkmcnt(0)
	s_barrier
	s_waitcnt lgkmcnt(0)
	v_mfma_f32_16x16x32_bf16 v[122:125], v[146:149], v[178:181], v[122:125]
	v_mfma_f32_16x16x32_bf16 v[114:117], v[154:157], v[178:181], v[114:117]
	v_mfma_f32_16x16x32_bf16 v[106:109], v[146:149], v[186:189], v[106:109]
	v_mfma_f32_16x16x32_bf16 v[98:101], v[154:157], v[186:189], v[98:101]
	v_mfma_f32_16x16x32_bf16 v[90:93], v[146:149], v[194:197], v[90:93]
	v_mfma_f32_16x16x32_bf16 v[82:85], v[154:157], v[194:197], v[82:85]
	v_mfma_f32_16x16x32_bf16 v[74:77], v[146:149], v[202:205], v[74:77]
	v_mfma_f32_16x16x32_bf16 v[58:61], v[154:157], v[202:205], v[58:61]
	v_mfma_f32_16x16x32_bf16 v[122:125], v[150:153], v[182:185], v[122:125]
	v_mfma_f32_16x16x32_bf16 v[114:117], v[158:161], v[182:185], v[114:117]
	v_mfma_f32_16x16x32_bf16 v[106:109], v[150:153], v[190:193], v[106:109]
	v_mfma_f32_16x16x32_bf16 v[98:101], v[158:161], v[190:193], v[98:101]
	v_mfma_f32_16x16x32_bf16 v[90:93], v[150:153], v[198:201], v[90:93]
	v_mfma_f32_16x16x32_bf16 v[82:85], v[158:161], v[198:201], v[82:85]
	v_mfma_f32_16x16x32_bf16 v[74:77], v[150:153], v[206:209], v[74:77]
	v_mfma_f32_16x16x32_bf16 v[58:61], v[158:161], v[206:209], v[58:61]
	v_mfma_f32_16x16x32_bf16 v[126:129], v[162:165], v[178:181], v[126:129]
	v_mfma_f32_16x16x32_bf16 v[118:121], v[170:173], v[178:181], v[118:121]
	v_mfma_f32_16x16x32_bf16 v[110:113], v[162:165], v[186:189], v[110:113]
	v_mfma_f32_16x16x32_bf16 v[102:105], v[170:173], v[186:189], v[102:105]
	v_mfma_f32_16x16x32_bf16 v[94:97], v[162:165], v[194:197], v[94:97]
	v_mfma_f32_16x16x32_bf16 v[86:89], v[170:173], v[194:197], v[86:89]
	v_mfma_f32_16x16x32_bf16 v[78:81], v[162:165], v[202:205], v[78:81]
	v_mfma_f32_16x16x32_bf16 v[66:69], v[170:173], v[202:205], v[66:69]
	v_mfma_f32_16x16x32_bf16 v[126:129], v[166:169], v[182:185], v[126:129]
	v_mfma_f32_16x16x32_bf16 v[118:121], v[174:177], v[182:185], v[118:121]
	v_mfma_f32_16x16x32_bf16 v[110:113], v[166:169], v[190:193], v[110:113]
	v_mfma_f32_16x16x32_bf16 v[102:105], v[174:177], v[190:193], v[102:105]
	v_mfma_f32_16x16x32_bf16 v[94:97], v[166:169], v[198:201], v[94:97]
	v_mfma_f32_16x16x32_bf16 v[86:89], v[174:177], v[198:201], v[86:89]
	v_mfma_f32_16x16x32_bf16 v[78:81], v[166:169], v[206:209], v[78:81]
	v_mfma_f32_16x16x32_bf16 v[66:69], v[174:177], v[206:209], v[66:69]
	s_barrier
	s_mov_b32 m0, s35
	ds_read_b128 v[178:181], v143 offset:49152
	ds_read_b128 v[182:185], v143 offset:50176
	ds_read_b128 v[186:189], v143 offset:51200
	ds_read_b128 v[190:193], v143 offset:52224
	ds_read_b128 v[194:197], v143 offset:53248
	ds_read_b128 v[198:201], v143 offset:54272
	ds_read_b128 v[202:205], v143 offset:55296
	ds_read_b128 v[206:209], v143 offset:56320
	s_add_u32 s12, s74, 0x40080
	global_load_lds_dwordx4 v212, s[70:71]
	s_mov_b32 m0, s11
	s_addc_u32 s13, s75, 0
	global_load_lds_dwordx4 v213, s[70:71]
	s_mov_b32 m0, s80
	s_nop 0
	global_load_lds_dwordx4 v212, s[12:13]
	s_mov_b32 m0, s8
	s_nop 0
	global_load_lds_dwordx4 v213, s[12:13]
	s_mov_b32 m0, s87
	s_nop 0
	global_load_lds_dwordx4 v210, s[72:73]
	s_mov_b32 m0, s88
	s_nop 0
	global_load_lds_dwordx4 v211, s[72:73]
	s_waitcnt vmcnt(8)
	s_waitcnt lgkmcnt(0)
	s_barrier
	s_waitcnt lgkmcnt(0)
	v_mfma_f32_16x16x32_bf16 v[62:65], v[146:149], v[178:181], v[62:65]
	v_mfma_f32_16x16x32_bf16 v[50:53], v[154:157], v[178:181], v[50:53]
	v_mfma_f32_16x16x32_bf16 v[42:45], v[146:149], v[186:189], v[42:45]
	v_mfma_f32_16x16x32_bf16 v[34:37], v[154:157], v[186:189], v[34:37]
	v_mfma_f32_16x16x32_bf16 v[26:29], v[146:149], v[194:197], v[26:29]
	v_mfma_f32_16x16x32_bf16 v[18:21], v[154:157], v[194:197], v[18:21]
	v_mfma_f32_16x16x32_bf16 v[10:13], v[146:149], v[202:205], v[10:13]
	v_mfma_f32_16x16x32_bf16 v[2:5], v[154:157], v[202:205], v[2:5]
	v_mfma_f32_16x16x32_bf16 v[62:65], v[150:153], v[182:185], v[62:65]
	v_mfma_f32_16x16x32_bf16 v[50:53], v[158:161], v[182:185], v[50:53]
	v_mfma_f32_16x16x32_bf16 v[42:45], v[150:153], v[190:193], v[42:45]
	v_mfma_f32_16x16x32_bf16 v[34:37], v[158:161], v[190:193], v[34:37]
	v_mfma_f32_16x16x32_bf16 v[26:29], v[150:153], v[198:201], v[26:29]
	v_mfma_f32_16x16x32_bf16 v[18:21], v[158:161], v[198:201], v[18:21]
	v_mfma_f32_16x16x32_bf16 v[10:13], v[150:153], v[206:209], v[10:13]
	v_mfma_f32_16x16x32_bf16 v[2:5], v[158:161], v[206:209], v[2:5]
	v_mfma_f32_16x16x32_bf16 v[70:73], v[162:165], v[178:181], v[70:73]
	v_mfma_f32_16x16x32_bf16 v[54:57], v[170:173], v[178:181], v[54:57]
	v_mfma_f32_16x16x32_bf16 v[46:49], v[162:165], v[186:189], v[46:49]
	v_mfma_f32_16x16x32_bf16 v[38:41], v[170:173], v[186:189], v[38:41]
	v_mfma_f32_16x16x32_bf16 v[30:33], v[162:165], v[194:197], v[30:33]
	v_mfma_f32_16x16x32_bf16 v[22:25], v[170:173], v[194:197], v[22:25]
	v_mfma_f32_16x16x32_bf16 v[14:17], v[162:165], v[202:205], v[14:17]
	v_mfma_f32_16x16x32_bf16 v[6:9], v[170:173], v[202:205], v[6:9]
	v_mfma_f32_16x16x32_bf16 v[70:73], v[166:169], v[182:185], v[70:73]
	v_mfma_f32_16x16x32_bf16 v[54:57], v[174:177], v[182:185], v[54:57]
	v_mfma_f32_16x16x32_bf16 v[46:49], v[166:169], v[190:193], v[46:49]
	v_mfma_f32_16x16x32_bf16 v[38:41], v[174:177], v[190:193], v[38:41]
	v_mfma_f32_16x16x32_bf16 v[30:33], v[166:169], v[198:201], v[30:33]
	v_mfma_f32_16x16x32_bf16 v[22:25], v[174:177], v[198:201], v[22:25]
	v_mfma_f32_16x16x32_bf16 v[14:17], v[166:169], v[206:209], v[14:17]
	v_mfma_f32_16x16x32_bf16 v[6:9], v[174:177], v[206:209], v[6:9]
	s_barrier
	s_add_i32 s62, s62, 2
	s_add_u32 s9, s9, 0x100
	s_addc_u32 s78, s78, 0
	s_cmp_gt_u32 s62, 13
	s_mov_b64 s[70:71], s[68:69]
	s_cbranch_scc0 .LBB0_125
	s_and_b64 vcc, exec, s[14:15]
	s_cbranch_vccz .LBB0_128
	s_barrier

.LBB0_237:
	ds_read_b128 v[2:5], v110
	ds_read_b128 v[6:9], v110 offset:1024
	ds_read_b128 v[10:13], v110 offset:2048
	ds_read_b128 v[14:17], v110 offset:3072
	ds_read_b128 v[18:21], v111
	ds_read_b128 v[22:25], v111 offset:1024
	ds_read_b128 v[26:29], v111 offset:2048
	ds_read_b128 v[30:33], v111 offset:3072
	s_add_u32 s66, s18, 0x100
	s_addc_u32 s67, s19, 0
	s_add_u32 s8, s14, 0x100
	s_addc_u32 s9, s15, 0
	s_add_u32 s30, s18, 0x180
	s_addc_u32 s31, s19, 0
	s_add_u32 s12, s18, 0xb0080
	s_addc_u32 s13, s19, 0
	s_add_i32 s94, s82, 0xc000
	v_mov_b32_e32 v186, v106
	s_mov_b32 m0, s94
	s_add_i32 s95, s82, 0xe000
	ds_read_b128 v[34:37], v112
	ds_read_b128 v[38:41], v112 offset:1024
	ds_read_b128 v[42:45], v112 offset:2048
	ds_read_b128 v[46:49], v112 offset:3072
	ds_read_b128 v[50:53], v112 offset:4096
	ds_read_b128 v[54:57], v112 offset:5120
	ds_read_b128 v[58:61], v112 offset:6144
	ds_read_b128 v[62:65], v112 offset:7168
	v_mov_b32_e32 v187, v107
	global_load_lds_dwordx4 v186, s[12:13]
	s_mov_b32 m0, s95
	s_add_u32 s64, s14, 0x180
	global_load_lds_dwordx4 v187, s[12:13]
	s_waitcnt vmcnt(8)
	s_waitcnt lgkmcnt(0)
	s_addc_u32 s65, s15, 0
	s_barrier
	s_waitcnt lgkmcnt(0)
	v_mfma_f32_16x16x32_bf16 v[66:69], v[2:5], v[34:37], 0
	v_mfma_f32_16x16x32_bf16 v[70:73], v[10:13], v[34:37], 0
	v_mfma_f32_16x16x32_bf16 v[74:77], v[2:5], v[42:45], 0
	v_mfma_f32_16x16x32_bf16 v[78:81], v[10:13], v[42:45], 0
	v_mfma_f32_16x16x32_bf16 v[82:85], v[2:5], v[50:53], 0
	v_mfma_f32_16x16x32_bf16 v[86:89], v[10:13], v[50:53], 0
	v_mfma_f32_16x16x32_bf16 v[90:93], v[2:5], v[58:61], 0
	v_mfma_f32_16x16x32_bf16 v[98:101], v[10:13], v[58:61], 0
	v_mfma_f32_16x16x32_bf16 v[66:69], v[6:9], v[38:41], v[66:69]
	v_mfma_f32_16x16x32_bf16 v[70:73], v[14:17], v[38:41], v[70:73]
	v_mfma_f32_16x16x32_bf16 v[74:77], v[6:9], v[46:49], v[74:77]
	v_mfma_f32_16x16x32_bf16 v[78:81], v[14:17], v[46:49], v[78:81]
	v_mfma_f32_16x16x32_bf16 v[82:85], v[6:9], v[54:57], v[82:85]
	v_mfma_f32_16x16x32_bf16 v[86:89], v[14:17], v[54:57], v[86:89]
	v_mfma_f32_16x16x32_bf16 v[90:93], v[6:9], v[62:65], v[90:93]
	v_mfma_f32_16x16x32_bf16 v[98:101], v[14:17], v[62:65], v[98:101]
	v_mfma_f32_16x16x32_bf16 v[102:105], v[18:21], v[34:37], 0
	v_mfma_f32_16x16x32_bf16 v[34:37], v[26:29], v[34:37], 0
	v_mfma_f32_16x16x32_bf16 v[114:117], v[18:21], v[42:45], 0
	v_mfma_f32_16x16x32_bf16 v[42:45], v[26:29], v[42:45], 0
	v_mfma_f32_16x16x32_bf16 v[118:121], v[18:21], v[50:53], 0
	v_mfma_f32_16x16x32_bf16 v[50:53], v[26:29], v[50:53], 0
	v_mfma_f32_16x16x32_bf16 v[122:125], v[18:21], v[58:61], 0
	v_mfma_f32_16x16x32_bf16 v[58:61], v[26:29], v[58:61], 0
	v_mfma_f32_16x16x32_bf16 v[102:105], v[22:25], v[38:41], v[102:105]
	v_mfma_f32_16x16x32_bf16 v[126:129], v[30:33], v[38:41], v[34:37]
	v_mfma_f32_16x16x32_bf16 v[114:117], v[22:25], v[46:49], v[114:117]
	v_mfma_f32_16x16x32_bf16 v[42:45], v[30:33], v[46:49], v[42:45]
	v_mfma_f32_16x16x32_bf16 v[118:121], v[22:25], v[54:57], v[118:121]
	v_mfma_f32_16x16x32_bf16 v[50:53], v[30:33], v[54:57], v[50:53]
	v_mfma_f32_16x16x32_bf16 v[54:57], v[22:25], v[62:65], v[122:125]
	v_mfma_f32_16x16x32_bf16 v[58:61], v[30:33], v[62:65], v[58:61]
	s_barrier
	s_add_i32 s96, s89, s81
	s_mov_b32 m0, s96
	s_add_i32 s97, s96, 0x2000
	ds_read_b128 v[34:37], v112 offset:16384
	ds_read_b128 v[38:41], v112 offset:17408
	ds_read_b128 v[46:49], v112 offset:18432
	ds_read_b128 v[62:65], v112 offset:19456
	ds_read_b128 v[122:125], v112 offset:20480
	ds_read_b128 v[130:133], v112 offset:21504
	ds_read_b128 v[134:137], v112 offset:22528
	ds_read_b128 v[138:141], v112 offset:23552
	s_nop 0
	global_load_lds_dwordx4 v186, s[8:9]
	s_mov_b32 m0, s97
	s_nop 0
	global_load_lds_dwordx4 v187, s[8:9]
	s_add_u32 s8, s14, 0xb0100
	s_addc_u32 s9, s15, 0
	s_add_i32 s34, s90, s81
	s_mov_b32 m0, s34
	s_add_i32 s35, s34, 0x2000
	s_nop 0
	global_load_lds_dwordx4 v186, s[8:9]
	s_mov_b32 m0, s35
	s_nop 0
	global_load_lds_dwordx4 v187, s[8:9]
	s_mov_b32 m0, s82
	s_nop 0
	global_load_lds_dwordx4 v186, s[66:67]
	s_mov_b32 m0, s83
	s_nop 0
	global_load_lds_dwordx4 v187, s[66:67]
	s_waitcnt vmcnt(8)
	s_waitcnt lgkmcnt(0)
	s_barrier
	s_waitcnt lgkmcnt(0)
	v_mfma_f32_16x16x32_bf16 v[142:145], v[2:5], v[34:37], 0
	v_mfma_f32_16x16x32_bf16 v[146:149], v[10:13], v[34:37], 0
	v_mfma_f32_16x16x32_bf16 v[150:153], v[2:5], v[46:49], 0
	v_mfma_f32_16x16x32_bf16 v[154:157], v[10:13], v[46:49], 0
	v_mfma_f32_16x16x32_bf16 v[158:161], v[2:5], v[122:125], 0
	v_mfma_f32_16x16x32_bf16 v[162:165], v[10:13], v[122:125], 0
	v_mfma_f32_16x16x32_bf16 v[2:5], v[2:5], v[134:137], 0
	v_mfma_f32_16x16x32_bf16 v[10:13], v[10:13], v[134:137], 0
	v_mfma_f32_16x16x32_bf16 v[166:169], v[6:9], v[38:41], v[142:145]
	v_mfma_f32_16x16x32_bf16 v[144:147], v[14:17], v[38:41], v[146:149]
	v_mfma_f32_16x16x32_bf16 v[148:151], v[6:9], v[62:65], v[150:153]
	v_mfma_f32_16x16x32_bf16 v[152:155], v[14:17], v[62:65], v[154:157]
	v_mfma_f32_16x16x32_bf16 v[156:159], v[6:9], v[130:133], v[158:161]
	v_mfma_f32_16x16x32_bf16 v[6:9], v[6:9], v[138:141], v[2:5]
	v_mfma_f32_16x16x32_bf16 v[10:13], v[14:17], v[138:141], v[10:13]
	v_mfma_f32_16x16x32_bf16 v[160:163], v[14:17], v[130:133], v[162:165]
	v_mfma_f32_16x16x32_bf16 v[2:5], v[18:21], v[34:37], 0
	v_mfma_f32_16x16x32_bf16 v[14:17], v[26:29], v[34:37], 0
	v_mfma_f32_16x16x32_bf16 v[34:37], v[18:21], v[46:49], 0
	v_mfma_f32_16x16x32_bf16 v[46:49], v[26:29], v[46:49], 0
	v_mfma_f32_16x16x32_bf16 v[170:173], v[18:21], v[122:125], 0
	v_mfma_f32_16x16x32_bf16 v[122:125], v[26:29], v[122:125], 0
	v_mfma_f32_16x16x32_bf16 v[18:21], v[18:21], v[134:137], 0
	v_mfma_f32_16x16x32_bf16 v[26:29], v[26:29], v[134:137], 0
	v_mfma_f32_16x16x32_bf16 v[134:137], v[22:25], v[38:41], v[2:5]
	v_mfma_f32_16x16x32_bf16 v[170:173], v[22:25], v[130:133], v[170:173]
	v_mfma_f32_16x16x32_bf16 v[122:125], v[30:33], v[130:133], v[122:125]
	v_mfma_f32_16x16x32_bf16 v[130:133], v[22:25], v[138:141], v[18:21]
	v_mfma_f32_16x16x32_bf16 v[138:141], v[30:33], v[138:141], v[26:29]
	v_mfma_f32_16x16x32_bf16 v[174:177], v[30:33], v[38:41], v[14:17]
	v_mfma_f32_16x16x32_bf16 v[178:181], v[22:25], v[62:65], v[34:37]
	v_mfma_f32_16x16x32_bf16 v[182:185], v[30:33], v[62:65], v[46:49]
	s_barrier
	s_add_i32 s11, 0, 0x18000
	s_add_i32 s22, 0, 0x1c000
	v_add_u32_e32 v113, s11, v109
	v_add_u32_e32 v142, s22, v109
	ds_read_b128 v[18:21], v113
	ds_read_b128 v[192:195], v113 offset:1024
	ds_read_b128 v[22:25], v113 offset:2048
	ds_read_b128 v[196:199], v113 offset:3072
	ds_read_b128 v[200:203], v142
	ds_read_b128 v[204:207], v142 offset:1024
	ds_read_b128 v[208:211], v142 offset:2048
	ds_read_b128 v[212:215], v142 offset:3072
	s_add_u32 s8, s18, 0xb0100
	s_addc_u32 s9, s19, 0
	s_mov_b32 m0, s84
	ds_read_b128 v[26:29], v112 offset:32768
	ds_read_b128 v[30:33], v112 offset:33792
	ds_read_b128 v[216:219], v112 offset:34816
	ds_read_b128 v[220:223], v112 offset:35840
	ds_read_b128 v[224:227], v112 offset:36864
	ds_read_b128 v[228:231], v112 offset:37888
	ds_read_b128 v[232:235], v112 offset:38912
	ds_read_b128 v[236:239], v112 offset:39936
	s_nop 0
	global_load_lds_dwordx4 v186, s[8:9]
	s_mov_b32 m0, s85
	s_nop 0
	global_load_lds_dwordx4 v187, s[8:9]
	s_waitcnt vmcnt(8)
	s_waitcnt lgkmcnt(0)
	s_barrier
	s_waitcnt lgkmcnt(0)
	v_mfma_f32_16x16x32_bf16 v[2:5], v[18:21], v[26:29], v[66:69]
	v_mfma_f32_16x16x32_bf16 v[14:17], v[22:25], v[26:29], v[70:73]
	v_mfma_f32_16x16x32_bf16 v[34:37], v[18:21], v[216:219], v[74:77]
	v_mfma_f32_16x16x32_bf16 v[46:49], v[22:25], v[216:219], v[78:81]
	v_mfma_f32_16x16x32_bf16 v[66:69], v[18:21], v[224:227], v[82:85]
	v_mfma_f32_16x16x32_bf16 v[74:77], v[22:25], v[224:227], v[86:89]
	v_mfma_f32_16x16x32_bf16 v[82:85], v[18:21], v[232:235], v[90:93]
	v_mfma_f32_16x16x32_bf16 v[86:89], v[22:25], v[232:235], v[98:101]
	v_mfma_f32_16x16x32_bf16 v[78:81], v[192:195], v[30:33], v[2:5]
	v_mfma_f32_16x16x32_bf16 v[38:41], v[196:199], v[30:33], v[14:17]
	v_mfma_f32_16x16x32_bf16 v[62:65], v[192:195], v[220:223], v[34:37]
	v_mfma_f32_16x16x32_bf16 v[34:37], v[196:199], v[220:223], v[46:49]
	v_mfma_f32_16x16x32_bf16 v[70:73], v[192:195], v[228:231], v[66:69]
	v_mfma_f32_16x16x32_bf16 v[46:49], v[196:199], v[228:231], v[74:77]
	v_mfma_f32_16x16x32_bf16 v[14:17], v[192:195], v[236:239], v[82:85]
	v_mfma_f32_16x16x32_bf16 v[2:5], v[196:199], v[236:239], v[86:89]
	v_mfma_f32_16x16x32_bf16 v[66:69], v[200:203], v[26:29], v[102:105]
	v_mfma_f32_16x16x32_bf16 v[26:29], v[208:211], v[26:29], v[126:129]
	v_mfma_f32_16x16x32_bf16 v[74:77], v[200:203], v[216:219], v[114:117]
	v_mfma_f32_16x16x32_bf16 v[42:45], v[208:211], v[216:219], v[42:45]
	v_mfma_f32_16x16x32_bf16 v[90:93], v[200:203], v[224:227], v[118:121]
	v_mfma_f32_16x16x32_bf16 v[50:53], v[208:211], v[224:227], v[50:53]
	v_mfma_f32_16x16x32_bf16 v[54:57], v[200:203], v[232:235], v[54:57]
	v_mfma_f32_16x16x32_bf16 v[58:61], v[208:211], v[232:235], v[58:61]
	v_mfma_f32_16x16x32_bf16 v[98:101], v[204:207], v[30:33], v[66:69]
	v_mfma_f32_16x16x32_bf16 v[82:85], v[212:215], v[30:33], v[26:29]
	v_mfma_f32_16x16x32_bf16 v[102:105], v[204:207], v[220:223], v[74:77]
	v_mfma_f32_16x16x32_bf16 v[86:89], v[212:215], v[220:223], v[42:45]
	v_mfma_f32_16x16x32_bf16 v[90:93], v[204:207], v[228:231], v[90:93]
	v_mfma_f32_16x16x32_bf16 v[74:77], v[212:215], v[228:231], v[50:53]
	v_mfma_f32_16x16x32_bf16 v[54:57], v[204:207], v[236:239], v[54:57]
	v_mfma_f32_16x16x32_bf16 v[50:53], v[212:215], v[236:239], v[58:61]
	s_barrier
	s_add_i32 s11, s11, s81
	s_add_i32 s80, s11, 0x2000
	s_mov_b32 m0, s11
	s_add_u32 s12, s14, 0xb0180
	ds_read_b128 v[42:45], v112 offset:49152
	ds_read_b128 v[58:61], v112 offset:50176
	ds_read_b128 v[66:69], v112 offset:51200
	ds_read_b128 v[126:129], v112 offset:52224
	ds_read_b128 v[216:219], v112 offset:53248
	ds_read_b128 v[220:223], v112 offset:54272
	ds_read_b128 v[224:227], v112 offset:55296
	ds_read_b128 v[228:231], v112 offset:56320
	s_addc_u32 s13, s15, 0
	global_load_lds_dwordx4 v186, s[64:65]
	s_mov_b32 m0, s80
	s_add_i32 s8, s22, s81
	global_load_lds_dwordx4 v187, s[64:65]
	s_mov_b32 m0, s8
	s_add_i32 s9, s8, 0x2000
	s_nop 0
	global_load_lds_dwordx4 v186, s[12:13]
	s_mov_b32 m0, s9
	s_nop 0
	global_load_lds_dwordx4 v187, s[12:13]
	s_mov_b32 m0, s87
	s_nop 0
	global_load_lds_dwordx4 v186, s[30:31]
	s_mov_b32 m0, s88
	s_nop 0
	global_load_lds_dwordx4 v187, s[30:31]
	s_waitcnt vmcnt(8)
	s_waitcnt lgkmcnt(0)
	s_barrier
	s_waitcnt lgkmcnt(0)
	v_mfma_f32_16x16x32_bf16 v[26:29], v[18:21], v[42:45], v[166:169]
	v_mfma_f32_16x16x32_bf16 v[114:117], v[22:25], v[42:45], v[144:147]
	v_mfma_f32_16x16x32_bf16 v[118:121], v[18:21], v[66:69], v[148:151]
	v_mfma_f32_16x16x32_bf16 v[144:147], v[22:25], v[66:69], v[152:155]
	v_mfma_f32_16x16x32_bf16 v[148:151], v[18:21], v[216:219], v[156:159]
	v_mfma_f32_16x16x32_bf16 v[152:155], v[22:25], v[216:219], v[160:163]
	v_mfma_f32_16x16x32_bf16 v[156:159], v[18:21], v[224:227], v[6:9]
	v_mfma_f32_16x16x32_bf16 v[160:163], v[22:25], v[224:227], v[10:13]
	v_mfma_f32_16x16x32_bf16 v[30:33], v[192:195], v[58:61], v[26:29]
	v_mfma_f32_16x16x32_bf16 v[26:29], v[196:199], v[58:61], v[114:117]
	v_mfma_f32_16x16x32_bf16 v[18:21], v[192:195], v[126:129], v[118:121]
	v_mfma_f32_16x16x32_bf16 v[6:9], v[196:199], v[126:129], v[144:147]
	v_mfma_f32_16x16x32_bf16 v[22:25], v[192:195], v[220:223], v[148:151]
	v_mfma_f32_16x16x32_bf16 v[10:13], v[196:199], v[220:223], v[152:155]
	v_mfma_f32_16x16x32_bf16 v[118:121], v[192:195], v[228:231], v[156:159]
	v_mfma_f32_16x16x32_bf16 v[114:117], v[196:199], v[228:231], v[160:163]
	v_mfma_f32_16x16x32_bf16 v[134:137], v[200:203], v[42:45], v[134:137]
	v_mfma_f32_16x16x32_bf16 v[42:45], v[208:211], v[42:45], v[174:177]
	v_mfma_f32_16x16x32_bf16 v[144:147], v[200:203], v[66:69], v[178:181]
	v_mfma_f32_16x16x32_bf16 v[148:151], v[208:211], v[66:69], v[182:185]
	v_mfma_f32_16x16x32_bf16 v[152:155], v[200:203], v[216:219], v[170:173]
	v_mfma_f32_16x16x32_bf16 v[122:125], v[208:211], v[216:219], v[122:125]
	v_mfma_f32_16x16x32_bf16 v[130:133], v[200:203], v[224:227], v[130:133]
	v_mfma_f32_16x16x32_bf16 v[156:159], v[208:211], v[224:227], v[138:141]
	v_mfma_f32_16x16x32_bf16 v[138:141], v[204:207], v[58:61], v[134:137]
	v_mfma_f32_16x16x32_bf16 v[58:61], v[212:215], v[58:61], v[42:45]
	v_mfma_f32_16x16x32_bf16 v[66:69], v[204:207], v[126:129], v[144:147]
	v_mfma_f32_16x16x32_bf16 v[42:45], v[212:215], v[126:129], v[148:151]
	v_mfma_f32_16x16x32_bf16 v[126:129], v[204:207], v[220:223], v[152:155]
	v_mfma_f32_16x16x32_bf16 v[122:125], v[212:215], v[220:223], v[122:125]
	v_mfma_f32_16x16x32_bf16 v[134:137], v[204:207], v[228:231], v[130:133]
	v_mfma_f32_16x16x32_bf16 v[130:133], v[212:215], v[228:231], v[156:159]
	s_barrier
	s_mov_b32 s12, 0
	s_mov_b64 s[30:31], 0
.LBB0_238:
	s_add_u32 s13, s18, s30
	ds_read_b128 v[144:147], v110
	ds_read_b128 v[148:151], v110 offset:1024
	ds_read_b128 v[152:155], v110 offset:2048
	ds_read_b128 v[156:159], v110 offset:3072
	ds_read_b128 v[160:163], v111
	ds_read_b128 v[164:167], v111 offset:1024
	ds_read_b128 v[168:171], v111 offset:2048
	ds_read_b128 v[172:175], v111 offset:3072
	s_addc_u32 s23, s19, s31
	s_add_u32 s22, s13, 0x200
	s_addc_u32 s24, s23, 0
	s_add_u32 s25, s14, s30
	s_addc_u32 s26, s15, s31
	s_add_u32 s25, s25, 0x200
	s_addc_u32 s26, s26, 0
	s_cmp_eq_u32 s12, 40
	s_cselect_b32 s70, s28, s22
	s_cselect_b32 s71, s29, s24
	s_cselect_b32 s66, s0, s25
	s_cselect_b32 s67, s1, s26
	s_add_u32 s64, s70, 0x80
	s_addc_u32 s65, s71, 0
	s_add_u32 s22, s13, 0xb0180
	s_mov_b32 m0, s94
	s_addc_u32 s23, s23, 0
	v_mov_b32_e32 v143, v106
	ds_read_b128 v[176:179], v112
	ds_read_b128 v[180:183], v112 offset:1024
	ds_read_b128 v[184:187], v112 offset:2048
	ds_read_b128 v[192:195], v112 offset:3072
	ds_read_b128 v[196:199], v112 offset:4096
	ds_read_b128 v[200:203], v112 offset:5120
	ds_read_b128 v[204:207], v112 offset:6144
	ds_read_b128 v[208:211], v112 offset:7168
	v_mov_b32_e32 v191, v107
	global_load_lds_dwordx4 v143, s[22:23]
	s_mov_b32 m0, s95
	s_add_u32 s68, s66, 0x80
	global_load_lds_dwordx4 v191, s[22:23]
	s_waitcnt vmcnt(8)
	s_waitcnt lgkmcnt(0)
	s_addc_u32 s69, s67, 0
	s_barrier
	s_waitcnt lgkmcnt(0)
	v_mfma_f32_16x16x32_bf16 v[78:81], v[144:147], v[176:179], v[78:81]
	v_mfma_f32_16x16x32_bf16 v[38:41], v[152:155], v[176:179], v[38:41]
	v_mfma_f32_16x16x32_bf16 v[62:65], v[144:147], v[184:187], v[62:65]
	v_mfma_f32_16x16x32_bf16 v[34:37], v[152:155], v[184:187], v[34:37]
	v_mfma_f32_16x16x32_bf16 v[70:73], v[144:147], v[196:199], v[70:73]
	v_mfma_f32_16x16x32_bf16 v[46:49], v[152:155], v[196:199], v[46:49]
	v_mfma_f32_16x16x32_bf16 v[14:17], v[144:147], v[204:207], v[14:17]
	v_mfma_f32_16x16x32_bf16 v[2:5], v[152:155], v[204:207], v[2:5]
	v_mfma_f32_16x16x32_bf16 v[78:81], v[148:151], v[180:183], v[78:81]
	v_mfma_f32_16x16x32_bf16 v[38:41], v[156:159], v[180:183], v[38:41]
	v_mfma_f32_16x16x32_bf16 v[62:65], v[148:151], v[192:195], v[62:65]
	v_mfma_f32_16x16x32_bf16 v[34:37], v[156:159], v[192:195], v[34:37]
	v_mfma_f32_16x16x32_bf16 v[70:73], v[148:151], v[200:203], v[70:73]
	v_mfma_f32_16x16x32_bf16 v[46:49], v[156:159], v[200:203], v[46:49]
	v_mfma_f32_16x16x32_bf16 v[14:17], v[148:151], v[208:211], v[14:17]
	v_mfma_f32_16x16x32_bf16 v[2:5], v[156:159], v[208:211], v[2:5]
	v_mfma_f32_16x16x32_bf16 v[98:101], v[160:163], v[176:179], v[98:101]
	v_mfma_f32_16x16x32_bf16 v[82:85], v[168:171], v[176:179], v[82:85]
	v_mfma_f32_16x16x32_bf16 v[102:105], v[160:163], v[184:187], v[102:105]
	v_mfma_f32_16x16x32_bf16 v[86:89], v[168:171], v[184:187], v[86:89]
	v_mfma_f32_16x16x32_bf16 v[90:93], v[160:163], v[196:199], v[90:93]
	v_mfma_f32_16x16x32_bf16 v[74:77], v[168:171], v[196:199], v[74:77]
	v_mfma_f32_16x16x32_bf16 v[54:57], v[160:163], v[204:207], v[54:57]
	v_mfma_f32_16x16x32_bf16 v[50:53], v[168:171], v[204:207], v[50:53]
	v_mfma_f32_16x16x32_bf16 v[98:101], v[164:167], v[180:183], v[98:101]
	v_mfma_f32_16x16x32_bf16 v[82:85], v[172:175], v[180:183], v[82:85]
	v_mfma_f32_16x16x32_bf16 v[102:105], v[164:167], v[192:195], v[102:105]
	v_mfma_f32_16x16x32_bf16 v[86:89], v[172:175], v[192:195], v[86:89]
	v_mfma_f32_16x16x32_bf16 v[90:93], v[164:167], v[200:203], v[90:93]
	v_mfma_f32_16x16x32_bf16 v[74:77], v[172:175], v[200:203], v[74:77]
	v_mfma_f32_16x16x32_bf16 v[54:57], v[164:167], v[208:211], v[54:57]
	v_mfma_f32_16x16x32_bf16 v[50:53], v[172:175], v[208:211], v[50:53]
	s_barrier
	s_mov_b32 m0, s96
	s_mov_b64 s[22:23], s[66:67]
	ds_read_b128 v[176:179], v112 offset:16384
	ds_read_b128 v[180:183], v112 offset:17408
	ds_read_b128 v[184:187], v112 offset:18432
	ds_read_b128 v[192:195], v112 offset:19456
	ds_read_b128 v[196:199], v112 offset:20480
	ds_read_b128 v[200:203], v112 offset:21504
	ds_read_b128 v[204:207], v112 offset:22528
	ds_read_b128 v[208:211], v112 offset:23552
	s_nop 0
	global_load_lds_dwordx4 v143, s[22:23]
	s_mov_b32 m0, s97
	s_nop 0
	global_load_lds_dwordx4 v191, s[22:23]
	s_add_u32 s22, s66, 0xb0000
	s_addc_u32 s23, s67, 0
	s_mov_b32 m0, s34
	s_nop 0
	global_load_lds_dwordx4 v143, s[22:23]
	s_mov_b32 m0, s35
	s_nop 0
	global_load_lds_dwordx4 v191, s[22:23]
	s_mov_b64 s[22:23], s[70:71]
	s_mov_b32 m0, s82
	s_nop 0
	global_load_lds_dwordx4 v143, s[22:23]
	s_mov_b32 m0, s83
	s_nop 0
	global_load_lds_dwordx4 v191, s[22:23]
	s_waitcnt vmcnt(8)
	s_waitcnt lgkmcnt(0)
	s_barrier
	s_waitcnt lgkmcnt(0)
	v_mfma_f32_16x16x32_bf16 v[30:33], v[144:147], v[176:179], v[30:33]
	v_mfma_f32_16x16x32_bf16 v[26:29], v[152:155], v[176:179], v[26:29]
	v_mfma_f32_16x16x32_bf16 v[18:21], v[144:147], v[184:187], v[18:21]
	v_mfma_f32_16x16x32_bf16 v[6:9], v[152:155], v[184:187], v[6:9]
	v_mfma_f32_16x16x32_bf16 v[22:25], v[144:147], v[196:199], v[22:25]
	v_mfma_f32_16x16x32_bf16 v[10:13], v[152:155], v[196:199], v[10:13]
	v_mfma_f32_16x16x32_bf16 v[118:121], v[144:147], v[204:207], v[118:121]
	v_mfma_f32_16x16x32_bf16 v[114:117], v[152:155], v[204:207], v[114:117]
	v_mfma_f32_16x16x32_bf16 v[30:33], v[148:151], v[180:183], v[30:33]
	v_mfma_f32_16x16x32_bf16 v[26:29], v[156:159], v[180:183], v[26:29]
	v_mfma_f32_16x16x32_bf16 v[18:21], v[148:151], v[192:195], v[18:21]
	v_mfma_f32_16x16x32_bf16 v[6:9], v[156:159], v[192:195], v[6:9]
	v_mfma_f32_16x16x32_bf16 v[22:25], v[148:151], v[200:203], v[22:25]
	v_mfma_f32_16x16x32_bf16 v[10:13], v[156:159], v[200:203], v[10:13]
	v_mfma_f32_16x16x32_bf16 v[118:121], v[148:151], v[208:211], v[118:121]
	v_mfma_f32_16x16x32_bf16 v[114:117], v[156:159], v[208:211], v[114:117]
	v_mfma_f32_16x16x32_bf16 v[138:141], v[160:163], v[176:179], v[138:141]
	v_mfma_f32_16x16x32_bf16 v[58:61], v[168:171], v[176:179], v[58:61]
	v_mfma_f32_16x16x32_bf16 v[66:69], v[160:163], v[184:187], v[66:69]
	v_mfma_f32_16x16x32_bf16 v[42:45], v[168:171], v[184:187], v[42:45]
	v_mfma_f32_16x16x32_bf16 v[126:129], v[160:163], v[196:199], v[126:129]
	v_mfma_f32_16x16x32_bf16 v[122:125], v[168:171], v[196:199], v[122:125]
	v_mfma_f32_16x16x32_bf16 v[134:137], v[160:163], v[204:207], v[134:137]
	v_mfma_f32_16x16x32_bf16 v[130:133], v[168:171], v[204:207], v[130:133]
	v_mfma_f32_16x16x32_bf16 v[138:141], v[164:167], v[180:183], v[138:141]
	v_mfma_f32_16x16x32_bf16 v[58:61], v[172:175], v[180:183], v[58:61]
	v_mfma_f32_16x16x32_bf16 v[66:69], v[164:167], v[192:195], v[66:69]
	v_mfma_f32_16x16x32_bf16 v[42:45], v[172:175], v[192:195], v[42:45]
	v_mfma_f32_16x16x32_bf16 v[126:129], v[164:167], v[200:203], v[126:129]
	v_mfma_f32_16x16x32_bf16 v[122:125], v[172:175], v[200:203], v[122:125]
	v_mfma_f32_16x16x32_bf16 v[134:137], v[164:167], v[208:211], v[134:137]
	v_mfma_f32_16x16x32_bf16 v[130:133], v[172:175], v[208:211], v[130:133]
	s_barrier
	ds_read_b128 v[144:147], v113
	ds_read_b128 v[148:151], v113 offset:1024
	ds_read_b128 v[152:155], v113 offset:2048
	ds_read_b128 v[156:159], v113 offset:3072
	ds_read_b128 v[160:163], v142
	ds_read_b128 v[164:167], v142 offset:1024
	ds_read_b128 v[168:171], v142 offset:2048
	ds_read_b128 v[172:175], v142 offset:3072
	s_add_u32 s22, s70, 0xb0000
	s_addc_u32 s23, s71, 0
	s_mov_b32 m0, s84
	ds_read_b128 v[176:179], v112 offset:32768
	ds_read_b128 v[180:183], v112 offset:33792
	ds_read_b128 v[184:187], v112 offset:34816
	ds_read_b128 v[192:195], v112 offset:35840
	ds_read_b128 v[196:199], v112 offset:36864
	ds_read_b128 v[200:203], v112 offset:37888
	ds_read_b128 v[204:207], v112 offset:38912
	ds_read_b128 v[208:211], v112 offset:39936
	s_nop 0
	global_load_lds_dwordx4 v143, s[22:23]
	s_mov_b32 m0, s85
	s_nop 0
	global_load_lds_dwordx4 v191, s[22:23]
	s_waitcnt vmcnt(8)
	s_waitcnt lgkmcnt(0)
	s_barrier
	s_waitcnt lgkmcnt(0)
	v_mfma_f32_16x16x32_bf16 v[78:81], v[144:147], v[176:179], v[78:81]
	v_mfma_f32_16x16x32_bf16 v[38:41], v[152:155], v[176:179], v[38:41]
	v_mfma_f32_16x16x32_bf16 v[62:65], v[144:147], v[184:187], v[62:65]
	v_mfma_f32_16x16x32_bf16 v[34:37], v[152:155], v[184:187], v[34:37]
	v_mfma_f32_16x16x32_bf16 v[70:73], v[144:147], v[196:199], v[70:73]
	v_mfma_f32_16x16x32_bf16 v[46:49], v[152:155], v[196:199], v[46:49]
	v_mfma_f32_16x16x32_bf16 v[14:17], v[144:147], v[204:207], v[14:17]
	v_mfma_f32_16x16x32_bf16 v[2:5], v[152:155], v[204:207], v[2:5]
	v_mfma_f32_16x16x32_bf16 v[78:81], v[148:151], v[180:183], v[78:81]
	v_mfma_f32_16x16x32_bf16 v[38:41], v[156:159], v[180:183], v[38:41]
	v_mfma_f32_16x16x32_bf16 v[62:65], v[148:151], v[192:195], v[62:65]
	v_mfma_f32_16x16x32_bf16 v[34:37], v[156:159], v[192:195], v[34:37]
	v_mfma_f32_16x16x32_bf16 v[70:73], v[148:151], v[200:203], v[70:73]
	v_mfma_f32_16x16x32_bf16 v[46:49], v[156:159], v[200:203], v[46:49]
	v_mfma_f32_16x16x32_bf16 v[14:17], v[148:151], v[208:211], v[14:17]
	v_mfma_f32_16x16x32_bf16 v[2:5], v[156:159], v[208:211], v[2:5]
	v_mfma_f32_16x16x32_bf16 v[98:101], v[160:163], v[176:179], v[98:101]
	v_mfma_f32_16x16x32_bf16 v[82:85], v[168:171], v[176:179], v[82:85]
	v_mfma_f32_16x16x32_bf16 v[102:105], v[160:163], v[184:187], v[102:105]
	v_mfma_f32_16x16x32_bf16 v[86:89], v[168:171], v[184:187], v[86:89]
	v_mfma_f32_16x16x32_bf16 v[90:93], v[160:163], v[196:199], v[90:93]
	v_mfma_f32_16x16x32_bf16 v[74:77], v[168:171], v[196:199], v[74:77]
	v_mfma_f32_16x16x32_bf16 v[54:57], v[160:163], v[204:207], v[54:57]
	v_mfma_f32_16x16x32_bf16 v[50:53], v[168:171], v[204:207], v[50:53]
	v_mfma_f32_16x16x32_bf16 v[98:101], v[164:167], v[180:183], v[98:101]
	v_mfma_f32_16x16x32_bf16 v[82:85], v[172:175], v[180:183], v[82:85]
	v_mfma_f32_16x16x32_bf16 v[102:105], v[164:167], v[192:195], v[102:105]
	v_mfma_f32_16x16x32_bf16 v[86:89], v[172:175], v[192:195], v[86:89]
	v_mfma_f32_16x16x32_bf16 v[90:93], v[164:167], v[200:203], v[90:93]
	v_mfma_f32_16x16x32_bf16 v[74:77], v[172:175], v[200:203], v[74:77]
	v_mfma_f32_16x16x32_bf16 v[54:57], v[164:167], v[208:211], v[54:57]
	v_mfma_f32_16x16x32_bf16 v[50:53], v[172:175], v[208:211], v[50:53]
	s_barrier
	s_mov_b32 m0, s11
	ds_read_b128 v[176:179], v112 offset:49152
	ds_read_b128 v[180:183], v112 offset:50176
	ds_read_b128 v[184:187], v112 offset:51200
	ds_read_b128 v[192:195], v112 offset:52224
	ds_read_b128 v[196:199], v112 offset:53248
	ds_read_b128 v[200:203], v112 offset:54272
	ds_read_b128 v[204:207], v112 offset:55296
	ds_read_b128 v[208:211], v112 offset:56320
	s_add_u32 s22, s66, 0xb0080
	global_load_lds_dwordx4 v143, s[68:69]
	s_mov_b32 m0, s80
	s_addc_u32 s23, s67, 0
	global_load_lds_dwordx4 v191, s[68:69]
	s_mov_b32 m0, s8
	s_nop 0
	global_load_lds_dwordx4 v143, s[22:23]
	s_mov_b32 m0, s9
	s_nop 0
	global_load_lds_dwordx4 v191, s[22:23]
	s_mov_b32 m0, s87
	s_nop 0
	global_load_lds_dwordx4 v143, s[64:65]
	s_mov_b32 m0, s88
	s_nop 0
	global_load_lds_dwordx4 v191, s[64:65]
	s_waitcnt vmcnt(8)
	s_waitcnt lgkmcnt(0)
	s_barrier
	s_waitcnt lgkmcnt(0)
	v_mfma_f32_16x16x32_bf16 v[30:33], v[144:147], v[176:179], v[30:33]
	v_mfma_f32_16x16x32_bf16 v[26:29], v[152:155], v[176:179], v[26:29]
	v_mfma_f32_16x16x32_bf16 v[18:21], v[144:147], v[184:187], v[18:21]
	v_mfma_f32_16x16x32_bf16 v[6:9], v[152:155], v[184:187], v[6:9]
	v_mfma_f32_16x16x32_bf16 v[22:25], v[144:147], v[196:199], v[22:25]
	v_mfma_f32_16x16x32_bf16 v[10:13], v[152:155], v[196:199], v[10:13]
	v_mfma_f32_16x16x32_bf16 v[118:121], v[144:147], v[204:207], v[118:121]
	v_mfma_f32_16x16x32_bf16 v[114:117], v[152:155], v[204:207], v[114:117]
	v_mfma_f32_16x16x32_bf16 v[30:33], v[148:151], v[180:183], v[30:33]
	v_mfma_f32_16x16x32_bf16 v[26:29], v[156:159], v[180:183], v[26:29]
	v_mfma_f32_16x16x32_bf16 v[18:21], v[148:151], v[192:195], v[18:21]
	v_mfma_f32_16x16x32_bf16 v[6:9], v[156:159], v[192:195], v[6:9]
	v_mfma_f32_16x16x32_bf16 v[22:25], v[148:151], v[200:203], v[22:25]
	v_mfma_f32_16x16x32_bf16 v[10:13], v[156:159], v[200:203], v[10:13]
	v_mfma_f32_16x16x32_bf16 v[118:121], v[148:151], v[208:211], v[118:121]
	v_mfma_f32_16x16x32_bf16 v[114:117], v[156:159], v[208:211], v[114:117]
	v_mfma_f32_16x16x32_bf16 v[138:141], v[160:163], v[176:179], v[138:141]
	v_mfma_f32_16x16x32_bf16 v[58:61], v[168:171], v[176:179], v[58:61]
	v_mfma_f32_16x16x32_bf16 v[66:69], v[160:163], v[184:187], v[66:69]
	v_mfma_f32_16x16x32_bf16 v[42:45], v[168:171], v[184:187], v[42:45]
	v_mfma_f32_16x16x32_bf16 v[126:129], v[160:163], v[196:199], v[126:129]
	v_mfma_f32_16x16x32_bf16 v[122:125], v[168:171], v[196:199], v[122:125]
	v_mfma_f32_16x16x32_bf16 v[134:137], v[160:163], v[204:207], v[134:137]
	v_mfma_f32_16x16x32_bf16 v[130:133], v[168:171], v[204:207], v[130:133]
	v_mfma_f32_16x16x32_bf16 v[138:141], v[164:167], v[180:183], v[138:141]
	v_mfma_f32_16x16x32_bf16 v[58:61], v[172:175], v[180:183], v[58:61]
	v_mfma_f32_16x16x32_bf16 v[66:69], v[164:167], v[192:195], v[66:69]
	v_mfma_f32_16x16x32_bf16 v[42:45], v[172:175], v[192:195], v[42:45]
	v_mfma_f32_16x16x32_bf16 v[126:129], v[164:167], v[200:203], v[126:129]
	v_mfma_f32_16x16x32_bf16 v[122:125], v[172:175], v[200:203], v[122:125]
	v_mfma_f32_16x16x32_bf16 v[134:137], v[164:167], v[208:211], v[134:137]
	v_mfma_f32_16x16x32_bf16 v[130:133], v[172:175], v[208:211], v[130:133]
	s_barrier
	s_add_i32 s12, s12, 2
	s_add_u32 s30, s30, 0x100
	s_addc_u32 s31, s31, 0
	s_cmp_gt_u32 s12, 41
	s_cbranch_scc0 .LBB0_238
	s_and_b64 vcc, exec, s[4:5]
	s_cbranch_vccz .LBB0_226
	s_mov_b32 s20, s92
	s_mov_b32 s6, s93
	s_mov_b64 s[14:15], s[0:1]
	s_mov_b64 s[18:19], s[28:29]
	s_mov_b32 s86, s91
	s_branch .LBB0_226

.LBB0_327:
	s_ashr_i32 s27, s26, 31
	s_lshl_b64 s[8:9], s[26:27], 19
	s_add_u32 s64, s16, s8
	s_addc_u32 s65, s79, s9
	s_and_b64 s[8:9], s[2:3], exec
	ds_read_b128 v[2:5], v143
	ds_read_b128 v[6:9], v143 offset:1024
	ds_read_b128 v[10:13], v143 offset:2048
	ds_read_b128 v[14:17], v143 offset:3072
	ds_read_b128 v[18:21], v144
	ds_read_b128 v[22:25], v144 offset:1024
	ds_read_b128 v[26:29], v144 offset:2048
	ds_read_b128 v[30:33], v144 offset:3072
	s_cselect_b32 s15, s65, s71
	s_cselect_b32 s27, s64, s70
	s_ashr_i32 s21, s20, 31
	s_lshl_b64 s[8:9], s[20:21], 19
	s_add_u32 s66, s17, s8
	s_addc_u32 s67, s63, s9
	s_and_b64 s[8:9], s[2:3], exec
	s_cselect_b32 s21, s67, s69
	s_cselect_b32 s95, s66, s68
	s_add_u32 s72, s70, 0x100
	s_addc_u32 s73, s71, 0
	s_add_u32 s8, s68, 0x100
	s_addc_u32 s9, s69, 0
	s_add_u32 s74, s70, 0x180
	s_addc_u32 s75, s71, 0
	s_add_u32 s22, s70, 0x40080
	s_addc_u32 s23, s71, 0
	s_add_i32 s96, s84, 0xc000
	v_mov_b32_e32 v238, v134
	s_mov_b32 m0, s96
	s_add_i32 s97, s84, 0xe000
	ds_read_b128 v[34:37], v145
	ds_read_b128 v[38:41], v145 offset:1024
	ds_read_b128 v[42:45], v145 offset:2048
	ds_read_b128 v[46:49], v145 offset:3072
	ds_read_b128 v[50:53], v145 offset:4096
	ds_read_b128 v[54:57], v145 offset:5120
	ds_read_b128 v[58:61], v145 offset:6144
	ds_read_b128 v[62:65], v145 offset:7168
	v_mov_b32_e32 v239, v136
	global_load_lds_dwordx4 v238, s[22:23]
	s_mov_b32 m0, s97
	s_add_u32 s76, s68, 0x180
	global_load_lds_dwordx4 v239, s[22:23]
	s_waitcnt vmcnt(8)
	s_waitcnt lgkmcnt(0)
	s_addc_u32 s77, s69, 0
	s_barrier
	s_waitcnt lgkmcnt(0)
	v_mfma_f32_16x16x32_bf16 v[66:69], v[2:5], v[34:37], 0
	v_mfma_f32_16x16x32_bf16 v[70:73], v[10:13], v[34:37], 0
	v_mfma_f32_16x16x32_bf16 v[74:77], v[2:5], v[42:45], 0
	v_mfma_f32_16x16x32_bf16 v[78:81], v[10:13], v[42:45], 0
	v_mfma_f32_16x16x32_bf16 v[82:85], v[2:5], v[50:53], 0
	v_mfma_f32_16x16x32_bf16 v[86:89], v[10:13], v[50:53], 0
	v_mfma_f32_16x16x32_bf16 v[90:93], v[2:5], v[58:61], 0
	v_mfma_f32_16x16x32_bf16 v[94:97], v[10:13], v[58:61], 0
	v_mfma_f32_16x16x32_bf16 v[66:69], v[6:9], v[38:41], v[66:69]
	v_mfma_f32_16x16x32_bf16 v[70:73], v[14:17], v[38:41], v[70:73]
	v_mfma_f32_16x16x32_bf16 v[74:77], v[6:9], v[46:49], v[74:77]
	v_mfma_f32_16x16x32_bf16 v[78:81], v[14:17], v[46:49], v[78:81]
	v_mfma_f32_16x16x32_bf16 v[82:85], v[6:9], v[54:57], v[82:85]
	v_mfma_f32_16x16x32_bf16 v[86:89], v[14:17], v[54:57], v[86:89]
	v_mfma_f32_16x16x32_bf16 v[90:93], v[6:9], v[62:65], v[90:93]
	v_mfma_f32_16x16x32_bf16 v[94:97], v[14:17], v[62:65], v[94:97]
	v_mfma_f32_16x16x32_bf16 v[98:101], v[18:21], v[34:37], 0
	v_mfma_f32_16x16x32_bf16 v[34:37], v[26:29], v[34:37], 0
	v_mfma_f32_16x16x32_bf16 v[102:105], v[18:21], v[42:45], 0
	v_mfma_f32_16x16x32_bf16 v[42:45], v[26:29], v[42:45], 0
	v_mfma_f32_16x16x32_bf16 v[106:109], v[18:21], v[50:53], 0
	v_mfma_f32_16x16x32_bf16 v[50:53], v[26:29], v[50:53], 0
	v_mfma_f32_16x16x32_bf16 v[110:113], v[18:21], v[58:61], 0
	v_mfma_f32_16x16x32_bf16 v[58:61], v[26:29], v[58:61], 0
	v_mfma_f32_16x16x32_bf16 v[114:117], v[22:25], v[38:41], v[98:101]
	v_mfma_f32_16x16x32_bf16 v[34:37], v[30:33], v[38:41], v[34:37]
	v_mfma_f32_16x16x32_bf16 v[102:105], v[22:25], v[46:49], v[102:105]
	v_mfma_f32_16x16x32_bf16 v[42:45], v[30:33], v[46:49], v[42:45]
	v_mfma_f32_16x16x32_bf16 v[46:49], v[22:25], v[54:57], v[106:109]
	v_mfma_f32_16x16x32_bf16 v[50:53], v[30:33], v[54:57], v[50:53]
	v_mfma_f32_16x16x32_bf16 v[110:113], v[22:25], v[62:65], v[110:113]
	v_mfma_f32_16x16x32_bf16 v[58:61], v[30:33], v[62:65], v[58:61]
	s_barrier
	s_add_i32 vcc_lo, s92, s81
	v_mov_b32_e32 v240, v135
	s_mov_b32 m0, vcc_lo
	s_add_i32 vcc_hi, vcc_lo, 0x2000
	ds_read_b128 v[38:41], v145 offset:16384
	ds_read_b128 v[54:57], v145 offset:17408
	ds_read_b128 v[62:65], v145 offset:18432
	ds_read_b128 v[98:101], v145 offset:19456
	ds_read_b128 v[106:109], v145 offset:20480
	ds_read_b128 v[118:121], v145 offset:21504
	ds_read_b128 v[122:125], v145 offset:22528
	ds_read_b128 v[126:129], v145 offset:23552
	v_mov_b32_e32 v241, v137
	global_load_lds_dwordx4 v240, s[8:9]
	s_mov_b32 m0, vcc_hi
	s_nop 0
	global_load_lds_dwordx4 v241, s[8:9]
	s_add_u32 s8, s68, 0x40100
	s_addc_u32 s9, s69, 0
	s_add_i32 s34, s93, s81
	s_mov_b32 m0, s34
	s_add_i32 s35, s34, 0x2000
	s_nop 0
	global_load_lds_dwordx4 v240, s[8:9]
	s_mov_b32 m0, s35
	s_nop 0
	global_load_lds_dwordx4 v241, s[8:9]
	s_mov_b64 s[8:9], s[72:73]
	s_mov_b32 m0, s84
	s_nop 0
	global_load_lds_dwordx4 v238, s[8:9]
	s_mov_b32 m0, s85
	s_nop 0
	global_load_lds_dwordx4 v239, s[8:9]
	s_waitcnt vmcnt(8)
	s_waitcnt lgkmcnt(0)
	s_barrier
	s_waitcnt lgkmcnt(0)
	v_mfma_f32_16x16x32_bf16 v[146:149], v[2:5], v[38:41], 0
	v_mfma_f32_16x16x32_bf16 v[150:153], v[10:13], v[38:41], 0
	v_mfma_f32_16x16x32_bf16 v[154:157], v[2:5], v[62:65], 0
	v_mfma_f32_16x16x32_bf16 v[158:161], v[10:13], v[62:65], 0
	v_mfma_f32_16x16x32_bf16 v[162:165], v[2:5], v[106:109], 0
	v_mfma_f32_16x16x32_bf16 v[166:169], v[10:13], v[106:109], 0
	v_mfma_f32_16x16x32_bf16 v[2:5], v[2:5], v[122:125], 0
	v_mfma_f32_16x16x32_bf16 v[10:13], v[10:13], v[122:125], 0
	v_mfma_f32_16x16x32_bf16 v[170:173], v[6:9], v[54:57], v[146:149]
	v_mfma_f32_16x16x32_bf16 v[148:151], v[14:17], v[54:57], v[150:153]
	v_mfma_f32_16x16x32_bf16 v[152:155], v[6:9], v[98:101], v[154:157]
	v_mfma_f32_16x16x32_bf16 v[156:159], v[14:17], v[98:101], v[158:161]
	v_mfma_f32_16x16x32_bf16 v[160:163], v[6:9], v[118:121], v[162:165]
	v_mfma_f32_16x16x32_bf16 v[2:5], v[6:9], v[126:129], v[2:5]
	v_mfma_f32_16x16x32_bf16 v[6:9], v[14:17], v[126:129], v[10:13]
	v_mfma_f32_16x16x32_bf16 v[164:167], v[14:17], v[118:121], v[166:169]
	v_mfma_f32_16x16x32_bf16 v[10:13], v[18:21], v[38:41], 0
	v_mfma_f32_16x16x32_bf16 v[14:17], v[26:29], v[38:41], 0
	v_mfma_f32_16x16x32_bf16 v[38:41], v[18:21], v[62:65], 0
	v_mfma_f32_16x16x32_bf16 v[62:65], v[26:29], v[62:65], 0
	v_mfma_f32_16x16x32_bf16 v[174:177], v[18:21], v[106:109], 0
	v_mfma_f32_16x16x32_bf16 v[106:109], v[26:29], v[106:109], 0
	v_mfma_f32_16x16x32_bf16 v[18:21], v[18:21], v[122:125], 0
	v_mfma_f32_16x16x32_bf16 v[26:29], v[26:29], v[122:125], 0
	v_mfma_f32_16x16x32_bf16 v[178:181], v[22:25], v[54:57], v[10:13]
	v_mfma_f32_16x16x32_bf16 v[14:17], v[30:33], v[54:57], v[14:17]
	v_mfma_f32_16x16x32_bf16 v[182:185], v[22:25], v[98:101], v[38:41]
	v_mfma_f32_16x16x32_bf16 v[186:189], v[30:33], v[98:101], v[62:65]
	v_mfma_f32_16x16x32_bf16 v[174:177], v[22:25], v[118:121], v[174:177]
	v_mfma_f32_16x16x32_bf16 v[190:193], v[30:33], v[118:121], v[106:109]
	v_mfma_f32_16x16x32_bf16 v[22:25], v[22:25], v[126:129], v[18:21]
	v_mfma_f32_16x16x32_bf16 v[30:33], v[30:33], v[126:129], v[26:29]
	s_barrier
	s_add_i32 s11, 0, 0x18000
	s_add_i32 s24, 0, 0x1c000
	v_add_u32_e32 v146, s11, v139
	v_add_u32_e32 v147, s24, v139
	ds_read_b128 v[10:13], v146
	ds_read_b128 v[194:197], v146 offset:1024
	ds_read_b128 v[18:21], v146 offset:2048
	ds_read_b128 v[198:201], v146 offset:3072
	ds_read_b128 v[202:205], v147
	ds_read_b128 v[206:209], v147 offset:1024
	ds_read_b128 v[210:213], v147 offset:2048
	ds_read_b128 v[214:217], v147 offset:3072
	s_add_u32 s8, s70, 0x40100
	s_addc_u32 s9, s71, 0
	s_mov_b32 m0, s86
	ds_read_b128 v[26:29], v145 offset:32768
	ds_read_b128 v[62:65], v145 offset:33792
	ds_read_b128 v[122:125], v145 offset:34816
	ds_read_b128 v[218:221], v145 offset:35840
	ds_read_b128 v[222:225], v145 offset:36864
	ds_read_b128 v[226:229], v145 offset:37888
	ds_read_b128 v[230:233], v145 offset:38912
	ds_read_b128 v[234:237], v145 offset:39936
	s_nop 0
	global_load_lds_dwordx4 v238, s[8:9]
	s_mov_b32 m0, s87
	s_nop 0
	global_load_lds_dwordx4 v239, s[8:9]
	s_waitcnt vmcnt(8)
	s_waitcnt lgkmcnt(0)
	s_barrier
	s_waitcnt lgkmcnt(0)
	v_mfma_f32_16x16x32_bf16 v[38:41], v[10:13], v[26:29], v[66:69]
	v_mfma_f32_16x16x32_bf16 v[54:57], v[18:21], v[26:29], v[70:73]
	v_mfma_f32_16x16x32_bf16 v[66:69], v[10:13], v[122:125], v[74:77]
	v_mfma_f32_16x16x32_bf16 v[70:73], v[18:21], v[122:125], v[78:81]
	v_mfma_f32_16x16x32_bf16 v[74:77], v[10:13], v[222:225], v[82:85]
	v_mfma_f32_16x16x32_bf16 v[78:81], v[18:21], v[222:225], v[86:89]
	v_mfma_f32_16x16x32_bf16 v[82:85], v[10:13], v[230:233], v[90:93]
	v_mfma_f32_16x16x32_bf16 v[90:93], v[18:21], v[230:233], v[94:97]
	v_mfma_f32_16x16x32_bf16 v[126:129], v[194:197], v[62:65], v[38:41]
	v_mfma_f32_16x16x32_bf16 v[118:121], v[198:201], v[62:65], v[54:57]
	v_mfma_f32_16x16x32_bf16 v[106:109], v[194:197], v[218:221], v[66:69]
	v_mfma_f32_16x16x32_bf16 v[98:101], v[198:201], v[218:221], v[70:73]
	v_mfma_f32_16x16x32_bf16 v[86:89], v[194:197], v[226:229], v[74:77]
	v_mfma_f32_16x16x32_bf16 v[70:73], v[198:201], v[226:229], v[78:81]
	v_mfma_f32_16x16x32_bf16 v[54:57], v[194:197], v[234:237], v[82:85]
	v_mfma_f32_16x16x32_bf16 v[38:41], v[198:201], v[234:237], v[90:93]
	v_mfma_f32_16x16x32_bf16 v[66:69], v[202:205], v[26:29], v[114:117]
	v_mfma_f32_16x16x32_bf16 v[26:29], v[210:213], v[26:29], v[34:37]
	v_mfma_f32_16x16x32_bf16 v[34:37], v[202:205], v[122:125], v[102:105]
	v_mfma_f32_16x16x32_bf16 v[42:45], v[210:213], v[122:125], v[42:45]
	v_mfma_f32_16x16x32_bf16 v[46:49], v[202:205], v[222:225], v[46:49]
	v_mfma_f32_16x16x32_bf16 v[50:53], v[210:213], v[222:225], v[50:53]
	v_mfma_f32_16x16x32_bf16 v[74:77], v[202:205], v[230:233], v[110:113]
	v_mfma_f32_16x16x32_bf16 v[58:61], v[210:213], v[230:233], v[58:61]
	v_mfma_f32_16x16x32_bf16 v[122:125], v[206:209], v[62:65], v[66:69]
	v_mfma_f32_16x16x32_bf16 v[114:117], v[214:217], v[62:65], v[26:29]
	v_mfma_f32_16x16x32_bf16 v[110:113], v[206:209], v[218:221], v[34:37]
	v_mfma_f32_16x16x32_bf16 v[102:105], v[214:217], v[218:221], v[42:45]
	v_mfma_f32_16x16x32_bf16 v[94:97], v[206:209], v[226:229], v[46:49]
	v_mfma_f32_16x16x32_bf16 v[78:81], v[214:217], v[226:229], v[50:53]
	v_mfma_f32_16x16x32_bf16 v[62:65], v[206:209], v[234:237], v[74:77]
	v_mfma_f32_16x16x32_bf16 v[46:49], v[214:217], v[234:237], v[58:61]
	s_barrier
	s_add_i32 s11, s11, s81
	s_add_i32 s80, s11, 0x2000
	s_mov_b32 m0, s11
	s_add_u32 s22, s68, 0x40180
	ds_read_b128 v[42:45], v145 offset:49152
	ds_read_b128 v[58:61], v145 offset:50176
	ds_read_b128 v[74:77], v145 offset:51200
	ds_read_b128 v[218:221], v145 offset:52224
	ds_read_b128 v[90:93], v145 offset:53248
	ds_read_b128 v[222:225], v145 offset:54272
	ds_read_b128 v[226:229], v145 offset:55296
	ds_read_b128 v[230:233], v145 offset:56320
	s_addc_u32 s23, s69, 0
	global_load_lds_dwordx4 v240, s[76:77]
	s_mov_b32 m0, s80
	s_add_i32 s8, s24, s81
	global_load_lds_dwordx4 v241, s[76:77]
	s_mov_b32 m0, s8
	s_add_i32 s9, s8, 0x2000
	s_nop 0
	global_load_lds_dwordx4 v240, s[22:23]
	s_mov_b32 m0, s9
	s_nop 0
	global_load_lds_dwordx4 v241, s[22:23]
	s_mov_b32 m0, s89
	s_nop 0
	global_load_lds_dwordx4 v238, s[74:75]
	s_mov_b32 m0, s90
	s_nop 0
	global_load_lds_dwordx4 v239, s[74:75]
	s_waitcnt vmcnt(8)
	s_waitcnt lgkmcnt(0)
	s_barrier
	s_waitcnt lgkmcnt(0)
	v_mfma_f32_16x16x32_bf16 v[26:29], v[10:13], v[42:45], v[170:173]
	v_mfma_f32_16x16x32_bf16 v[34:37], v[18:21], v[42:45], v[148:151]
	v_mfma_f32_16x16x32_bf16 v[50:53], v[10:13], v[74:77], v[152:155]
	v_mfma_f32_16x16x32_bf16 v[148:151], v[18:21], v[74:77], v[156:159]
	v_mfma_f32_16x16x32_bf16 v[152:155], v[10:13], v[90:93], v[160:163]
	v_mfma_f32_16x16x32_bf16 v[156:159], v[18:21], v[90:93], v[164:167]
	v_mfma_f32_16x16x32_bf16 v[2:5], v[10:13], v[226:229], v[2:5]
	v_mfma_f32_16x16x32_bf16 v[6:9], v[18:21], v[226:229], v[6:9]
	v_mfma_f32_16x16x32_bf16 v[82:85], v[194:197], v[58:61], v[26:29]
	v_mfma_f32_16x16x32_bf16 v[66:69], v[198:201], v[58:61], v[34:37]
	v_mfma_f32_16x16x32_bf16 v[50:53], v[194:197], v[218:221], v[50:53]
	v_mfma_f32_16x16x32_bf16 v[34:37], v[198:201], v[218:221], v[148:151]
	v_mfma_f32_16x16x32_bf16 v[26:29], v[194:197], v[222:225], v[152:155]
	v_mfma_f32_16x16x32_bf16 v[18:21], v[198:201], v[222:225], v[156:159]
	v_mfma_f32_16x16x32_bf16 v[10:13], v[194:197], v[230:233], v[2:5]
	v_mfma_f32_16x16x32_bf16 v[2:5], v[198:201], v[230:233], v[6:9]
	v_mfma_f32_16x16x32_bf16 v[6:9], v[202:205], v[42:45], v[178:181]
	v_mfma_f32_16x16x32_bf16 v[14:17], v[210:213], v[42:45], v[14:17]
	v_mfma_f32_16x16x32_bf16 v[42:45], v[202:205], v[74:77], v[182:185]
	v_mfma_f32_16x16x32_bf16 v[148:151], v[210:213], v[74:77], v[186:189]
	v_mfma_f32_16x16x32_bf16 v[152:155], v[202:205], v[90:93], v[174:177]
	v_mfma_f32_16x16x32_bf16 v[156:159], v[210:213], v[90:93], v[190:193]
	v_mfma_f32_16x16x32_bf16 v[160:163], v[202:205], v[226:229], v[22:25]
	v_mfma_f32_16x16x32_bf16 v[164:167], v[210:213], v[226:229], v[30:33]
	v_mfma_f32_16x16x32_bf16 v[90:93], v[206:209], v[58:61], v[6:9]
	v_mfma_f32_16x16x32_bf16 v[74:77], v[214:217], v[58:61], v[14:17]
	v_mfma_f32_16x16x32_bf16 v[58:61], v[206:209], v[218:221], v[42:45]
	v_mfma_f32_16x16x32_bf16 v[42:45], v[214:217], v[218:221], v[148:151]
	v_mfma_f32_16x16x32_bf16 v[30:33], v[206:209], v[222:225], v[152:155]
	v_mfma_f32_16x16x32_bf16 v[22:25], v[214:217], v[222:225], v[156:159]
	v_mfma_f32_16x16x32_bf16 v[14:17], v[206:209], v[230:233], v[160:163]
	v_mfma_f32_16x16x32_bf16 v[6:9], v[214:217], v[230:233], v[164:167]
	s_barrier
	s_add_u32 s78, s68, 0x200
	s_addc_u32 s62, s69, 0
	s_mov_b32 s22, 0
.LBB0_328:
	ds_read_b128 v[148:151], v143
	ds_read_b128 v[152:155], v143 offset:1024
	ds_read_b128 v[156:159], v143 offset:2048
	ds_read_b128 v[160:163], v143 offset:3072
	ds_read_b128 v[164:167], v144
	ds_read_b128 v[168:171], v144 offset:1024
	ds_read_b128 v[172:175], v144 offset:2048
	ds_read_b128 v[176:179], v144 offset:3072
	s_add_u32 s68, s72, 0x100
	s_addc_u32 s69, s73, 0
	s_cmp_eq_u32 s22, 12
	s_cselect_b32 s76, s27, s68
	s_cselect_b32 s77, s15, s69
	s_cselect_b32 s74, s95, s78
	s_cselect_b32 s75, s21, s62
	s_add_u32 s70, s76, 0x80
	s_addc_u32 s71, s77, 0
	s_add_u32 s24, s72, 0x40080
	s_mov_b32 m0, s96
	s_addc_u32 s25, s73, 0
	v_mov_b32_e32 v212, v134
	ds_read_b128 v[180:183], v145
	ds_read_b128 v[184:187], v145 offset:1024
	ds_read_b128 v[188:191], v145 offset:2048
	ds_read_b128 v[192:195], v145 offset:3072
	ds_read_b128 v[196:199], v145 offset:4096
	ds_read_b128 v[200:203], v145 offset:5120
	ds_read_b128 v[204:207], v145 offset:6144
	ds_read_b128 v[208:211], v145 offset:7168
	v_mov_b32_e32 v213, v136
	global_load_lds_dwordx4 v212, s[24:25]
	s_mov_b32 m0, s97
	s_add_u32 s72, s74, 0x80
	global_load_lds_dwordx4 v213, s[24:25]
	s_waitcnt vmcnt(8)
	s_waitcnt lgkmcnt(0)
	s_addc_u32 s73, s75, 0
	s_barrier
	s_waitcnt lgkmcnt(0)
	v_mfma_f32_16x16x32_bf16 v[126:129], v[148:151], v[180:183], v[126:129]
	v_mfma_f32_16x16x32_bf16 v[118:121], v[156:159], v[180:183], v[118:121]
	v_mfma_f32_16x16x32_bf16 v[106:109], v[148:151], v[188:191], v[106:109]
	v_mfma_f32_16x16x32_bf16 v[98:101], v[156:159], v[188:191], v[98:101]
	v_mfma_f32_16x16x32_bf16 v[86:89], v[148:151], v[196:199], v[86:89]
	v_mfma_f32_16x16x32_bf16 v[70:73], v[156:159], v[196:199], v[70:73]
	v_mfma_f32_16x16x32_bf16 v[54:57], v[148:151], v[204:207], v[54:57]
	v_mfma_f32_16x16x32_bf16 v[38:41], v[156:159], v[204:207], v[38:41]
	v_mfma_f32_16x16x32_bf16 v[126:129], v[152:155], v[184:187], v[126:129]
	v_mfma_f32_16x16x32_bf16 v[118:121], v[160:163], v[184:187], v[118:121]
	v_mfma_f32_16x16x32_bf16 v[106:109], v[152:155], v[192:195], v[106:109]
	v_mfma_f32_16x16x32_bf16 v[98:101], v[160:163], v[192:195], v[98:101]
	v_mfma_f32_16x16x32_bf16 v[86:89], v[152:155], v[200:203], v[86:89]
	v_mfma_f32_16x16x32_bf16 v[70:73], v[160:163], v[200:203], v[70:73]
	v_mfma_f32_16x16x32_bf16 v[54:57], v[152:155], v[208:211], v[54:57]
	v_mfma_f32_16x16x32_bf16 v[38:41], v[160:163], v[208:211], v[38:41]
	v_mfma_f32_16x16x32_bf16 v[122:125], v[164:167], v[180:183], v[122:125]
	v_mfma_f32_16x16x32_bf16 v[114:117], v[172:175], v[180:183], v[114:117]
	v_mfma_f32_16x16x32_bf16 v[110:113], v[164:167], v[188:191], v[110:113]
	v_mfma_f32_16x16x32_bf16 v[102:105], v[172:175], v[188:191], v[102:105]
	v_mfma_f32_16x16x32_bf16 v[94:97], v[164:167], v[196:199], v[94:97]
	v_mfma_f32_16x16x32_bf16 v[78:81], v[172:175], v[196:199], v[78:81]
	v_mfma_f32_16x16x32_bf16 v[62:65], v[164:167], v[204:207], v[62:65]
	v_mfma_f32_16x16x32_bf16 v[46:49], v[172:175], v[204:207], v[46:49]
	v_mfma_f32_16x16x32_bf16 v[122:125], v[168:171], v[184:187], v[122:125]
	v_mfma_f32_16x16x32_bf16 v[114:117], v[176:179], v[184:187], v[114:117]
	v_mfma_f32_16x16x32_bf16 v[110:113], v[168:171], v[192:195], v[110:113]
	v_mfma_f32_16x16x32_bf16 v[102:105], v[176:179], v[192:195], v[102:105]
	v_mfma_f32_16x16x32_bf16 v[94:97], v[168:171], v[200:203], v[94:97]
	v_mfma_f32_16x16x32_bf16 v[78:81], v[176:179], v[200:203], v[78:81]
	v_mfma_f32_16x16x32_bf16 v[62:65], v[168:171], v[208:211], v[62:65]
	v_mfma_f32_16x16x32_bf16 v[46:49], v[176:179], v[208:211], v[46:49]
	s_barrier
	s_mov_b32 m0, vcc_lo
	s_mov_b64 s[24:25], s[74:75]
	v_mov_b32_e32 v214, v135
	ds_read_b128 v[180:183], v145 offset:16384
	ds_read_b128 v[184:187], v145 offset:17408
	ds_read_b128 v[188:191], v145 offset:18432
	ds_read_b128 v[192:195], v145 offset:19456
	ds_read_b128 v[196:199], v145 offset:20480
	ds_read_b128 v[200:203], v145 offset:21504
	ds_read_b128 v[204:207], v145 offset:22528
	ds_read_b128 v[208:211], v145 offset:23552
	v_mov_b32_e32 v215, v137
	global_load_lds_dwordx4 v214, s[24:25]
	s_mov_b32 m0, vcc_hi
	s_nop 0
	global_load_lds_dwordx4 v215, s[24:25]
	s_add_u32 s24, s74, 0x40000
	s_addc_u32 s25, s75, 0
	s_mov_b32 m0, s34
	s_nop 0
	global_load_lds_dwordx4 v214, s[24:25]
	s_mov_b32 m0, s35
	s_nop 0
	global_load_lds_dwordx4 v215, s[24:25]
	s_mov_b64 s[24:25], s[76:77]
	s_mov_b32 m0, s84
	s_nop 0
	global_load_lds_dwordx4 v212, s[24:25]
	s_mov_b32 m0, s85
	s_nop 0
	global_load_lds_dwordx4 v213, s[24:25]
	s_waitcnt vmcnt(8)
	s_waitcnt lgkmcnt(0)
	s_barrier
	s_waitcnt lgkmcnt(0)
	v_mfma_f32_16x16x32_bf16 v[82:85], v[148:151], v[180:183], v[82:85]
	v_mfma_f32_16x16x32_bf16 v[66:69], v[156:159], v[180:183], v[66:69]
	v_mfma_f32_16x16x32_bf16 v[50:53], v[148:151], v[188:191], v[50:53]
	v_mfma_f32_16x16x32_bf16 v[34:37], v[156:159], v[188:191], v[34:37]
	v_mfma_f32_16x16x32_bf16 v[26:29], v[148:151], v[196:199], v[26:29]
	v_mfma_f32_16x16x32_bf16 v[18:21], v[156:159], v[196:199], v[18:21]
	v_mfma_f32_16x16x32_bf16 v[10:13], v[148:151], v[204:207], v[10:13]
	v_mfma_f32_16x16x32_bf16 v[2:5], v[156:159], v[204:207], v[2:5]
	v_mfma_f32_16x16x32_bf16 v[82:85], v[152:155], v[184:187], v[82:85]
	v_mfma_f32_16x16x32_bf16 v[66:69], v[160:163], v[184:187], v[66:69]
	v_mfma_f32_16x16x32_bf16 v[50:53], v[152:155], v[192:195], v[50:53]
	v_mfma_f32_16x16x32_bf16 v[34:37], v[160:163], v[192:195], v[34:37]
	v_mfma_f32_16x16x32_bf16 v[26:29], v[152:155], v[200:203], v[26:29]
	v_mfma_f32_16x16x32_bf16 v[18:21], v[160:163], v[200:203], v[18:21]
	v_mfma_f32_16x16x32_bf16 v[10:13], v[152:155], v[208:211], v[10:13]
	v_mfma_f32_16x16x32_bf16 v[2:5], v[160:163], v[208:211], v[2:5]
	v_mfma_f32_16x16x32_bf16 v[90:93], v[164:167], v[180:183], v[90:93]
	v_mfma_f32_16x16x32_bf16 v[74:77], v[172:175], v[180:183], v[74:77]
	v_mfma_f32_16x16x32_bf16 v[58:61], v[164:167], v[188:191], v[58:61]
	v_mfma_f32_16x16x32_bf16 v[42:45], v[172:175], v[188:191], v[42:45]
	v_mfma_f32_16x16x32_bf16 v[30:33], v[164:167], v[196:199], v[30:33]
	v_mfma_f32_16x16x32_bf16 v[22:25], v[172:175], v[196:199], v[22:25]
	v_mfma_f32_16x16x32_bf16 v[14:17], v[164:167], v[204:207], v[14:17]
	v_mfma_f32_16x16x32_bf16 v[6:9], v[172:175], v[204:207], v[6:9]
	v_mfma_f32_16x16x32_bf16 v[90:93], v[168:171], v[184:187], v[90:93]
	v_mfma_f32_16x16x32_bf16 v[74:77], v[176:179], v[184:187], v[74:77]
	v_mfma_f32_16x16x32_bf16 v[58:61], v[168:171], v[192:195], v[58:61]
	v_mfma_f32_16x16x32_bf16 v[42:45], v[176:179], v[192:195], v[42:45]
	v_mfma_f32_16x16x32_bf16 v[30:33], v[168:171], v[200:203], v[30:33]
	v_mfma_f32_16x16x32_bf16 v[22:25], v[176:179], v[200:203], v[22:25]
	v_mfma_f32_16x16x32_bf16 v[14:17], v[168:171], v[208:211], v[14:17]
	v_mfma_f32_16x16x32_bf16 v[6:9], v[176:179], v[208:211], v[6:9]
	s_barrier
	ds_read_b128 v[148:151], v146
	ds_read_b128 v[152:155], v146 offset:1024
	ds_read_b128 v[156:159], v146 offset:2048
	ds_read_b128 v[160:163], v146 offset:3072
	ds_read_b128 v[164:167], v147
	ds_read_b128 v[168:171], v147 offset:1024
	ds_read_b128 v[172:175], v147 offset:2048
	ds_read_b128 v[176:179], v147 offset:3072
	s_add_u32 s24, s76, 0x40000
	s_addc_u32 s25, s77, 0
	s_mov_b32 m0, s86
	ds_read_b128 v[180:183], v145 offset:32768
	ds_read_b128 v[184:187], v145 offset:33792
	ds_read_b128 v[188:191], v145 offset:34816
	ds_read_b128 v[192:195], v145 offset:35840
	ds_read_b128 v[196:199], v145 offset:36864
	ds_read_b128 v[200:203], v145 offset:37888
	ds_read_b128 v[204:207], v145 offset:38912
	ds_read_b128 v[208:211], v145 offset:39936
	s_nop 0
	global_load_lds_dwordx4 v212, s[24:25]
	s_mov_b32 m0, s87
	s_nop 0
	global_load_lds_dwordx4 v213, s[24:25]
	s_waitcnt vmcnt(8)
	s_waitcnt lgkmcnt(0)
	s_barrier
	s_waitcnt lgkmcnt(0)
	v_mfma_f32_16x16x32_bf16 v[126:129], v[148:151], v[180:183], v[126:129]
	v_mfma_f32_16x16x32_bf16 v[118:121], v[156:159], v[180:183], v[118:121]
	v_mfma_f32_16x16x32_bf16 v[106:109], v[148:151], v[188:191], v[106:109]
	v_mfma_f32_16x16x32_bf16 v[98:101], v[156:159], v[188:191], v[98:101]
	v_mfma_f32_16x16x32_bf16 v[86:89], v[148:151], v[196:199], v[86:89]
	v_mfma_f32_16x16x32_bf16 v[70:73], v[156:159], v[196:199], v[70:73]
	v_mfma_f32_16x16x32_bf16 v[54:57], v[148:151], v[204:207], v[54:57]
	v_mfma_f32_16x16x32_bf16 v[38:41], v[156:159], v[204:207], v[38:41]
	v_mfma_f32_16x16x32_bf16 v[126:129], v[152:155], v[184:187], v[126:129]
	v_mfma_f32_16x16x32_bf16 v[118:121], v[160:163], v[184:187], v[118:121]
	v_mfma_f32_16x16x32_bf16 v[106:109], v[152:155], v[192:195], v[106:109]
	v_mfma_f32_16x16x32_bf16 v[98:101], v[160:163], v[192:195], v[98:101]
	v_mfma_f32_16x16x32_bf16 v[86:89], v[152:155], v[200:203], v[86:89]
	v_mfma_f32_16x16x32_bf16 v[70:73], v[160:163], v[200:203], v[70:73]
	v_mfma_f32_16x16x32_bf16 v[54:57], v[152:155], v[208:211], v[54:57]
	v_mfma_f32_16x16x32_bf16 v[38:41], v[160:163], v[208:211], v[38:41]
	v_mfma_f32_16x16x32_bf16 v[122:125], v[164:167], v[180:183], v[122:125]
	v_mfma_f32_16x16x32_bf16 v[114:117], v[172:175], v[180:183], v[114:117]
	v_mfma_f32_16x16x32_bf16 v[110:113], v[164:167], v[188:191], v[110:113]
	v_mfma_f32_16x16x32_bf16 v[102:105], v[172:175], v[188:191], v[102:105]
	v_mfma_f32_16x16x32_bf16 v[94:97], v[164:167], v[196:199], v[94:97]
	v_mfma_f32_16x16x32_bf16 v[78:81], v[172:175], v[196:199], v[78:81]
	v_mfma_f32_16x16x32_bf16 v[62:65], v[164:167], v[204:207], v[62:65]
	v_mfma_f32_16x16x32_bf16 v[46:49], v[172:175], v[204:207], v[46:49]
	v_mfma_f32_16x16x32_bf16 v[122:125], v[168:171], v[184:187], v[122:125]
	v_mfma_f32_16x16x32_bf16 v[114:117], v[176:179], v[184:187], v[114:117]
	v_mfma_f32_16x16x32_bf16 v[110:113], v[168:171], v[192:195], v[110:113]
	v_mfma_f32_16x16x32_bf16 v[102:105], v[176:179], v[192:195], v[102:105]
	v_mfma_f32_16x16x32_bf16 v[94:97], v[168:171], v[200:203], v[94:97]
	v_mfma_f32_16x16x32_bf16 v[78:81], v[176:179], v[200:203], v[78:81]
	v_mfma_f32_16x16x32_bf16 v[62:65], v[168:171], v[208:211], v[62:65]
	v_mfma_f32_16x16x32_bf16 v[46:49], v[176:179], v[208:211], v[46:49]
	s_barrier
	s_mov_b32 m0, s11
	ds_read_b128 v[180:183], v145 offset:49152
	ds_read_b128 v[184:187], v145 offset:50176
	ds_read_b128 v[188:191], v145 offset:51200
	ds_read_b128 v[192:195], v145 offset:52224
	ds_read_b128 v[196:199], v145 offset:53248
	ds_read_b128 v[200:203], v145 offset:54272
	ds_read_b128 v[204:207], v145 offset:55296
	ds_read_b128 v[208:211], v145 offset:56320
	s_add_u32 s24, s74, 0x40080
	global_load_lds_dwordx4 v214, s[72:73]
	s_mov_b32 m0, s80
	s_addc_u32 s25, s75, 0
	global_load_lds_dwordx4 v215, s[72:73]
	s_mov_b32 m0, s8
	s_nop 0
	global_load_lds_dwordx4 v214, s[24:25]
	s_mov_b32 m0, s9
	s_nop 0
	global_load_lds_dwordx4 v215, s[24:25]
	s_mov_b32 m0, s89
	s_nop 0
	global_load_lds_dwordx4 v212, s[70:71]
	s_mov_b32 m0, s90
	s_nop 0
	global_load_lds_dwordx4 v213, s[70:71]
	s_waitcnt vmcnt(8)
	s_waitcnt lgkmcnt(0)
	s_barrier
	s_waitcnt lgkmcnt(0)
	v_mfma_f32_16x16x32_bf16 v[82:85], v[148:151], v[180:183], v[82:85]
	v_mfma_f32_16x16x32_bf16 v[66:69], v[156:159], v[180:183], v[66:69]
	v_mfma_f32_16x16x32_bf16 v[50:53], v[148:151], v[188:191], v[50:53]
	v_mfma_f32_16x16x32_bf16 v[34:37], v[156:159], v[188:191], v[34:37]
	v_mfma_f32_16x16x32_bf16 v[26:29], v[148:151], v[196:199], v[26:29]
	v_mfma_f32_16x16x32_bf16 v[18:21], v[156:159], v[196:199], v[18:21]
	v_mfma_f32_16x16x32_bf16 v[10:13], v[148:151], v[204:207], v[10:13]
	v_mfma_f32_16x16x32_bf16 v[2:5], v[156:159], v[204:207], v[2:5]
	v_mfma_f32_16x16x32_bf16 v[82:85], v[152:155], v[184:187], v[82:85]
	v_mfma_f32_16x16x32_bf16 v[66:69], v[160:163], v[184:187], v[66:69]
	v_mfma_f32_16x16x32_bf16 v[50:53], v[152:155], v[192:195], v[50:53]
	v_mfma_f32_16x16x32_bf16 v[34:37], v[160:163], v[192:195], v[34:37]
	v_mfma_f32_16x16x32_bf16 v[26:29], v[152:155], v[200:203], v[26:29]
	v_mfma_f32_16x16x32_bf16 v[18:21], v[160:163], v[200:203], v[18:21]
	v_mfma_f32_16x16x32_bf16 v[10:13], v[152:155], v[208:211], v[10:13]
	v_mfma_f32_16x16x32_bf16 v[2:5], v[160:163], v[208:211], v[2:5]
	v_mfma_f32_16x16x32_bf16 v[90:93], v[164:167], v[180:183], v[90:93]
	v_mfma_f32_16x16x32_bf16 v[74:77], v[172:175], v[180:183], v[74:77]
	v_mfma_f32_16x16x32_bf16 v[58:61], v[164:167], v[188:191], v[58:61]
	v_mfma_f32_16x16x32_bf16 v[42:45], v[172:175], v[188:191], v[42:45]
	v_mfma_f32_16x16x32_bf16 v[30:33], v[164:167], v[196:199], v[30:33]
	v_mfma_f32_16x16x32_bf16 v[22:25], v[172:175], v[196:199], v[22:25]
	v_mfma_f32_16x16x32_bf16 v[14:17], v[164:167], v[204:207], v[14:17]
	v_mfma_f32_16x16x32_bf16 v[6:9], v[172:175], v[204:207], v[6:9]
	v_mfma_f32_16x16x32_bf16 v[90:93], v[168:171], v[184:187], v[90:93]
	v_mfma_f32_16x16x32_bf16 v[74:77], v[176:179], v[184:187], v[74:77]
	v_mfma_f32_16x16x32_bf16 v[58:61], v[168:171], v[192:195], v[58:61]
	v_mfma_f32_16x16x32_bf16 v[42:45], v[176:179], v[192:195], v[42:45]
	v_mfma_f32_16x16x32_bf16 v[30:33], v[168:171], v[200:203], v[30:33]
	v_mfma_f32_16x16x32_bf16 v[22:25], v[176:179], v[200:203], v[22:25]
	v_mfma_f32_16x16x32_bf16 v[14:17], v[168:171], v[208:211], v[14:17]
	v_mfma_f32_16x16x32_bf16 v[6:9], v[176:179], v[208:211], v[6:9]
	s_barrier
	s_add_i32 s22, s22, 2
	s_add_u32 s78, s78, 0x100
	s_addc_u32 s62, s62, 0
	s_cmp_gt_u32 s22, 13
	s_mov_b64 s[72:73], s[68:69]
	s_cbranch_scc0 .LBB0_328
	s_and_b64 vcc, exec, s[18:19]
	s_cbranch_vccnz .LBB0_333
	v_lshl_add_u32 v146, s14, 8, v138
	s_cmp_gt_i32 s94, 1
	s_mov_b64 s[14:15], -1
	s_cbranch_scc1 .LBB0_334

.LBB0_528:
	s_ashr_i32 s19, s18, 31
	s_lshl_b64 s[8:9], s[18:19], 19
	v_cmp_lt_i64_e32 vcc, s[20:21], v[22:23]
	s_add_u32 s20, s63, s8
	s_addc_u32 s21, s64, s9
	s_and_b64 s[8:9], vcc, exec
	s_cselect_b32 s19, s21, s13
	s_cselect_b32 s80, s20, s12
	s_ashr_i32 s15, s14, 31
	ds_read_b128 v[2:5], v33
	ds_read_b128 v[6:9], v33 offset:1024
	ds_read_b128 v[10:13], v33 offset:2048
	ds_read_b128 v[14:17], v33 offset:3072
	ds_read_b128 v[18:21], v138
	ds_read_b128 v[26:29], v138 offset:1024
	ds_read_b128 v[34:37], v138 offset:2048
	ds_read_b128 v[38:41], v138 offset:3072
	s_lshl_b64 s[8:9], s[14:15], 19
	s_add_u32 s26, s65, s8
	s_addc_u32 s27, s66, s9
	s_and_b64 s[8:9], vcc, exec
	s_cselect_b32 s15, s27, s5
	s_cselect_b32 s81, s26, s4
	s_add_u32 s38, s12, 0x100
	s_addc_u32 s39, s13, 0
	s_add_u32 s8, s4, 0x100
	s_addc_u32 s9, s5, 0
	s_add_u32 s28, s12, 0x180
	s_addc_u32 s29, s13, 0
	s_add_u32 s22, s12, 0x40080
	s_addc_u32 s23, s13, 0
	s_add_i32 s82, s68, 0xc000
	v_mov_b32_e32 v176, v30
	s_mov_b32 m0, s82
	s_add_i32 s83, s68, 0xe000
	ds_read_b128 v[42:45], v139
	ds_read_b128 v[46:49], v139 offset:1024
	ds_read_b128 v[50:53], v139 offset:2048
	ds_read_b128 v[54:57], v139 offset:3072
	ds_read_b128 v[58:61], v139 offset:4096
	ds_read_b128 v[62:65], v139 offset:5120
	ds_read_b128 v[66:69], v139 offset:6144
	ds_read_b128 v[70:73], v139 offset:7168
	v_mov_b32_e32 v177, v31
	global_load_lds_dwordx4 v176, s[22:23]
	s_mov_b32 m0, s83
	s_add_u32 s30, s4, 0x180
	global_load_lds_dwordx4 v177, s[22:23]
	s_waitcnt vmcnt(8)
	s_waitcnt lgkmcnt(0)
	s_addc_u32 s31, s5, 0
	s_barrier
	s_waitcnt lgkmcnt(0)
	v_mfma_f32_16x16x32_bf16 v[74:77], v[2:5], v[42:45], 0
	v_mfma_f32_16x16x32_bf16 v[78:81], v[10:13], v[42:45], 0
	v_mfma_f32_16x16x32_bf16 v[82:85], v[2:5], v[50:53], 0
	v_mfma_f32_16x16x32_bf16 v[86:89], v[10:13], v[50:53], 0
	v_mfma_f32_16x16x32_bf16 v[90:93], v[2:5], v[58:61], 0
	v_mfma_f32_16x16x32_bf16 v[94:97], v[10:13], v[58:61], 0
	v_mfma_f32_16x16x32_bf16 v[98:101], v[2:5], v[66:69], 0
	v_mfma_f32_16x16x32_bf16 v[102:105], v[10:13], v[66:69], 0
	v_mfma_f32_16x16x32_bf16 v[74:77], v[6:9], v[46:49], v[74:77]
	v_mfma_f32_16x16x32_bf16 v[78:81], v[14:17], v[46:49], v[78:81]
	v_mfma_f32_16x16x32_bf16 v[82:85], v[6:9], v[54:57], v[82:85]
	v_mfma_f32_16x16x32_bf16 v[86:89], v[14:17], v[54:57], v[86:89]
	v_mfma_f32_16x16x32_bf16 v[90:93], v[6:9], v[62:65], v[90:93]
	v_mfma_f32_16x16x32_bf16 v[94:97], v[14:17], v[62:65], v[94:97]
	v_mfma_f32_16x16x32_bf16 v[98:101], v[6:9], v[70:73], v[98:101]
	v_mfma_f32_16x16x32_bf16 v[102:105], v[14:17], v[70:73], v[102:105]
	v_mfma_f32_16x16x32_bf16 v[106:109], v[18:21], v[42:45], 0
	v_mfma_f32_16x16x32_bf16 v[42:45], v[34:37], v[42:45], 0
	v_mfma_f32_16x16x32_bf16 v[110:113], v[18:21], v[50:53], 0
	v_mfma_f32_16x16x32_bf16 v[50:53], v[34:37], v[50:53], 0
	v_mfma_f32_16x16x32_bf16 v[114:117], v[18:21], v[58:61], 0
	v_mfma_f32_16x16x32_bf16 v[58:61], v[34:37], v[58:61], 0
	v_mfma_f32_16x16x32_bf16 v[118:121], v[18:21], v[66:69], 0
	v_mfma_f32_16x16x32_bf16 v[66:69], v[34:37], v[66:69], 0
	v_mfma_f32_16x16x32_bf16 v[106:109], v[26:29], v[46:49], v[106:109]
	v_mfma_f32_16x16x32_bf16 v[46:49], v[38:41], v[46:49], v[42:45]
	v_mfma_f32_16x16x32_bf16 v[110:113], v[26:29], v[54:57], v[110:113]
	v_mfma_f32_16x16x32_bf16 v[54:57], v[38:41], v[54:57], v[50:53]
	v_mfma_f32_16x16x32_bf16 v[114:117], v[26:29], v[62:65], v[114:117]
	v_mfma_f32_16x16x32_bf16 v[58:61], v[38:41], v[62:65], v[58:61]
	v_mfma_f32_16x16x32_bf16 v[62:65], v[26:29], v[70:73], v[118:121]
	v_mfma_f32_16x16x32_bf16 v[66:69], v[38:41], v[70:73], v[66:69]
	s_barrier
	s_add_i32 s84, s75, s67
	s_mov_b32 m0, s84
	s_add_i32 s85, s84, 0x2000
	ds_read_b128 v[42:45], v139 offset:16384
	ds_read_b128 v[50:53], v139 offset:17408
	ds_read_b128 v[70:73], v139 offset:18432
	ds_read_b128 v[118:121], v139 offset:19456
	ds_read_b128 v[122:125], v139 offset:20480
	ds_read_b128 v[126:129], v139 offset:21504
	ds_read_b128 v[130:133], v139 offset:22528
	ds_read_b128 v[134:137], v139 offset:23552
	s_nop 0
	global_load_lds_dwordx4 v176, s[8:9]
	s_mov_b32 m0, s85
	s_nop 0
	global_load_lds_dwordx4 v177, s[8:9]
	s_add_u32 s8, s4, 0x40100
	s_addc_u32 s9, s5, 0
	s_add_i32 s34, s76, s67
	s_mov_b32 m0, s34
	s_add_i32 s35, s34, 0x2000
	s_nop 0
	global_load_lds_dwordx4 v176, s[8:9]
	s_mov_b32 m0, s35
	s_nop 0
	global_load_lds_dwordx4 v177, s[8:9]
	s_mov_b32 m0, s68
	s_nop 0
	global_load_lds_dwordx4 v176, s[38:39]
	s_mov_b32 m0, s69
	s_nop 0
	global_load_lds_dwordx4 v177, s[38:39]
	s_waitcnt vmcnt(8)
	s_waitcnt lgkmcnt(0)
	s_barrier
	s_waitcnt lgkmcnt(0)
	v_mfma_f32_16x16x32_bf16 v[140:143], v[2:5], v[42:45], 0
	v_mfma_f32_16x16x32_bf16 v[144:147], v[10:13], v[42:45], 0
	v_mfma_f32_16x16x32_bf16 v[148:151], v[2:5], v[70:73], 0
	v_mfma_f32_16x16x32_bf16 v[152:155], v[10:13], v[70:73], 0
	v_mfma_f32_16x16x32_bf16 v[156:159], v[2:5], v[122:125], 0
	v_mfma_f32_16x16x32_bf16 v[160:163], v[10:13], v[122:125], 0
	v_mfma_f32_16x16x32_bf16 v[2:5], v[2:5], v[130:133], 0
	v_mfma_f32_16x16x32_bf16 v[10:13], v[10:13], v[130:133], 0
	v_mfma_f32_16x16x32_bf16 v[164:167], v[6:9], v[50:53], v[140:143]
	v_mfma_f32_16x16x32_bf16 v[142:145], v[14:17], v[50:53], v[144:147]
	v_mfma_f32_16x16x32_bf16 v[146:149], v[6:9], v[118:121], v[148:151]
	v_mfma_f32_16x16x32_bf16 v[150:153], v[14:17], v[118:121], v[152:155]
	v_mfma_f32_16x16x32_bf16 v[154:157], v[6:9], v[126:129], v[156:159]
	v_mfma_f32_16x16x32_bf16 v[158:161], v[14:17], v[126:129], v[160:163]
	v_mfma_f32_16x16x32_bf16 v[168:171], v[6:9], v[134:137], v[2:5]
	v_mfma_f32_16x16x32_bf16 v[172:175], v[14:17], v[134:137], v[10:13]
	v_mfma_f32_16x16x32_bf16 v[2:5], v[18:21], v[42:45], 0
	v_mfma_f32_16x16x32_bf16 v[6:9], v[34:37], v[42:45], 0
	v_mfma_f32_16x16x32_bf16 v[10:13], v[18:21], v[70:73], 0
	v_mfma_f32_16x16x32_bf16 v[14:17], v[34:37], v[70:73], 0
	v_mfma_f32_16x16x32_bf16 v[42:45], v[18:21], v[122:125], 0
	v_mfma_f32_16x16x32_bf16 v[70:73], v[34:37], v[122:125], 0
	v_mfma_f32_16x16x32_bf16 v[18:21], v[18:21], v[130:133], 0
	v_mfma_f32_16x16x32_bf16 v[34:37], v[34:37], v[130:133], 0
	v_mfma_f32_16x16x32_bf16 v[122:125], v[26:29], v[50:53], v[2:5]
	v_mfma_f32_16x16x32_bf16 v[130:133], v[38:41], v[50:53], v[6:9]
	v_mfma_f32_16x16x32_bf16 v[182:185], v[26:29], v[118:121], v[10:13]
	v_mfma_f32_16x16x32_bf16 v[118:121], v[38:41], v[118:121], v[14:17]
	v_mfma_f32_16x16x32_bf16 v[186:189], v[26:29], v[126:129], v[42:45]
	v_mfma_f32_16x16x32_bf16 v[126:129], v[38:41], v[126:129], v[70:73]
	v_mfma_f32_16x16x32_bf16 v[190:193], v[26:29], v[134:137], v[18:21]
	v_mfma_f32_16x16x32_bf16 v[134:137], v[38:41], v[134:137], v[34:37]
	s_barrier
	s_add_i32 s11, 0, 0x18000
	s_add_i32 s24, 0, 0x1c000
	v_add_u32_e32 v140, s11, v32
	v_add_u32_e32 v141, s24, v32
	ds_read_b128 v[70:73], v140
	ds_read_b128 v[194:197], v140 offset:1024
	ds_read_b128 v[198:201], v140 offset:2048
	ds_read_b128 v[202:205], v140 offset:3072
	ds_read_b128 v[206:209], v141
	ds_read_b128 v[210:213], v141 offset:1024
	ds_read_b128 v[214:217], v141 offset:2048
	ds_read_b128 v[218:221], v141 offset:3072
	s_add_u32 s8, s12, 0x40100
	s_addc_u32 s9, s13, 0
	s_mov_b32 m0, s70
	ds_read_b128 v[14:17], v139 offset:32768
	ds_read_b128 v[26:29], v139 offset:33792
	ds_read_b128 v[222:225], v139 offset:34816
	ds_read_b128 v[226:229], v139 offset:35840
	ds_read_b128 v[230:233], v139 offset:36864
	ds_read_b128 v[234:237], v139 offset:37888
	ds_read_b128 v[238:241], v139 offset:38912
	ds_read_b128 v[242:245], v139 offset:39936
	s_nop 0
	global_load_lds_dwordx4 v176, s[8:9]
	s_mov_b32 m0, s71
	s_nop 0
	global_load_lds_dwordx4 v177, s[8:9]
	s_waitcnt vmcnt(8)
	s_waitcnt lgkmcnt(0)
	s_barrier
	s_waitcnt lgkmcnt(0)
	v_mfma_f32_16x16x32_bf16 v[2:5], v[70:73], v[14:17], v[74:77]
	v_mfma_f32_16x16x32_bf16 v[6:9], v[198:201], v[14:17], v[78:81]
	v_mfma_f32_16x16x32_bf16 v[10:13], v[70:73], v[222:225], v[82:85]
	v_mfma_f32_16x16x32_bf16 v[34:37], v[198:201], v[222:225], v[86:89]
	v_mfma_f32_16x16x32_bf16 v[38:41], v[70:73], v[230:233], v[90:93]
	v_mfma_f32_16x16x32_bf16 v[42:45], v[198:201], v[230:233], v[94:97]
	v_mfma_f32_16x16x32_bf16 v[74:77], v[70:73], v[238:241], v[98:101]
	v_mfma_f32_16x16x32_bf16 v[78:81], v[198:201], v[238:241], v[102:105]
	v_mfma_f32_16x16x32_bf16 v[18:21], v[194:197], v[26:29], v[2:5]
	v_mfma_f32_16x16x32_bf16 v[6:9], v[202:205], v[26:29], v[6:9]
	v_mfma_f32_16x16x32_bf16 v[10:13], v[194:197], v[226:229], v[10:13]
	v_mfma_f32_16x16x32_bf16 v[2:5], v[202:205], v[226:229], v[34:37]
	v_mfma_f32_16x16x32_bf16 v[50:53], v[194:197], v[234:237], v[38:41]
	v_mfma_f32_16x16x32_bf16 v[38:41], v[202:205], v[234:237], v[42:45]
	v_mfma_f32_16x16x32_bf16 v[42:45], v[194:197], v[242:245], v[74:77]
	v_mfma_f32_16x16x32_bf16 v[34:37], v[202:205], v[242:245], v[78:81]
	v_mfma_f32_16x16x32_bf16 v[74:77], v[206:209], v[14:17], v[106:109]
	v_mfma_f32_16x16x32_bf16 v[14:17], v[214:217], v[14:17], v[46:49]
	v_mfma_f32_16x16x32_bf16 v[46:49], v[206:209], v[222:225], v[110:113]
	v_mfma_f32_16x16x32_bf16 v[78:81], v[214:217], v[222:225], v[54:57]
	v_mfma_f32_16x16x32_bf16 v[82:85], v[206:209], v[230:233], v[114:117]
	v_mfma_f32_16x16x32_bf16 v[58:61], v[214:217], v[230:233], v[58:61]
	v_mfma_f32_16x16x32_bf16 v[86:89], v[206:209], v[238:241], v[62:65]
	v_mfma_f32_16x16x32_bf16 v[66:69], v[214:217], v[238:241], v[66:69]
	v_mfma_f32_16x16x32_bf16 v[62:65], v[210:213], v[26:29], v[74:77]
	v_mfma_f32_16x16x32_bf16 v[26:29], v[218:221], v[26:29], v[14:17]
	v_mfma_f32_16x16x32_bf16 v[54:57], v[210:213], v[226:229], v[46:49]
	v_mfma_f32_16x16x32_bf16 v[14:17], v[218:221], v[226:229], v[78:81]
	v_mfma_f32_16x16x32_bf16 v[94:97], v[210:213], v[234:237], v[82:85]
	v_mfma_f32_16x16x32_bf16 v[58:61], v[218:221], v[234:237], v[58:61]
	v_mfma_f32_16x16x32_bf16 v[86:89], v[210:213], v[242:245], v[86:89]
	v_mfma_f32_16x16x32_bf16 v[46:49], v[218:221], v[242:245], v[66:69]
	s_barrier
	s_add_i32 s11, s11, s67
	s_add_i32 s86, s11, 0x2000
	s_mov_b32 m0, s11
	s_add_u32 s22, s4, 0x40180
	ds_read_b128 v[78:81], v139 offset:49152
	ds_read_b128 v[90:93], v139 offset:50176
	ds_read_b128 v[110:113], v139 offset:51200
	ds_read_b128 v[222:225], v139 offset:52224
	ds_read_b128 v[226:229], v139 offset:53248
	ds_read_b128 v[230:233], v139 offset:54272
	ds_read_b128 v[234:237], v139 offset:55296
	ds_read_b128 v[238:241], v139 offset:56320
	s_addc_u32 s23, s5, 0
	global_load_lds_dwordx4 v176, s[30:31]
	s_mov_b32 m0, s86
	s_add_i32 s8, s24, s67
	global_load_lds_dwordx4 v177, s[30:31]
	s_mov_b32 m0, s8
	s_add_i32 s9, s8, 0x2000
	s_nop 0
	global_load_lds_dwordx4 v176, s[22:23]
	s_mov_b32 m0, s9
	s_nop 0
	global_load_lds_dwordx4 v177, s[22:23]
	s_mov_b32 m0, s73
	s_nop 0
	global_load_lds_dwordx4 v176, s[28:29]
	s_mov_b32 m0, s74
	s_nop 0
	global_load_lds_dwordx4 v177, s[28:29]
	s_waitcnt vmcnt(8)
	s_waitcnt lgkmcnt(0)
	s_barrier
	s_waitcnt lgkmcnt(0)
	v_mfma_f32_16x16x32_bf16 v[66:69], v[70:73], v[78:81], v[164:167]
	v_mfma_f32_16x16x32_bf16 v[74:77], v[198:201], v[78:81], v[142:145]
	v_mfma_f32_16x16x32_bf16 v[98:101], v[70:73], v[110:113], v[146:149]
	v_mfma_f32_16x16x32_bf16 v[102:105], v[198:201], v[110:113], v[150:153]
	v_mfma_f32_16x16x32_bf16 v[106:109], v[70:73], v[226:229], v[154:157]
	v_mfma_f32_16x16x32_bf16 v[142:145], v[198:201], v[226:229], v[158:161]
	v_mfma_f32_16x16x32_bf16 v[146:149], v[70:73], v[234:237], v[168:171]
	v_mfma_f32_16x16x32_bf16 v[150:153], v[198:201], v[234:237], v[172:175]
	v_mfma_f32_16x16x32_bf16 v[82:85], v[194:197], v[90:93], v[66:69]
	v_mfma_f32_16x16x32_bf16 v[70:73], v[202:205], v[90:93], v[74:77]
	v_mfma_f32_16x16x32_bf16 v[74:77], v[194:197], v[222:225], v[98:101]
	v_mfma_f32_16x16x32_bf16 v[66:69], v[202:205], v[222:225], v[102:105]
	v_mfma_f32_16x16x32_bf16 v[114:117], v[194:197], v[230:233], v[106:109]
	v_mfma_f32_16x16x32_bf16 v[102:105], v[202:205], v[230:233], v[142:145]
	v_mfma_f32_16x16x32_bf16 v[106:109], v[194:197], v[238:241], v[146:149]
	v_mfma_f32_16x16x32_bf16 v[98:101], v[202:205], v[238:241], v[150:153]
	v_mfma_f32_16x16x32_bf16 v[122:125], v[206:209], v[78:81], v[122:125]
	v_mfma_f32_16x16x32_bf16 v[78:81], v[214:217], v[78:81], v[130:133]
	v_mfma_f32_16x16x32_bf16 v[130:133], v[206:209], v[110:113], v[182:185]
	v_mfma_f32_16x16x32_bf16 v[110:113], v[214:217], v[110:113], v[118:121]
	v_mfma_f32_16x16x32_bf16 v[142:145], v[206:209], v[226:229], v[186:189]
	v_mfma_f32_16x16x32_bf16 v[146:149], v[214:217], v[226:229], v[126:129]
	v_mfma_f32_16x16x32_bf16 v[150:153], v[206:209], v[234:237], v[190:193]
	v_mfma_f32_16x16x32_bf16 v[154:157], v[214:217], v[234:237], v[134:137]
	v_mfma_f32_16x16x32_bf16 v[126:129], v[210:213], v[90:93], v[122:125]
	v_mfma_f32_16x16x32_bf16 v[90:93], v[218:221], v[90:93], v[78:81]
	v_mfma_f32_16x16x32_bf16 v[118:121], v[210:213], v[222:225], v[130:133]
	v_mfma_f32_16x16x32_bf16 v[78:81], v[218:221], v[222:225], v[110:113]
	v_mfma_f32_16x16x32_bf16 v[134:137], v[210:213], v[230:233], v[142:145]
	v_mfma_f32_16x16x32_bf16 v[122:125], v[218:221], v[230:233], v[146:149]
	v_mfma_f32_16x16x32_bf16 v[130:133], v[210:213], v[238:241], v[150:153]
	v_mfma_f32_16x16x32_bf16 v[110:113], v[218:221], v[238:241], v[154:157]
	s_barrier
	s_mov_b32 s22, 0
	s_mov_b64 s[28:29], 0
.LBB0_529:
	s_add_u32 s23, s12, s28
	ds_read_b128 v[142:145], v33
	ds_read_b128 v[146:149], v33 offset:1024
	ds_read_b128 v[150:153], v33 offset:2048
	ds_read_b128 v[154:157], v33 offset:3072
	ds_read_b128 v[158:161], v138
	ds_read_b128 v[162:165], v138 offset:1024
	ds_read_b128 v[166:169], v138 offset:2048
	ds_read_b128 v[170:173], v138 offset:3072
	s_addc_u32 s25, s13, s29
	s_add_u32 s24, s23, 0x200
	s_addc_u32 s30, s25, 0
	s_add_u32 s31, s4, s28
	s_addc_u32 s38, s5, s29
	s_add_u32 s31, s31, 0x200
	s_addc_u32 s39, s38, 0
	s_cmp_eq_u32 s22, 12
	s_cselect_b32 s42, s80, s24
	s_cselect_b32 s43, s19, s30
	s_cselect_b32 s38, s81, s31
	s_cselect_b32 s39, s15, s39
	s_add_u32 s30, s42, 0x80
	s_addc_u32 s31, s43, 0
	s_add_u32 s24, s23, 0x40180
	s_mov_b32 m0, s82
	s_addc_u32 s25, s25, 0
	v_mov_b32_e32 v181, v30
	ds_read_b128 v[174:177], v139
	ds_read_b128 v[182:185], v139 offset:1024
	ds_read_b128 v[186:189], v139 offset:2048
	ds_read_b128 v[190:193], v139 offset:3072
	ds_read_b128 v[194:197], v139 offset:4096
	ds_read_b128 v[198:201], v139 offset:5120
	ds_read_b128 v[202:205], v139 offset:6144
	ds_read_b128 v[206:209], v139 offset:7168
	v_mov_b32_e32 v210, v31
	global_load_lds_dwordx4 v181, s[24:25]
	s_mov_b32 m0, s83
	s_add_u32 s40, s38, 0x80
	global_load_lds_dwordx4 v210, s[24:25]
	s_waitcnt vmcnt(8)
	s_waitcnt lgkmcnt(0)
	s_addc_u32 s41, s39, 0
	s_barrier
	s_waitcnt lgkmcnt(0)
	v_mfma_f32_16x16x32_bf16 v[18:21], v[142:145], v[174:177], v[18:21]
	v_mfma_f32_16x16x32_bf16 v[6:9], v[150:153], v[174:177], v[6:9]
	v_mfma_f32_16x16x32_bf16 v[10:13], v[142:145], v[186:189], v[10:13]
	v_mfma_f32_16x16x32_bf16 v[2:5], v[150:153], v[186:189], v[2:5]
	v_mfma_f32_16x16x32_bf16 v[50:53], v[142:145], v[194:197], v[50:53]
	v_mfma_f32_16x16x32_bf16 v[38:41], v[150:153], v[194:197], v[38:41]
	v_mfma_f32_16x16x32_bf16 v[42:45], v[142:145], v[202:205], v[42:45]
	v_mfma_f32_16x16x32_bf16 v[34:37], v[150:153], v[202:205], v[34:37]
	v_mfma_f32_16x16x32_bf16 v[18:21], v[146:149], v[182:185], v[18:21]
	v_mfma_f32_16x16x32_bf16 v[6:9], v[154:157], v[182:185], v[6:9]
	v_mfma_f32_16x16x32_bf16 v[10:13], v[146:149], v[190:193], v[10:13]
	v_mfma_f32_16x16x32_bf16 v[2:5], v[154:157], v[190:193], v[2:5]
	v_mfma_f32_16x16x32_bf16 v[50:53], v[146:149], v[198:201], v[50:53]
	v_mfma_f32_16x16x32_bf16 v[38:41], v[154:157], v[198:201], v[38:41]
	v_mfma_f32_16x16x32_bf16 v[42:45], v[146:149], v[206:209], v[42:45]
	v_mfma_f32_16x16x32_bf16 v[34:37], v[154:157], v[206:209], v[34:37]
	v_mfma_f32_16x16x32_bf16 v[62:65], v[158:161], v[174:177], v[62:65]
	v_mfma_f32_16x16x32_bf16 v[26:29], v[166:169], v[174:177], v[26:29]
	v_mfma_f32_16x16x32_bf16 v[54:57], v[158:161], v[186:189], v[54:57]
	v_mfma_f32_16x16x32_bf16 v[14:17], v[166:169], v[186:189], v[14:17]
	v_mfma_f32_16x16x32_bf16 v[94:97], v[158:161], v[194:197], v[94:97]
	v_mfma_f32_16x16x32_bf16 v[58:61], v[166:169], v[194:197], v[58:61]
	v_mfma_f32_16x16x32_bf16 v[86:89], v[158:161], v[202:205], v[86:89]
	v_mfma_f32_16x16x32_bf16 v[46:49], v[166:169], v[202:205], v[46:49]
	v_mfma_f32_16x16x32_bf16 v[62:65], v[162:165], v[182:185], v[62:65]
	v_mfma_f32_16x16x32_bf16 v[26:29], v[170:173], v[182:185], v[26:29]
	v_mfma_f32_16x16x32_bf16 v[54:57], v[162:165], v[190:193], v[54:57]
	v_mfma_f32_16x16x32_bf16 v[14:17], v[170:173], v[190:193], v[14:17]
	v_mfma_f32_16x16x32_bf16 v[94:97], v[162:165], v[198:201], v[94:97]
	v_mfma_f32_16x16x32_bf16 v[58:61], v[170:173], v[198:201], v[58:61]
	v_mfma_f32_16x16x32_bf16 v[86:89], v[162:165], v[206:209], v[86:89]
	v_mfma_f32_16x16x32_bf16 v[46:49], v[170:173], v[206:209], v[46:49]
	s_barrier
	s_mov_b32 m0, s84
	s_mov_b64 s[24:25], s[38:39]
	ds_read_b128 v[174:177], v139 offset:16384
	ds_read_b128 v[182:185], v139 offset:17408
	ds_read_b128 v[186:189], v139 offset:18432
	ds_read_b128 v[190:193], v139 offset:19456
	ds_read_b128 v[194:197], v139 offset:20480
	ds_read_b128 v[198:201], v139 offset:21504
	ds_read_b128 v[202:205], v139 offset:22528
	ds_read_b128 v[206:209], v139 offset:23552
	s_nop 0
	global_load_lds_dwordx4 v181, s[24:25]
	s_mov_b32 m0, s85
	s_nop 0
	global_load_lds_dwordx4 v210, s[24:25]
	s_add_u32 s24, s38, 0x40000
	s_addc_u32 s25, s39, 0
	s_mov_b32 m0, s34
	s_nop 0
	global_load_lds_dwordx4 v181, s[24:25]
	s_mov_b32 m0, s35
	s_nop 0
	global_load_lds_dwordx4 v210, s[24:25]
	s_mov_b64 s[24:25], s[42:43]
	s_mov_b32 m0, s68
	s_nop 0
	global_load_lds_dwordx4 v181, s[24:25]
	s_mov_b32 m0, s69
	s_nop 0
	global_load_lds_dwordx4 v210, s[24:25]
	s_waitcnt vmcnt(8)
	s_waitcnt lgkmcnt(0)
	s_barrier
	s_waitcnt lgkmcnt(0)
	v_mfma_f32_16x16x32_bf16 v[82:85], v[142:145], v[174:177], v[82:85]
	v_mfma_f32_16x16x32_bf16 v[70:73], v[150:153], v[174:177], v[70:73]
	v_mfma_f32_16x16x32_bf16 v[74:77], v[142:145], v[186:189], v[74:77]
	v_mfma_f32_16x16x32_bf16 v[66:69], v[150:153], v[186:189], v[66:69]
	v_mfma_f32_16x16x32_bf16 v[114:117], v[142:145], v[194:197], v[114:117]
	v_mfma_f32_16x16x32_bf16 v[102:105], v[150:153], v[194:197], v[102:105]
	v_mfma_f32_16x16x32_bf16 v[106:109], v[142:145], v[202:205], v[106:109]
	v_mfma_f32_16x16x32_bf16 v[98:101], v[150:153], v[202:205], v[98:101]
	v_mfma_f32_16x16x32_bf16 v[82:85], v[146:149], v[182:185], v[82:85]
	v_mfma_f32_16x16x32_bf16 v[70:73], v[154:157], v[182:185], v[70:73]
	v_mfma_f32_16x16x32_bf16 v[74:77], v[146:149], v[190:193], v[74:77]
	v_mfma_f32_16x16x32_bf16 v[66:69], v[154:157], v[190:193], v[66:69]
	v_mfma_f32_16x16x32_bf16 v[114:117], v[146:149], v[198:201], v[114:117]
	v_mfma_f32_16x16x32_bf16 v[102:105], v[154:157], v[198:201], v[102:105]
	v_mfma_f32_16x16x32_bf16 v[106:109], v[146:149], v[206:209], v[106:109]
	v_mfma_f32_16x16x32_bf16 v[98:101], v[154:157], v[206:209], v[98:101]
	v_mfma_f32_16x16x32_bf16 v[126:129], v[158:161], v[174:177], v[126:129]
	v_mfma_f32_16x16x32_bf16 v[90:93], v[166:169], v[174:177], v[90:93]
	v_mfma_f32_16x16x32_bf16 v[118:121], v[158:161], v[186:189], v[118:121]
	v_mfma_f32_16x16x32_bf16 v[78:81], v[166:169], v[186:189], v[78:81]
	v_mfma_f32_16x16x32_bf16 v[134:137], v[158:161], v[194:197], v[134:137]
	v_mfma_f32_16x16x32_bf16 v[122:125], v[166:169], v[194:197], v[122:125]
	v_mfma_f32_16x16x32_bf16 v[130:133], v[158:161], v[202:205], v[130:133]
	v_mfma_f32_16x16x32_bf16 v[110:113], v[166:169], v[202:205], v[110:113]
	v_mfma_f32_16x16x32_bf16 v[126:129], v[162:165], v[182:185], v[126:129]
	v_mfma_f32_16x16x32_bf16 v[90:93], v[170:173], v[182:185], v[90:93]
	v_mfma_f32_16x16x32_bf16 v[118:121], v[162:165], v[190:193], v[118:121]
	v_mfma_f32_16x16x32_bf16 v[78:81], v[170:173], v[190:193], v[78:81]
	v_mfma_f32_16x16x32_bf16 v[134:137], v[162:165], v[198:201], v[134:137]
	v_mfma_f32_16x16x32_bf16 v[122:125], v[170:173], v[198:201], v[122:125]
	v_mfma_f32_16x16x32_bf16 v[130:133], v[162:165], v[206:209], v[130:133]
	v_mfma_f32_16x16x32_bf16 v[110:113], v[170:173], v[206:209], v[110:113]
	s_barrier
	ds_read_b128 v[142:145], v140
	ds_read_b128 v[146:149], v140 offset:1024
	ds_read_b128 v[150:153], v140 offset:2048
	ds_read_b128 v[154:157], v140 offset:3072
	ds_read_b128 v[158:161], v141
	ds_read_b128 v[162:165], v141 offset:1024
	ds_read_b128 v[166:169], v141 offset:2048
	ds_read_b128 v[170:173], v141 offset:3072
	s_add_u32 s24, s42, 0x40000
	s_addc_u32 s25, s43, 0
	s_mov_b32 m0, s70
	ds_read_b128 v[174:177], v139 offset:32768
	ds_read_b128 v[182:185], v139 offset:33792
	ds_read_b128 v[186:189], v139 offset:34816
	ds_read_b128 v[190:193], v139 offset:35840
	ds_read_b128 v[194:197], v139 offset:36864
	ds_read_b128 v[198:201], v139 offset:37888
	ds_read_b128 v[202:205], v139 offset:38912
	ds_read_b128 v[206:209], v139 offset:39936
	s_nop 0
	global_load_lds_dwordx4 v181, s[24:25]
	s_mov_b32 m0, s71
	s_nop 0
	global_load_lds_dwordx4 v210, s[24:25]
	s_waitcnt vmcnt(8)
	s_waitcnt lgkmcnt(0)
	s_barrier
	s_waitcnt lgkmcnt(0)
	v_mfma_f32_16x16x32_bf16 v[18:21], v[142:145], v[174:177], v[18:21]
	v_mfma_f32_16x16x32_bf16 v[6:9], v[150:153], v[174:177], v[6:9]
	v_mfma_f32_16x16x32_bf16 v[10:13], v[142:145], v[186:189], v[10:13]
	v_mfma_f32_16x16x32_bf16 v[2:5], v[150:153], v[186:189], v[2:5]
	v_mfma_f32_16x16x32_bf16 v[50:53], v[142:145], v[194:197], v[50:53]
	v_mfma_f32_16x16x32_bf16 v[38:41], v[150:153], v[194:197], v[38:41]
	v_mfma_f32_16x16x32_bf16 v[42:45], v[142:145], v[202:205], v[42:45]
	v_mfma_f32_16x16x32_bf16 v[34:37], v[150:153], v[202:205], v[34:37]
	v_mfma_f32_16x16x32_bf16 v[18:21], v[146:149], v[182:185], v[18:21]
	v_mfma_f32_16x16x32_bf16 v[6:9], v[154:157], v[182:185], v[6:9]
	v_mfma_f32_16x16x32_bf16 v[10:13], v[146:149], v[190:193], v[10:13]
	v_mfma_f32_16x16x32_bf16 v[2:5], v[154:157], v[190:193], v[2:5]
	v_mfma_f32_16x16x32_bf16 v[50:53], v[146:149], v[198:201], v[50:53]
	v_mfma_f32_16x16x32_bf16 v[38:41], v[154:157], v[198:201], v[38:41]
	v_mfma_f32_16x16x32_bf16 v[42:45], v[146:149], v[206:209], v[42:45]
	v_mfma_f32_16x16x32_bf16 v[34:37], v[154:157], v[206:209], v[34:37]
	v_mfma_f32_16x16x32_bf16 v[62:65], v[158:161], v[174:177], v[62:65]
	v_mfma_f32_16x16x32_bf16 v[26:29], v[166:169], v[174:177], v[26:29]
	v_mfma_f32_16x16x32_bf16 v[54:57], v[158:161], v[186:189], v[54:57]
	v_mfma_f32_16x16x32_bf16 v[14:17], v[166:169], v[186:189], v[14:17]
	v_mfma_f32_16x16x32_bf16 v[94:97], v[158:161], v[194:197], v[94:97]
	v_mfma_f32_16x16x32_bf16 v[58:61], v[166:169], v[194:197], v[58:61]
	v_mfma_f32_16x16x32_bf16 v[86:89], v[158:161], v[202:205], v[86:89]
	v_mfma_f32_16x16x32_bf16 v[46:49], v[166:169], v[202:205], v[46:49]
	v_mfma_f32_16x16x32_bf16 v[62:65], v[162:165], v[182:185], v[62:65]
	v_mfma_f32_16x16x32_bf16 v[26:29], v[170:173], v[182:185], v[26:29]
	v_mfma_f32_16x16x32_bf16 v[54:57], v[162:165], v[190:193], v[54:57]
	v_mfma_f32_16x16x32_bf16 v[14:17], v[170:173], v[190:193], v[14:17]
	v_mfma_f32_16x16x32_bf16 v[94:97], v[162:165], v[198:201], v[94:97]
	v_mfma_f32_16x16x32_bf16 v[58:61], v[170:173], v[198:201], v[58:61]
	v_mfma_f32_16x16x32_bf16 v[86:89], v[162:165], v[206:209], v[86:89]
	v_mfma_f32_16x16x32_bf16 v[46:49], v[170:173], v[206:209], v[46:49]
	s_barrier
	s_mov_b32 m0, s11
	ds_read_b128 v[174:177], v139 offset:49152
	ds_read_b128 v[182:185], v139 offset:50176
	ds_read_b128 v[186:189], v139 offset:51200
	ds_read_b128 v[190:193], v139 offset:52224
	ds_read_b128 v[194:197], v139 offset:53248
	ds_read_b128 v[198:201], v139 offset:54272
	ds_read_b128 v[202:205], v139 offset:55296
	ds_read_b128 v[206:209], v139 offset:56320
	s_add_u32 s24, s38, 0x40080
	global_load_lds_dwordx4 v181, s[40:41]
	s_mov_b32 m0, s86
	s_addc_u32 s25, s39, 0
	global_load_lds_dwordx4 v210, s[40:41]
	s_mov_b32 m0, s8
	s_nop 0
	global_load_lds_dwordx4 v181, s[24:25]
	s_mov_b32 m0, s9
	s_nop 0
	global_load_lds_dwordx4 v210, s[24:25]
	s_mov_b32 m0, s73
	s_nop 0
	global_load_lds_dwordx4 v181, s[30:31]
	s_mov_b32 m0, s74
	s_nop 0
	global_load_lds_dwordx4 v210, s[30:31]
	s_waitcnt vmcnt(8)
	s_waitcnt lgkmcnt(0)
	s_barrier
	s_waitcnt lgkmcnt(0)
	v_mfma_f32_16x16x32_bf16 v[82:85], v[142:145], v[174:177], v[82:85]
	v_mfma_f32_16x16x32_bf16 v[70:73], v[150:153], v[174:177], v[70:73]
	v_mfma_f32_16x16x32_bf16 v[74:77], v[142:145], v[186:189], v[74:77]
	v_mfma_f32_16x16x32_bf16 v[66:69], v[150:153], v[186:189], v[66:69]
	v_mfma_f32_16x16x32_bf16 v[114:117], v[142:145], v[194:197], v[114:117]
	v_mfma_f32_16x16x32_bf16 v[102:105], v[150:153], v[194:197], v[102:105]
	v_mfma_f32_16x16x32_bf16 v[106:109], v[142:145], v[202:205], v[106:109]
	v_mfma_f32_16x16x32_bf16 v[98:101], v[150:153], v[202:205], v[98:101]
	v_mfma_f32_16x16x32_bf16 v[82:85], v[146:149], v[182:185], v[82:85]
	v_mfma_f32_16x16x32_bf16 v[70:73], v[154:157], v[182:185], v[70:73]
	v_mfma_f32_16x16x32_bf16 v[74:77], v[146:149], v[190:193], v[74:77]
	v_mfma_f32_16x16x32_bf16 v[66:69], v[154:157], v[190:193], v[66:69]
	v_mfma_f32_16x16x32_bf16 v[114:117], v[146:149], v[198:201], v[114:117]
	v_mfma_f32_16x16x32_bf16 v[102:105], v[154:157], v[198:201], v[102:105]
	v_mfma_f32_16x16x32_bf16 v[106:109], v[146:149], v[206:209], v[106:109]
	v_mfma_f32_16x16x32_bf16 v[98:101], v[154:157], v[206:209], v[98:101]
	v_mfma_f32_16x16x32_bf16 v[126:129], v[158:161], v[174:177], v[126:129]
	v_mfma_f32_16x16x32_bf16 v[90:93], v[166:169], v[174:177], v[90:93]
	v_mfma_f32_16x16x32_bf16 v[118:121], v[158:161], v[186:189], v[118:121]
	v_mfma_f32_16x16x32_bf16 v[78:81], v[166:169], v[186:189], v[78:81]
	v_mfma_f32_16x16x32_bf16 v[134:137], v[158:161], v[194:197], v[134:137]
	v_mfma_f32_16x16x32_bf16 v[122:125], v[166:169], v[194:197], v[122:125]
	v_mfma_f32_16x16x32_bf16 v[130:133], v[158:161], v[202:205], v[130:133]
	v_mfma_f32_16x16x32_bf16 v[110:113], v[166:169], v[202:205], v[110:113]
	v_mfma_f32_16x16x32_bf16 v[126:129], v[162:165], v[182:185], v[126:129]
	v_mfma_f32_16x16x32_bf16 v[90:93], v[170:173], v[182:185], v[90:93]
	v_mfma_f32_16x16x32_bf16 v[118:121], v[162:165], v[190:193], v[118:121]
	v_mfma_f32_16x16x32_bf16 v[78:81], v[170:173], v[190:193], v[78:81]
	v_mfma_f32_16x16x32_bf16 v[134:137], v[162:165], v[198:201], v[134:137]
	v_mfma_f32_16x16x32_bf16 v[122:125], v[170:173], v[198:201], v[122:125]
	v_mfma_f32_16x16x32_bf16 v[130:133], v[162:165], v[206:209], v[130:133]
	v_mfma_f32_16x16x32_bf16 v[110:113], v[170:173], v[206:209], v[110:113]
	s_barrier
	s_add_i32 s22, s22, 2
	s_add_u32 s28, s28, 0x100
	s_addc_u32 s29, s29, 0
	s_cmp_gt_u32 s22, 13
	s_cbranch_scc0 .LBB0_529
	s_and_b64 vcc, exec, vcc
	s_cbranch_vccz .LBB0_521
	s_mov_b32 s6, s14
	s_mov_b32 s0, s18
	s_mov_b64 s[4:5], s[26:27]
	s_mov_b64 s[12:13], s[20:21]
	s_mov_b32 s72, s77
	s_branch .LBB0_521

.LBB0_618:
	s_ashr_i32 s21, s20, 31
	s_lshl_b64 s[8:9], s[20:21], 19
	s_add_u32 s26, s16, s8
	s_addc_u32 s27, s79, s9
	s_and_b64 s[8:9], s[2:3], exec
	ds_read_b128 v[2:5], v141
	ds_read_b128 v[6:9], v141 offset:1024
	ds_read_b128 v[10:13], v141 offset:2048
	ds_read_b128 v[14:17], v141 offset:3072
	ds_read_b128 v[18:21], v142
	ds_read_b128 v[22:25], v142 offset:1024
	ds_read_b128 v[26:29], v142 offset:2048
	ds_read_b128 v[30:33], v142 offset:3072
	s_cselect_b32 s21, s27, s43
	s_cselect_b32 s76, s26, s42
	s_ashr_i32 s19, s18, 31
	s_lshl_b64 s[8:9], s[18:19], 19
	s_add_u32 s28, s15, s8
	s_addc_u32 s29, s17, s9
	s_and_b64 s[8:9], s[2:3], exec
	s_cselect_b32 s19, s29, s39
	s_cselect_b32 s77, s28, s38
	s_add_u32 s40, s42, 0x100
	s_addc_u32 s41, s43, 0
	s_add_u32 s8, s38, 0x100
	s_addc_u32 s9, s39, 0
	s_add_u32 s44, s42, 0x180
	s_addc_u32 s45, s43, 0
	s_add_u32 s22, s42, 0x40080
	s_addc_u32 s23, s43, 0
	s_add_i32 s80, s31, 0xc000
	v_mov_b32_e32 v232, v134
	s_mov_b32 m0, s80
	s_add_i32 s81, s31, 0xe000
	ds_read_b128 v[34:37], v143
	ds_read_b128 v[38:41], v143 offset:1024
	ds_read_b128 v[42:45], v143 offset:2048
	ds_read_b128 v[46:49], v143 offset:3072
	ds_read_b128 v[50:53], v143 offset:4096
	ds_read_b128 v[54:57], v143 offset:5120
	ds_read_b128 v[58:61], v143 offset:6144
	ds_read_b128 v[62:65], v143 offset:7168
	v_mov_b32_e32 v233, v136
	global_load_lds_dwordx4 v232, s[22:23]
	s_mov_b32 m0, s81
	s_add_u32 s48, s38, 0x180
	global_load_lds_dwordx4 v233, s[22:23]
	s_waitcnt vmcnt(8)
	s_waitcnt lgkmcnt(0)
	s_addc_u32 s49, s39, 0
	s_barrier
	s_waitcnt lgkmcnt(0)
	v_mfma_f32_16x16x32_bf16 v[66:69], v[2:5], v[34:37], 0
	v_mfma_f32_16x16x32_bf16 v[70:73], v[10:13], v[34:37], 0
	v_mfma_f32_16x16x32_bf16 v[74:77], v[2:5], v[42:45], 0
	v_mfma_f32_16x16x32_bf16 v[78:81], v[10:13], v[42:45], 0
	v_mfma_f32_16x16x32_bf16 v[82:85], v[2:5], v[50:53], 0
	v_mfma_f32_16x16x32_bf16 v[86:89], v[10:13], v[50:53], 0
	v_mfma_f32_16x16x32_bf16 v[90:93], v[2:5], v[58:61], 0
	v_mfma_f32_16x16x32_bf16 v[94:97], v[10:13], v[58:61], 0
	v_mfma_f32_16x16x32_bf16 v[66:69], v[6:9], v[38:41], v[66:69]
	v_mfma_f32_16x16x32_bf16 v[70:73], v[14:17], v[38:41], v[70:73]
	v_mfma_f32_16x16x32_bf16 v[74:77], v[6:9], v[46:49], v[74:77]
	v_mfma_f32_16x16x32_bf16 v[78:81], v[14:17], v[46:49], v[78:81]
	v_mfma_f32_16x16x32_bf16 v[82:85], v[6:9], v[54:57], v[82:85]
	v_mfma_f32_16x16x32_bf16 v[86:89], v[14:17], v[54:57], v[86:89]
	v_mfma_f32_16x16x32_bf16 v[90:93], v[6:9], v[62:65], v[90:93]
	v_mfma_f32_16x16x32_bf16 v[94:97], v[14:17], v[62:65], v[94:97]
	v_mfma_f32_16x16x32_bf16 v[98:101], v[18:21], v[34:37], 0
	v_mfma_f32_16x16x32_bf16 v[34:37], v[26:29], v[34:37], 0
	v_mfma_f32_16x16x32_bf16 v[102:105], v[18:21], v[42:45], 0
	v_mfma_f32_16x16x32_bf16 v[42:45], v[26:29], v[42:45], 0
	v_mfma_f32_16x16x32_bf16 v[106:109], v[18:21], v[50:53], 0
	v_mfma_f32_16x16x32_bf16 v[50:53], v[26:29], v[50:53], 0
	v_mfma_f32_16x16x32_bf16 v[110:113], v[18:21], v[58:61], 0
	v_mfma_f32_16x16x32_bf16 v[58:61], v[26:29], v[58:61], 0
	v_mfma_f32_16x16x32_bf16 v[118:121], v[22:25], v[38:41], v[98:101]
	v_mfma_f32_16x16x32_bf16 v[34:37], v[30:33], v[38:41], v[34:37]
	v_mfma_f32_16x16x32_bf16 v[38:41], v[22:25], v[46:49], v[102:105]
	v_mfma_f32_16x16x32_bf16 v[42:45], v[30:33], v[46:49], v[42:45]
	v_mfma_f32_16x16x32_bf16 v[46:49], v[22:25], v[54:57], v[106:109]
	v_mfma_f32_16x16x32_bf16 v[50:53], v[30:33], v[54:57], v[50:53]
	v_mfma_f32_16x16x32_bf16 v[102:105], v[22:25], v[62:65], v[110:113]
	v_mfma_f32_16x16x32_bf16 v[58:61], v[30:33], v[62:65], v[58:61]
	s_barrier
	s_add_i32 s82, s72, s62
	v_mov_b32_e32 v234, v135
	s_mov_b32 m0, s82
	s_add_i32 s83, s82, 0x2000
	ds_read_b128 v[54:57], v143 offset:16384
	ds_read_b128 v[62:65], v143 offset:17408
	ds_read_b128 v[98:101], v143 offset:18432
	ds_read_b128 v[106:109], v143 offset:19456
	ds_read_b128 v[110:113], v143 offset:20480
	ds_read_b128 v[114:117], v143 offset:21504
	ds_read_b128 v[122:125], v143 offset:22528
	ds_read_b128 v[126:129], v143 offset:23552
	v_mov_b32_e32 v235, v137
	global_load_lds_dwordx4 v234, s[8:9]
	s_mov_b32 m0, s83
	s_nop 0
	global_load_lds_dwordx4 v235, s[8:9]
	s_add_u32 s8, s38, 0x40100
	s_addc_u32 s9, s39, 0
	s_add_i32 s34, s73, s62
	s_mov_b32 m0, s34
	s_add_i32 s35, s34, 0x2000
	s_nop 0
	global_load_lds_dwordx4 v234, s[8:9]
	s_mov_b32 m0, s35
	s_nop 0
	global_load_lds_dwordx4 v235, s[8:9]
	s_mov_b64 s[8:9], s[40:41]
	s_mov_b32 m0, s31
	s_nop 0
	global_load_lds_dwordx4 v232, s[8:9]
	s_mov_b32 m0, s65
	s_nop 0
	global_load_lds_dwordx4 v233, s[8:9]
	s_waitcnt vmcnt(8)
	s_waitcnt lgkmcnt(0)
	s_barrier
	s_waitcnt lgkmcnt(0)
	v_mfma_f32_16x16x32_bf16 v[144:147], v[2:5], v[54:57], 0
	v_mfma_f32_16x16x32_bf16 v[148:151], v[10:13], v[54:57], 0
	v_mfma_f32_16x16x32_bf16 v[152:155], v[2:5], v[98:101], 0
	v_mfma_f32_16x16x32_bf16 v[156:159], v[10:13], v[98:101], 0
	v_mfma_f32_16x16x32_bf16 v[160:163], v[2:5], v[110:113], 0
	v_mfma_f32_16x16x32_bf16 v[164:167], v[10:13], v[110:113], 0
	v_mfma_f32_16x16x32_bf16 v[2:5], v[2:5], v[122:125], 0
	v_mfma_f32_16x16x32_bf16 v[10:13], v[10:13], v[122:125], 0
	v_mfma_f32_16x16x32_bf16 v[168:171], v[6:9], v[62:65], v[144:147]
	v_mfma_f32_16x16x32_bf16 v[146:149], v[14:17], v[62:65], v[148:151]
	v_mfma_f32_16x16x32_bf16 v[150:153], v[6:9], v[106:109], v[152:155]
	v_mfma_f32_16x16x32_bf16 v[154:157], v[14:17], v[106:109], v[156:159]
	v_mfma_f32_16x16x32_bf16 v[158:161], v[6:9], v[114:117], v[160:163]
	v_mfma_f32_16x16x32_bf16 v[2:5], v[6:9], v[126:129], v[2:5]
	v_mfma_f32_16x16x32_bf16 v[6:9], v[14:17], v[126:129], v[10:13]
	v_mfma_f32_16x16x32_bf16 v[162:165], v[14:17], v[114:117], v[164:167]
	v_mfma_f32_16x16x32_bf16 v[10:13], v[18:21], v[54:57], 0
	v_mfma_f32_16x16x32_bf16 v[14:17], v[26:29], v[54:57], 0
	v_mfma_f32_16x16x32_bf16 v[54:57], v[18:21], v[98:101], 0
	v_mfma_f32_16x16x32_bf16 v[98:101], v[26:29], v[98:101], 0
	v_mfma_f32_16x16x32_bf16 v[172:175], v[18:21], v[110:113], 0
	v_mfma_f32_16x16x32_bf16 v[110:113], v[26:29], v[110:113], 0
	v_mfma_f32_16x16x32_bf16 v[18:21], v[18:21], v[122:125], 0
	v_mfma_f32_16x16x32_bf16 v[26:29], v[26:29], v[122:125], 0
	v_mfma_f32_16x16x32_bf16 v[176:179], v[22:25], v[62:65], v[10:13]
	v_mfma_f32_16x16x32_bf16 v[14:17], v[30:33], v[62:65], v[14:17]
	v_mfma_f32_16x16x32_bf16 v[180:183], v[22:25], v[106:109], v[54:57]
	v_mfma_f32_16x16x32_bf16 v[184:187], v[30:33], v[106:109], v[98:101]
	v_mfma_f32_16x16x32_bf16 v[172:175], v[22:25], v[114:117], v[172:175]
	v_mfma_f32_16x16x32_bf16 v[188:191], v[30:33], v[114:117], v[110:113]
	v_mfma_f32_16x16x32_bf16 v[22:25], v[22:25], v[126:129], v[18:21]
	v_mfma_f32_16x16x32_bf16 v[30:33], v[30:33], v[126:129], v[26:29]
	s_barrier
	s_add_i32 s11, 0, 0x18000
	s_add_i32 s24, 0, 0x1c000
	v_add_u32_e32 v144, s11, v138
	v_add_u32_e32 v145, s24, v138
	ds_read_b128 v[10:13], v144
	ds_read_b128 v[192:195], v144 offset:1024
	ds_read_b128 v[18:21], v144 offset:2048
	ds_read_b128 v[196:199], v144 offset:3072
	ds_read_b128 v[200:203], v145
	ds_read_b128 v[204:207], v145 offset:1024
	ds_read_b128 v[208:211], v145 offset:2048
	ds_read_b128 v[212:215], v145 offset:3072
	s_add_u32 s8, s42, 0x40100
	s_addc_u32 s9, s43, 0
	s_mov_b32 m0, s66
	ds_read_b128 v[26:29], v143 offset:32768
	ds_read_b128 v[62:65], v143 offset:33792
	ds_read_b128 v[110:113], v143 offset:34816
	ds_read_b128 v[216:219], v143 offset:35840
	ds_read_b128 v[126:129], v143 offset:36864
	ds_read_b128 v[220:223], v143 offset:37888
	ds_read_b128 v[224:227], v143 offset:38912
	ds_read_b128 v[228:231], v143 offset:39936
	s_nop 0
	global_load_lds_dwordx4 v232, s[8:9]
	s_mov_b32 m0, s67
	s_nop 0
	global_load_lds_dwordx4 v233, s[8:9]
	s_waitcnt vmcnt(8)
	s_waitcnt lgkmcnt(0)
	s_barrier
	s_waitcnt lgkmcnt(0)
	v_mfma_f32_16x16x32_bf16 v[54:57], v[10:13], v[26:29], v[66:69]
	v_mfma_f32_16x16x32_bf16 v[66:69], v[18:21], v[26:29], v[70:73]
	v_mfma_f32_16x16x32_bf16 v[70:73], v[10:13], v[110:113], v[74:77]
	v_mfma_f32_16x16x32_bf16 v[74:77], v[18:21], v[110:113], v[78:81]
	v_mfma_f32_16x16x32_bf16 v[78:81], v[10:13], v[126:129], v[82:85]
	v_mfma_f32_16x16x32_bf16 v[82:85], v[18:21], v[126:129], v[86:89]
	v_mfma_f32_16x16x32_bf16 v[86:89], v[10:13], v[224:227], v[90:93]
	v_mfma_f32_16x16x32_bf16 v[94:97], v[18:21], v[224:227], v[94:97]
	v_mfma_f32_16x16x32_bf16 v[122:125], v[192:195], v[62:65], v[54:57]
	v_mfma_f32_16x16x32_bf16 v[114:117], v[196:199], v[62:65], v[66:69]
	v_mfma_f32_16x16x32_bf16 v[106:109], v[192:195], v[216:219], v[70:73]
	v_mfma_f32_16x16x32_bf16 v[98:101], v[196:199], v[216:219], v[74:77]
	v_mfma_f32_16x16x32_bf16 v[90:93], v[192:195], v[220:223], v[78:81]
	v_mfma_f32_16x16x32_bf16 v[82:85], v[196:199], v[220:223], v[82:85]
	v_mfma_f32_16x16x32_bf16 v[74:77], v[192:195], v[228:231], v[86:89]
	v_mfma_f32_16x16x32_bf16 v[54:57], v[196:199], v[228:231], v[94:97]
	v_mfma_f32_16x16x32_bf16 v[66:69], v[200:203], v[26:29], v[118:121]
	v_mfma_f32_16x16x32_bf16 v[26:29], v[208:211], v[26:29], v[34:37]
	v_mfma_f32_16x16x32_bf16 v[34:37], v[200:203], v[110:113], v[38:41]
	v_mfma_f32_16x16x32_bf16 v[38:41], v[208:211], v[110:113], v[42:45]
	v_mfma_f32_16x16x32_bf16 v[42:45], v[200:203], v[126:129], v[46:49]
	v_mfma_f32_16x16x32_bf16 v[46:49], v[208:211], v[126:129], v[50:53]
	v_mfma_f32_16x16x32_bf16 v[50:53], v[200:203], v[224:227], v[102:105]
	v_mfma_f32_16x16x32_bf16 v[58:61], v[208:211], v[224:227], v[58:61]
	v_mfma_f32_16x16x32_bf16 v[126:129], v[204:207], v[62:65], v[66:69]
	v_mfma_f32_16x16x32_bf16 v[118:121], v[212:215], v[62:65], v[26:29]
	v_mfma_f32_16x16x32_bf16 v[110:113], v[204:207], v[216:219], v[34:37]
	v_mfma_f32_16x16x32_bf16 v[102:105], v[212:215], v[216:219], v[38:41]
	v_mfma_f32_16x16x32_bf16 v[94:97], v[204:207], v[220:223], v[42:45]
	v_mfma_f32_16x16x32_bf16 v[86:89], v[212:215], v[220:223], v[46:49]
	v_mfma_f32_16x16x32_bf16 v[78:81], v[204:207], v[228:231], v[50:53]
	v_mfma_f32_16x16x32_bf16 v[62:65], v[212:215], v[228:231], v[58:61]
	s_barrier
	s_add_i32 s11, s11, s62
	s_add_i32 s84, s11, 0x2000
	s_mov_b32 m0, s11
	s_add_u32 s22, s38, 0x40180
	ds_read_b128 v[38:41], v143 offset:49152
	ds_read_b128 v[46:49], v143 offset:50176
	ds_read_b128 v[58:61], v143 offset:51200
	ds_read_b128 v[216:219], v143 offset:52224
	ds_read_b128 v[70:73], v143 offset:53248
	ds_read_b128 v[220:223], v143 offset:54272
	ds_read_b128 v[224:227], v143 offset:55296
	ds_read_b128 v[228:231], v143 offset:56320
	s_addc_u32 s23, s39, 0
	global_load_lds_dwordx4 v234, s[48:49]
	s_mov_b32 m0, s84
	s_add_i32 s8, s24, s62
	global_load_lds_dwordx4 v235, s[48:49]
	s_mov_b32 m0, s8
	s_add_i32 s9, s8, 0x2000
	s_nop 0
	global_load_lds_dwordx4 v234, s[22:23]
	s_mov_b32 m0, s9
	s_nop 0
	global_load_lds_dwordx4 v235, s[22:23]
	s_mov_b32 m0, s69
	s_nop 0
	global_load_lds_dwordx4 v232, s[44:45]
	s_mov_b32 m0, s70
	s_nop 0
	global_load_lds_dwordx4 v233, s[44:45]
	s_waitcnt vmcnt(8)
	s_waitcnt lgkmcnt(0)
	s_barrier
	s_waitcnt lgkmcnt(0)
	v_mfma_f32_16x16x32_bf16 v[26:29], v[10:13], v[38:41], v[168:171]
	v_mfma_f32_16x16x32_bf16 v[34:37], v[18:21], v[38:41], v[146:149]
	v_mfma_f32_16x16x32_bf16 v[42:45], v[10:13], v[58:61], v[150:153]
	v_mfma_f32_16x16x32_bf16 v[146:149], v[18:21], v[58:61], v[154:157]
	v_mfma_f32_16x16x32_bf16 v[150:153], v[10:13], v[70:73], v[158:161]
	v_mfma_f32_16x16x32_bf16 v[154:157], v[18:21], v[70:73], v[162:165]
	v_mfma_f32_16x16x32_bf16 v[2:5], v[10:13], v[224:227], v[2:5]
	v_mfma_f32_16x16x32_bf16 v[6:9], v[18:21], v[224:227], v[6:9]
	v_mfma_f32_16x16x32_bf16 v[66:69], v[192:195], v[46:49], v[26:29]
	v_mfma_f32_16x16x32_bf16 v[50:53], v[196:199], v[46:49], v[34:37]
	v_mfma_f32_16x16x32_bf16 v[42:45], v[192:195], v[216:219], v[42:45]
	v_mfma_f32_16x16x32_bf16 v[34:37], v[196:199], v[216:219], v[146:149]
	v_mfma_f32_16x16x32_bf16 v[26:29], v[192:195], v[220:223], v[150:153]
	v_mfma_f32_16x16x32_bf16 v[18:21], v[196:199], v[220:223], v[154:157]
	v_mfma_f32_16x16x32_bf16 v[10:13], v[192:195], v[228:231], v[2:5]
	v_mfma_f32_16x16x32_bf16 v[2:5], v[196:199], v[228:231], v[6:9]
	v_mfma_f32_16x16x32_bf16 v[6:9], v[200:203], v[38:41], v[176:179]
	v_mfma_f32_16x16x32_bf16 v[14:17], v[208:211], v[38:41], v[14:17]
	v_mfma_f32_16x16x32_bf16 v[38:41], v[200:203], v[58:61], v[180:183]
	v_mfma_f32_16x16x32_bf16 v[146:149], v[208:211], v[58:61], v[184:187]
	v_mfma_f32_16x16x32_bf16 v[150:153], v[200:203], v[70:73], v[172:175]
	v_mfma_f32_16x16x32_bf16 v[154:157], v[208:211], v[70:73], v[188:191]
	v_mfma_f32_16x16x32_bf16 v[158:161], v[200:203], v[224:227], v[22:25]
	v_mfma_f32_16x16x32_bf16 v[162:165], v[208:211], v[224:227], v[30:33]
	v_mfma_f32_16x16x32_bf16 v[70:73], v[204:207], v[46:49], v[6:9]
	v_mfma_f32_16x16x32_bf16 v[58:61], v[212:215], v[46:49], v[14:17]
	v_mfma_f32_16x16x32_bf16 v[46:49], v[204:207], v[216:219], v[38:41]
	v_mfma_f32_16x16x32_bf16 v[38:41], v[212:215], v[216:219], v[146:149]
	v_mfma_f32_16x16x32_bf16 v[30:33], v[204:207], v[220:223], v[150:153]
	v_mfma_f32_16x16x32_bf16 v[22:25], v[212:215], v[220:223], v[154:157]
	v_mfma_f32_16x16x32_bf16 v[14:17], v[204:207], v[228:231], v[158:161]
	v_mfma_f32_16x16x32_bf16 v[6:9], v[212:215], v[228:231], v[162:165]
	s_barrier
	s_add_u32 s78, s38, 0x200
	s_addc_u32 s85, s39, 0
	s_mov_b32 s22, 0
.LBB0_619:
	ds_read_b128 v[146:149], v141
	ds_read_b128 v[150:153], v141 offset:1024
	ds_read_b128 v[154:157], v141 offset:2048
	ds_read_b128 v[158:161], v141 offset:3072
	ds_read_b128 v[162:165], v142
	ds_read_b128 v[166:169], v142 offset:1024
	ds_read_b128 v[170:173], v142 offset:2048
	ds_read_b128 v[174:177], v142 offset:3072
	s_add_u32 s38, s40, 0x100
	s_addc_u32 s39, s41, 0
	s_cmp_eq_u32 s22, 12
	s_cselect_b32 s48, s76, s38
	s_cselect_b32 s49, s21, s39
	s_cselect_b32 s44, s77, s78
	s_cselect_b32 s45, s19, s85
	s_add_u32 s42, s48, 0x80
	s_addc_u32 s43, s49, 0
	s_add_u32 s24, s40, 0x40080
	s_mov_b32 m0, s80
	s_addc_u32 s25, s41, 0
	v_mov_b32_e32 v210, v134
	ds_read_b128 v[178:181], v143
	ds_read_b128 v[182:185], v143 offset:1024
	ds_read_b128 v[186:189], v143 offset:2048
	ds_read_b128 v[190:193], v143 offset:3072
	ds_read_b128 v[194:197], v143 offset:4096
	ds_read_b128 v[198:201], v143 offset:5120
	ds_read_b128 v[202:205], v143 offset:6144
	ds_read_b128 v[206:209], v143 offset:7168
	v_mov_b32_e32 v211, v136
	global_load_lds_dwordx4 v210, s[24:25]
	s_mov_b32 m0, s81
	s_add_u32 s40, s44, 0x80
	global_load_lds_dwordx4 v211, s[24:25]
	s_waitcnt vmcnt(8)
	s_waitcnt lgkmcnt(0)
	s_addc_u32 s41, s45, 0
	s_barrier
	s_waitcnt lgkmcnt(0)
	v_mfma_f32_16x16x32_bf16 v[122:125], v[146:149], v[178:181], v[122:125]
	v_mfma_f32_16x16x32_bf16 v[114:117], v[154:157], v[178:181], v[114:117]
	v_mfma_f32_16x16x32_bf16 v[106:109], v[146:149], v[186:189], v[106:109]
	v_mfma_f32_16x16x32_bf16 v[98:101], v[154:157], v[186:189], v[98:101]
	v_mfma_f32_16x16x32_bf16 v[90:93], v[146:149], v[194:197], v[90:93]
	v_mfma_f32_16x16x32_bf16 v[82:85], v[154:157], v[194:197], v[82:85]
	v_mfma_f32_16x16x32_bf16 v[74:77], v[146:149], v[202:205], v[74:77]
	v_mfma_f32_16x16x32_bf16 v[54:57], v[154:157], v[202:205], v[54:57]
	v_mfma_f32_16x16x32_bf16 v[122:125], v[150:153], v[182:185], v[122:125]
	v_mfma_f32_16x16x32_bf16 v[114:117], v[158:161], v[182:185], v[114:117]
	v_mfma_f32_16x16x32_bf16 v[106:109], v[150:153], v[190:193], v[106:109]
	v_mfma_f32_16x16x32_bf16 v[98:101], v[158:161], v[190:193], v[98:101]
	v_mfma_f32_16x16x32_bf16 v[90:93], v[150:153], v[198:201], v[90:93]
	v_mfma_f32_16x16x32_bf16 v[82:85], v[158:161], v[198:201], v[82:85]
	v_mfma_f32_16x16x32_bf16 v[74:77], v[150:153], v[206:209], v[74:77]
	v_mfma_f32_16x16x32_bf16 v[54:57], v[158:161], v[206:209], v[54:57]
	v_mfma_f32_16x16x32_bf16 v[126:129], v[162:165], v[178:181], v[126:129]
	v_mfma_f32_16x16x32_bf16 v[118:121], v[170:173], v[178:181], v[118:121]
	v_mfma_f32_16x16x32_bf16 v[110:113], v[162:165], v[186:189], v[110:113]
	v_mfma_f32_16x16x32_bf16 v[102:105], v[170:173], v[186:189], v[102:105]
	v_mfma_f32_16x16x32_bf16 v[94:97], v[162:165], v[194:197], v[94:97]
	v_mfma_f32_16x16x32_bf16 v[86:89], v[170:173], v[194:197], v[86:89]
	v_mfma_f32_16x16x32_bf16 v[78:81], v[162:165], v[202:205], v[78:81]
	v_mfma_f32_16x16x32_bf16 v[62:65], v[170:173], v[202:205], v[62:65]
	v_mfma_f32_16x16x32_bf16 v[126:129], v[166:169], v[182:185], v[126:129]
	v_mfma_f32_16x16x32_bf16 v[118:121], v[174:177], v[182:185], v[118:121]
	v_mfma_f32_16x16x32_bf16 v[110:113], v[166:169], v[190:193], v[110:113]
	v_mfma_f32_16x16x32_bf16 v[102:105], v[174:177], v[190:193], v[102:105]
	v_mfma_f32_16x16x32_bf16 v[94:97], v[166:169], v[198:201], v[94:97]
	v_mfma_f32_16x16x32_bf16 v[86:89], v[174:177], v[198:201], v[86:89]
	v_mfma_f32_16x16x32_bf16 v[78:81], v[166:169], v[206:209], v[78:81]
	v_mfma_f32_16x16x32_bf16 v[62:65], v[174:177], v[206:209], v[62:65]
	s_barrier
	s_mov_b32 m0, s82
	s_mov_b64 s[24:25], s[44:45]
	v_mov_b32_e32 v212, v135
	ds_read_b128 v[178:181], v143 offset:16384
	ds_read_b128 v[182:185], v143 offset:17408
	ds_read_b128 v[186:189], v143 offset:18432
	ds_read_b128 v[190:193], v143 offset:19456
	ds_read_b128 v[194:197], v143 offset:20480
	ds_read_b128 v[198:201], v143 offset:21504
	ds_read_b128 v[202:205], v143 offset:22528
	ds_read_b128 v[206:209], v143 offset:23552
	v_mov_b32_e32 v213, v137
	global_load_lds_dwordx4 v212, s[24:25]
	s_mov_b32 m0, s83
	s_nop 0
	global_load_lds_dwordx4 v213, s[24:25]
	s_add_u32 s24, s44, 0x40000
	s_addc_u32 s25, s45, 0
	s_mov_b32 m0, s34
	s_nop 0
	global_load_lds_dwordx4 v212, s[24:25]
	s_mov_b32 m0, s35
	s_nop 0
	global_load_lds_dwordx4 v213, s[24:25]
	s_mov_b64 s[24:25], s[48:49]
	s_mov_b32 m0, s31
	s_nop 0
	global_load_lds_dwordx4 v210, s[24:25]
	s_mov_b32 m0, s65
	s_nop 0
	global_load_lds_dwordx4 v211, s[24:25]
	s_waitcnt vmcnt(8)
	s_waitcnt lgkmcnt(0)
	s_barrier
	s_waitcnt lgkmcnt(0)
	v_mfma_f32_16x16x32_bf16 v[66:69], v[146:149], v[178:181], v[66:69]
	v_mfma_f32_16x16x32_bf16 v[50:53], v[154:157], v[178:181], v[50:53]
	v_mfma_f32_16x16x32_bf16 v[42:45], v[146:149], v[186:189], v[42:45]
	v_mfma_f32_16x16x32_bf16 v[34:37], v[154:157], v[186:189], v[34:37]
	v_mfma_f32_16x16x32_bf16 v[26:29], v[146:149], v[194:197], v[26:29]
	v_mfma_f32_16x16x32_bf16 v[18:21], v[154:157], v[194:197], v[18:21]
	v_mfma_f32_16x16x32_bf16 v[10:13], v[146:149], v[202:205], v[10:13]
	v_mfma_f32_16x16x32_bf16 v[2:5], v[154:157], v[202:205], v[2:5]
	v_mfma_f32_16x16x32_bf16 v[66:69], v[150:153], v[182:185], v[66:69]
	v_mfma_f32_16x16x32_bf16 v[50:53], v[158:161], v[182:185], v[50:53]
	v_mfma_f32_16x16x32_bf16 v[42:45], v[150:153], v[190:193], v[42:45]
	v_mfma_f32_16x16x32_bf16 v[34:37], v[158:161], v[190:193], v[34:37]
	v_mfma_f32_16x16x32_bf16 v[26:29], v[150:153], v[198:201], v[26:29]
	v_mfma_f32_16x16x32_bf16 v[18:21], v[158:161], v[198:201], v[18:21]
	v_mfma_f32_16x16x32_bf16 v[10:13], v[150:153], v[206:209], v[10:13]
	v_mfma_f32_16x16x32_bf16 v[2:5], v[158:161], v[206:209], v[2:5]
	v_mfma_f32_16x16x32_bf16 v[70:73], v[162:165], v[178:181], v[70:73]
	v_mfma_f32_16x16x32_bf16 v[58:61], v[170:173], v[178:181], v[58:61]
	v_mfma_f32_16x16x32_bf16 v[46:49], v[162:165], v[186:189], v[46:49]
	v_mfma_f32_16x16x32_bf16 v[38:41], v[170:173], v[186:189], v[38:41]
	v_mfma_f32_16x16x32_bf16 v[30:33], v[162:165], v[194:197], v[30:33]
	v_mfma_f32_16x16x32_bf16 v[22:25], v[170:173], v[194:197], v[22:25]
	v_mfma_f32_16x16x32_bf16 v[14:17], v[162:165], v[202:205], v[14:17]
	v_mfma_f32_16x16x32_bf16 v[6:9], v[170:173], v[202:205], v[6:9]
	v_mfma_f32_16x16x32_bf16 v[70:73], v[166:169], v[182:185], v[70:73]
	v_mfma_f32_16x16x32_bf16 v[58:61], v[174:177], v[182:185], v[58:61]
	v_mfma_f32_16x16x32_bf16 v[46:49], v[166:169], v[190:193], v[46:49]
	v_mfma_f32_16x16x32_bf16 v[38:41], v[174:177], v[190:193], v[38:41]
	v_mfma_f32_16x16x32_bf16 v[30:33], v[166:169], v[198:201], v[30:33]
	v_mfma_f32_16x16x32_bf16 v[22:25], v[174:177], v[198:201], v[22:25]
	v_mfma_f32_16x16x32_bf16 v[14:17], v[166:169], v[206:209], v[14:17]
	v_mfma_f32_16x16x32_bf16 v[6:9], v[174:177], v[206:209], v[6:9]
	s_barrier
	ds_read_b128 v[146:149], v144
	ds_read_b128 v[150:153], v144 offset:1024
	ds_read_b128 v[154:157], v144 offset:2048
	ds_read_b128 v[158:161], v144 offset:3072
	ds_read_b128 v[162:165], v145
	ds_read_b128 v[166:169], v145 offset:1024
	ds_read_b128 v[170:173], v145 offset:2048
	ds_read_b128 v[174:177], v145 offset:3072
	s_add_u32 s24, s48, 0x40000
	s_addc_u32 s25, s49, 0
	s_mov_b32 m0, s66
	ds_read_b128 v[178:181], v143 offset:32768
	ds_read_b128 v[182:185], v143 offset:33792
	ds_read_b128 v[186:189], v143 offset:34816
	ds_read_b128 v[190:193], v143 offset:35840
	ds_read_b128 v[194:197], v143 offset:36864
	ds_read_b128 v[198:201], v143 offset:37888
	ds_read_b128 v[202:205], v143 offset:38912
	ds_read_b128 v[206:209], v143 offset:39936
	s_nop 0
	global_load_lds_dwordx4 v210, s[24:25]
	s_mov_b32 m0, s67
	s_nop 0
	global_load_lds_dwordx4 v211, s[24:25]
	s_waitcnt vmcnt(8)
	s_waitcnt lgkmcnt(0)
	s_barrier
	s_waitcnt lgkmcnt(0)
	v_mfma_f32_16x16x32_bf16 v[122:125], v[146:149], v[178:181], v[122:125]
	v_mfma_f32_16x16x32_bf16 v[114:117], v[154:157], v[178:181], v[114:117]
	v_mfma_f32_16x16x32_bf16 v[106:109], v[146:149], v[186:189], v[106:109]
	v_mfma_f32_16x16x32_bf16 v[98:101], v[154:157], v[186:189], v[98:101]
	v_mfma_f32_16x16x32_bf16 v[90:93], v[146:149], v[194:197], v[90:93]
	v_mfma_f32_16x16x32_bf16 v[82:85], v[154:157], v[194:197], v[82:85]
	v_mfma_f32_16x16x32_bf16 v[74:77], v[146:149], v[202:205], v[74:77]
	v_mfma_f32_16x16x32_bf16 v[54:57], v[154:157], v[202:205], v[54:57]
	v_mfma_f32_16x16x32_bf16 v[122:125], v[150:153], v[182:185], v[122:125]
	v_mfma_f32_16x16x32_bf16 v[114:117], v[158:161], v[182:185], v[114:117]
	v_mfma_f32_16x16x32_bf16 v[106:109], v[150:153], v[190:193], v[106:109]
	v_mfma_f32_16x16x32_bf16 v[98:101], v[158:161], v[190:193], v[98:101]
	v_mfma_f32_16x16x32_bf16 v[90:93], v[150:153], v[198:201], v[90:93]
	v_mfma_f32_16x16x32_bf16 v[82:85], v[158:161], v[198:201], v[82:85]
	v_mfma_f32_16x16x32_bf16 v[74:77], v[150:153], v[206:209], v[74:77]
	v_mfma_f32_16x16x32_bf16 v[54:57], v[158:161], v[206:209], v[54:57]
	v_mfma_f32_16x16x32_bf16 v[126:129], v[162:165], v[178:181], v[126:129]
	v_mfma_f32_16x16x32_bf16 v[118:121], v[170:173], v[178:181], v[118:121]
	v_mfma_f32_16x16x32_bf16 v[110:113], v[162:165], v[186:189], v[110:113]
	v_mfma_f32_16x16x32_bf16 v[102:105], v[170:173], v[186:189], v[102:105]
	v_mfma_f32_16x16x32_bf16 v[94:97], v[162:165], v[194:197], v[94:97]
	v_mfma_f32_16x16x32_bf16 v[86:89], v[170:173], v[194:197], v[86:89]
	v_mfma_f32_16x16x32_bf16 v[78:81], v[162:165], v[202:205], v[78:81]
	v_mfma_f32_16x16x32_bf16 v[62:65], v[170:173], v[202:205], v[62:65]
	v_mfma_f32_16x16x32_bf16 v[126:129], v[166:169], v[182:185], v[126:129]
	v_mfma_f32_16x16x32_bf16 v[118:121], v[174:177], v[182:185], v[118:121]
	v_mfma_f32_16x16x32_bf16 v[110:113], v[166:169], v[190:193], v[110:113]
	v_mfma_f32_16x16x32_bf16 v[102:105], v[174:177], v[190:193], v[102:105]
	v_mfma_f32_16x16x32_bf16 v[94:97], v[166:169], v[198:201], v[94:97]
	v_mfma_f32_16x16x32_bf16 v[86:89], v[174:177], v[198:201], v[86:89]
	v_mfma_f32_16x16x32_bf16 v[78:81], v[166:169], v[206:209], v[78:81]
	v_mfma_f32_16x16x32_bf16 v[62:65], v[174:177], v[206:209], v[62:65]
	s_barrier
	s_mov_b32 m0, s11
	ds_read_b128 v[178:181], v143 offset:49152
	ds_read_b128 v[182:185], v143 offset:50176
	ds_read_b128 v[186:189], v143 offset:51200
	ds_read_b128 v[190:193], v143 offset:52224
	ds_read_b128 v[194:197], v143 offset:53248
	ds_read_b128 v[198:201], v143 offset:54272
	ds_read_b128 v[202:205], v143 offset:55296
	ds_read_b128 v[206:209], v143 offset:56320
	s_add_u32 s24, s44, 0x40080
	global_load_lds_dwordx4 v212, s[40:41]
	s_mov_b32 m0, s84
	s_addc_u32 s25, s45, 0
	global_load_lds_dwordx4 v213, s[40:41]
	s_mov_b32 m0, s8
	s_nop 0
	global_load_lds_dwordx4 v212, s[24:25]
	s_mov_b32 m0, s9
	s_nop 0
	global_load_lds_dwordx4 v213, s[24:25]
	s_mov_b32 m0, s69
	s_nop 0
	global_load_lds_dwordx4 v210, s[42:43]
	s_mov_b32 m0, s70
	s_nop 0
	global_load_lds_dwordx4 v211, s[42:43]
	s_waitcnt vmcnt(8)
	s_waitcnt lgkmcnt(0)
	s_barrier
	s_waitcnt lgkmcnt(0)
	v_mfma_f32_16x16x32_bf16 v[66:69], v[146:149], v[178:181], v[66:69]
	v_mfma_f32_16x16x32_bf16 v[50:53], v[154:157], v[178:181], v[50:53]
	v_mfma_f32_16x16x32_bf16 v[42:45], v[146:149], v[186:189], v[42:45]
	v_mfma_f32_16x16x32_bf16 v[34:37], v[154:157], v[186:189], v[34:37]
	v_mfma_f32_16x16x32_bf16 v[26:29], v[146:149], v[194:197], v[26:29]
	v_mfma_f32_16x16x32_bf16 v[18:21], v[154:157], v[194:197], v[18:21]
	v_mfma_f32_16x16x32_bf16 v[10:13], v[146:149], v[202:205], v[10:13]
	v_mfma_f32_16x16x32_bf16 v[2:5], v[154:157], v[202:205], v[2:5]
	v_mfma_f32_16x16x32_bf16 v[66:69], v[150:153], v[182:185], v[66:69]
	v_mfma_f32_16x16x32_bf16 v[50:53], v[158:161], v[182:185], v[50:53]
	v_mfma_f32_16x16x32_bf16 v[42:45], v[150:153], v[190:193], v[42:45]
	v_mfma_f32_16x16x32_bf16 v[34:37], v[158:161], v[190:193], v[34:37]
	v_mfma_f32_16x16x32_bf16 v[26:29], v[150:153], v[198:201], v[26:29]
	v_mfma_f32_16x16x32_bf16 v[18:21], v[158:161], v[198:201], v[18:21]
	v_mfma_f32_16x16x32_bf16 v[10:13], v[150:153], v[206:209], v[10:13]
	v_mfma_f32_16x16x32_bf16 v[2:5], v[158:161], v[206:209], v[2:5]
	v_mfma_f32_16x16x32_bf16 v[70:73], v[162:165], v[178:181], v[70:73]
	v_mfma_f32_16x16x32_bf16 v[58:61], v[170:173], v[178:181], v[58:61]
	v_mfma_f32_16x16x32_bf16 v[46:49], v[162:165], v[186:189], v[46:49]
	v_mfma_f32_16x16x32_bf16 v[38:41], v[170:173], v[186:189], v[38:41]
	v_mfma_f32_16x16x32_bf16 v[30:33], v[162:165], v[194:197], v[30:33]
	v_mfma_f32_16x16x32_bf16 v[22:25], v[170:173], v[194:197], v[22:25]
	v_mfma_f32_16x16x32_bf16 v[14:17], v[162:165], v[202:205], v[14:17]
	v_mfma_f32_16x16x32_bf16 v[6:9], v[170:173], v[202:205], v[6:9]
	v_mfma_f32_16x16x32_bf16 v[70:73], v[166:169], v[182:185], v[70:73]
	v_mfma_f32_16x16x32_bf16 v[58:61], v[174:177], v[182:185], v[58:61]
	v_mfma_f32_16x16x32_bf16 v[46:49], v[166:169], v[190:193], v[46:49]
	v_mfma_f32_16x16x32_bf16 v[38:41], v[174:177], v[190:193], v[38:41]
	v_mfma_f32_16x16x32_bf16 v[30:33], v[166:169], v[198:201], v[30:33]
	v_mfma_f32_16x16x32_bf16 v[22:25], v[174:177], v[198:201], v[22:25]
	v_mfma_f32_16x16x32_bf16 v[14:17], v[166:169], v[206:209], v[14:17]
	v_mfma_f32_16x16x32_bf16 v[6:9], v[174:177], v[206:209], v[6:9]
	s_barrier
	s_add_i32 s22, s22, 2
	s_add_u32 s78, s78, 0x100
	s_addc_u32 s85, s85, 0
	s_cmp_gt_u32 s22, 13
	s_mov_b64 s[40:41], s[38:39]
	s_cbranch_scc0 .LBB0_619
	s_and_b64 vcc, exec, s[12:13]
	s_cbranch_vccz .LBB0_622
	s_barrier

.LBB0_708:
	s_add_u32 s8, s14, s18
	s_addc_u32 s9, s15, s19
	s_add_u32 s20, s8, 0x100
	v_add_u32_e32 v146, s47, v136
	s_addc_u32 s21, s9, 0
	ds_read_b128 v[138:141], v146
	ds_read_b128 v[142:145], v146 offset:1024
	ds_read_b128 v[152:155], v146 offset:2048
	ds_read_b128 v[156:159], v146 offset:3072
	v_add_u32_e32 v146, s48, v136
	s_add_u32 s22, s0, s18
	ds_read_b128 v[160:163], v146
	ds_read_b128 v[164:167], v146 offset:1024
	ds_read_b128 v[168:171], v146 offset:2048
	ds_read_b128 v[172:175], v146 offset:3072
	s_addc_u32 s23, s1, s19
	s_add_u32 s22, s22, 0x100
	s_addc_u32 s23, s23, 0
	s_cmp_eq_u32 s52, 18
	s_cselect_b32 s24, s6, s20
	s_cselect_b32 s25, s7, s21
	s_cselect_b32 s22, s16, s22
	s_cselect_b32 s23, s17, s23
	s_add_u32 s20, s24, 0x80
	s_addc_u32 s21, s25, 0
	s_add_u32 s8, s8, 0x58080
	s_addc_u32 s9, s9, 0
	v_mov_b32_e32 v252, v134
	s_add_i32 m0, s39, 0xc000
	ds_read_b128 v[176:179], v137
	ds_read_b128 v[180:183], v137 offset:1024
	ds_read_b128 v[184:187], v137 offset:2048
	ds_read_b128 v[188:191], v137 offset:3072
	ds_read_b128 v[192:195], v137 offset:4096
	ds_read_b128 v[196:199], v137 offset:5120
	ds_read_b128 v[200:203], v137 offset:6144
	ds_read_b128 v[204:207], v137 offset:7168
	v_mov_b32_e32 v253, v135
	global_load_lds_dwordx4 v252, s[8:9]
	s_add_i32 m0, s39, 0xe000
	s_nop 0
	global_load_lds_dwordx4 v253, s[8:9]
	s_waitcnt vmcnt(8)
	s_waitcnt lgkmcnt(0)
	s_barrier
	s_waitcnt lgkmcnt(0)
	v_mfma_f32_16x16x128_f8f6f4 v[126:129], v[138:145], v[176:183], v[126:129]
	v_mfma_f32_16x16x128_f8f6f4 v[122:125], v[152:159], v[176:183], v[122:125]
	v_mfma_f32_16x16x128_f8f6f4 v[118:121], v[138:145], v[184:191], v[118:121]
	v_mfma_f32_16x16x128_f8f6f4 v[114:117], v[152:159], v[184:191], v[114:117]
	v_mfma_f32_16x16x128_f8f6f4 v[146:149], v[138:145], v[192:199], v[94:97]
	v_mfma_f32_16x16x128_f8f6f4 v[208:211], v[152:159], v[192:199], v[90:93]
	v_mfma_f32_16x16x128_f8f6f4 v[212:215], v[138:145], v[200:207], v[86:89]
	v_mfma_f32_16x16x128_f8f6f4 v[216:219], v[152:159], v[200:207], v[82:85]
	v_mfma_f32_16x16x128_f8f6f4 v[110:113], v[160:167], v[176:183], v[110:113]
	v_mfma_f32_16x16x128_f8f6f4 v[102:105], v[168:175], v[176:183], v[102:105]
	v_mfma_f32_16x16x128_f8f6f4 v[106:109], v[160:167], v[184:191], v[106:109]
	v_mfma_f32_16x16x128_f8f6f4 v[98:101], v[168:175], v[184:191], v[98:101]
	v_mfma_f32_16x16x128_f8f6f4 v[176:179], v[160:167], v[192:199], v[78:81]
	v_mfma_f32_16x16x128_f8f6f4 v[180:183], v[168:175], v[192:199], v[70:73]
	v_mfma_f32_16x16x128_f8f6f4 v[184:187], v[160:167], v[200:207], v[74:77]
	v_mfma_f32_16x16x128_f8f6f4 v[188:191], v[168:175], v[200:207], v[66:69]
	s_barrier
	s_add_i32 s34, s47, s38
	s_mov_b64 s[8:9], s[22:23]
	s_mov_b32 m0, s34
	s_nop 1
	ds_read_b128 v[66:69], v137 offset:16384
	ds_read_b128 v[70:73], v137 offset:17408
	ds_read_b128 v[74:77], v137 offset:18432
	ds_read_b128 v[78:81], v137 offset:19456
	ds_read_b128 v[82:85], v137 offset:20480
	ds_read_b128 v[86:89], v137 offset:21504
	ds_read_b128 v[90:93], v137 offset:22528
	ds_read_b128 v[94:97], v137 offset:23552
	s_nop 0
	global_load_lds_dwordx4 v252, s[8:9]
	s_add_i32 m0, s34, 0x2000
	s_nop 0
	global_load_lds_dwordx4 v253, s[8:9]
	s_add_u32 s8, s22, 0x58000
	s_addc_u32 s9, s23, 0
	s_add_i32 s34, s48, s38
	s_mov_b32 m0, s34
	s_nop 0
	global_load_lds_dwordx4 v252, s[8:9]
	s_add_i32 m0, s34, 0x2000
	s_nop 0
	global_load_lds_dwordx4 v253, s[8:9]
	s_mov_b64 s[8:9], s[24:25]
	s_mov_b32 m0, s39
	s_nop 0
	global_load_lds_dwordx4 v252, s[8:9]
	s_mov_b32 m0, s40
	s_nop 0
	global_load_lds_dwordx4 v253, s[8:9]
	s_waitcnt vmcnt(8)
	s_waitcnt lgkmcnt(0)
	s_barrier
	s_waitcnt lgkmcnt(0)
	v_mfma_f32_16x16x128_f8f6f4 v[62:65], v[138:145], v[66:73], v[62:65]
	v_mfma_f32_16x16x128_f8f6f4 v[58:61], v[152:159], v[66:73], v[58:61]
	v_mfma_f32_16x16x128_f8f6f4 v[54:57], v[138:145], v[74:81], v[54:57]
	v_mfma_f32_16x16x128_f8f6f4 v[50:53], v[152:159], v[74:81], v[50:53]
	v_mfma_f32_16x16x128_f8f6f4 v[192:195], v[138:145], v[82:89], v[30:33]
	v_mfma_f32_16x16x128_f8f6f4 v[196:199], v[152:159], v[82:89], v[26:29]
	v_mfma_f32_16x16x128_f8f6f4 v[200:203], v[138:145], v[90:97], v[22:25]
	v_mfma_f32_16x16x128_f8f6f4 v[204:207], v[152:159], v[90:97], v[18:21]
	v_mfma_f32_16x16x128_f8f6f4 v[220:223], v[160:167], v[66:73], v[46:49]
	v_mfma_f32_16x16x128_f8f6f4 v[224:227], v[168:175], v[66:73], v[38:41]
	v_mfma_f32_16x16x128_f8f6f4 v[228:231], v[160:167], v[74:81], v[42:45]
	v_mfma_f32_16x16x128_f8f6f4 v[232:235], v[168:175], v[74:81], v[34:37]
	v_mfma_f32_16x16x128_f8f6f4 v[236:239], v[160:167], v[82:89], v[14:17]
	v_mfma_f32_16x16x128_f8f6f4 v[240:243], v[168:175], v[82:89], v[6:9]
	v_mfma_f32_16x16x128_f8f6f4 v[244:247], v[160:167], v[90:97], v[10:13]
	v_mfma_f32_16x16x128_f8f6f4 v[248:251], v[168:175], v[90:97], v[2:5]
	s_barrier
	s_add_i32 s34, 0, 0x18000
	s_add_i32 s35, 0, 0x1c000
	v_add_u32_e32 v14, s34, v136
	v_add_u32_e32 v18, s35, v136
	s_nop 0
	ds_read_b128 v[2:5], v14
	ds_read_b128 v[6:9], v14 offset:1024
	ds_read_b128 v[10:13], v14 offset:2048
	ds_read_b128 v[14:17], v14 offset:3072
	ds_read_b128 v[138:141], v18
	ds_read_b128 v[142:145], v18 offset:1024
	ds_read_b128 v[152:155], v18 offset:2048
	ds_read_b128 v[156:159], v18 offset:3072
	s_add_u32 s8, s24, 0x58000
	s_addc_u32 s9, s25, 0
	s_mov_b32 m0, s41
	ds_read_b128 v[18:21], v137 offset:32768
	ds_read_b128 v[22:25], v137 offset:33792
	ds_read_b128 v[26:29], v137 offset:34816
	ds_read_b128 v[30:33], v137 offset:35840
	ds_read_b128 v[34:37], v137 offset:36864
	ds_read_b128 v[38:41], v137 offset:37888
	ds_read_b128 v[42:45], v137 offset:38912
	ds_read_b128 v[46:49], v137 offset:39936
	s_nop 0
	global_load_lds_dwordx4 v252, s[8:9]
	s_mov_b32 m0, s43
	s_nop 0
	global_load_lds_dwordx4 v253, s[8:9]
	s_waitcnt vmcnt(8)
	s_waitcnt lgkmcnt(0)
	s_barrier
	s_waitcnt lgkmcnt(0)
	v_mfma_f32_16x16x128_f8f6f4 v[126:129], v[2:9], v[18:25], v[126:129]
	v_mfma_f32_16x16x128_f8f6f4 v[122:125], v[10:17], v[18:25], v[122:125]
	v_mfma_f32_16x16x128_f8f6f4 v[118:121], v[2:9], v[26:33], v[118:121]
	v_mfma_f32_16x16x128_f8f6f4 v[114:117], v[10:17], v[26:33], v[114:117]
	v_mfma_f32_16x16x128_f8f6f4 v[94:97], v[2:9], v[34:41], v[146:149]
	v_mfma_f32_16x16x128_f8f6f4 v[90:93], v[10:17], v[34:41], v[208:211]
	v_mfma_f32_16x16x128_f8f6f4 v[86:89], v[2:9], v[42:49], v[212:215]
	v_mfma_f32_16x16x128_f8f6f4 v[82:85], v[10:17], v[42:49], v[216:219]
	v_mfma_f32_16x16x128_f8f6f4 v[110:113], v[138:145], v[18:25], v[110:113]
	v_mfma_f32_16x16x128_f8f6f4 v[102:105], v[152:159], v[18:25], v[102:105]
	v_mfma_f32_16x16x128_f8f6f4 v[106:109], v[138:145], v[26:33], v[106:109]
	v_mfma_f32_16x16x128_f8f6f4 v[98:101], v[152:159], v[26:33], v[98:101]
	v_mfma_f32_16x16x128_f8f6f4 v[78:81], v[138:145], v[34:41], v[176:179]
	v_mfma_f32_16x16x128_f8f6f4 v[70:73], v[152:159], v[34:41], v[180:183]
	v_mfma_f32_16x16x128_f8f6f4 v[74:77], v[138:145], v[42:49], v[184:187]
	v_mfma_f32_16x16x128_f8f6f4 v[66:69], v[152:159], v[42:49], v[188:191]
	s_barrier
	s_add_u32 s8, s22, 0x80
	s_addc_u32 s9, s23, 0
	s_add_i32 s24, s34, s38
	s_mov_b32 m0, s24
	ds_read_b128 v[34:37], v137 offset:49152
	ds_read_b128 v[38:41], v137 offset:50176
	ds_read_b128 v[160:163], v137 offset:51200
	ds_read_b128 v[164:167], v137 offset:52224
	ds_read_b128 v[168:171], v137 offset:53248
	ds_read_b128 v[172:175], v137 offset:54272
	ds_read_b128 v[176:179], v137 offset:55296
	ds_read_b128 v[180:183], v137 offset:56320
	s_nop 0
	global_load_lds_dwordx4 v252, s[8:9]
	s_add_i32 m0, s24, 0x2000
	s_nop 0
	global_load_lds_dwordx4 v253, s[8:9]
	s_add_u32 s8, s22, 0x58080
	s_addc_u32 s9, s23, 0
	s_add_i32 s22, s35, s38
	s_mov_b32 m0, s22
	s_nop 0
	global_load_lds_dwordx4 v252, s[8:9]
	s_add_i32 m0, s22, 0x2000
	s_nop 0
	global_load_lds_dwordx4 v253, s[8:9]
	s_mov_b32 m0, s45
	s_nop 0
	global_load_lds_dwordx4 v252, s[20:21]
	s_mov_b32 m0, s46
	s_nop 0
	global_load_lds_dwordx4 v253, s[20:21]
	s_waitcnt vmcnt(8)
	s_waitcnt lgkmcnt(0)
	s_barrier
	s_waitcnt lgkmcnt(0)
	v_mfma_f32_16x16x128_f8f6f4 v[62:65], v[2:9], v[34:41], v[62:65]
	v_mfma_f32_16x16x128_f8f6f4 v[58:61], v[10:17], v[34:41], v[58:61]
	v_mfma_f32_16x16x128_f8f6f4 v[54:57], v[2:9], v[160:167], v[54:57]
	v_mfma_f32_16x16x128_f8f6f4 v[50:53], v[10:17], v[160:167], v[50:53]
	v_mfma_f32_16x16x128_f8f6f4 v[30:33], v[2:9], v[168:175], v[192:195]
	v_mfma_f32_16x16x128_f8f6f4 v[26:29], v[10:17], v[168:175], v[196:199]
	v_mfma_f32_16x16x128_f8f6f4 v[22:25], v[2:9], v[176:183], v[200:203]
	v_mfma_f32_16x16x128_f8f6f4 v[18:21], v[10:17], v[176:183], v[204:207]
	v_mfma_f32_16x16x128_f8f6f4 v[46:49], v[138:145], v[34:41], v[220:223]
	v_mfma_f32_16x16x128_f8f6f4 v[38:41], v[152:159], v[34:41], v[224:227]
	v_mfma_f32_16x16x128_f8f6f4 v[42:45], v[138:145], v[160:167], v[228:231]
	v_mfma_f32_16x16x128_f8f6f4 v[34:37], v[152:159], v[160:167], v[232:235]
	v_mfma_f32_16x16x128_f8f6f4 v[14:17], v[138:145], v[168:175], v[236:239]
	v_mfma_f32_16x16x128_f8f6f4 v[6:9], v[152:159], v[168:175], v[240:243]
	v_mfma_f32_16x16x128_f8f6f4 v[10:13], v[138:145], v[176:183], v[244:247]
	v_mfma_f32_16x16x128_f8f6f4 v[2:5], v[152:159], v[176:183], v[248:251]
	s_barrier
	s_add_i32 s52, s52, 2
	s_add_u32 s18, s18, 0x100
	s_addc_u32 s19, s19, 0
	s_cmp_gt_u32 s52, 19
	s_cbranch_scc0 .LBB0_708
	s_and_b64 vcc, exec, s[4:5]
	s_cbranch_vccnz .LBB0_696
	s_nop 2
	v_mov_b32_e32 v2, 0
	s_mov_b32 s12, s49
	s_mov_b32 s11, s50
	s_mov_b64 s[0:1], s[16:17]
	s_mov_b64 s[14:15], s[6:7]
	s_mov_b32 s44, s51
	v_mov_b32_e32 v3, v2
	v_mov_b32_e32 v4, v2
	v_mov_b32_e32 v5, v2
	v_mov_b32_e32 v10, v2
	v_mov_b32_e32 v11, v2
	v_mov_b32_e32 v12, v2
	v_mov_b32_e32 v13, v2
	v_mov_b32_e32 v6, v2
	v_mov_b32_e32 v7, v2
	v_mov_b32_e32 v8, v2
	v_mov_b32_e32 v9, v2
	v_mov_b32_e32 v14, v2
	v_mov_b32_e32 v15, v2
	v_mov_b32_e32 v16, v2
	v_mov_b32_e32 v17, v2
	v_mov_b32_e32 v34, v2
	v_mov_b32_e32 v35, v2
	v_mov_b32_e32 v36, v2
	v_mov_b32_e32 v37, v2
	v_mov_b32_e32 v42, v2
	v_mov_b32_e32 v43, v2
	v_mov_b32_e32 v44, v2
	v_mov_b32_e32 v45, v2
	v_mov_b32_e32 v38, v2
	v_mov_b32_e32 v39, v2
	v_mov_b32_e32 v40, v2
	v_mov_b32_e32 v41, v2
	v_mov_b32_e32 v46, v2
	v_mov_b32_e32 v47, v2
	v_mov_b32_e32 v48, v2
	v_mov_b32_e32 v49, v2
	v_mov_b32_e32 v18, v2
	v_mov_b32_e32 v19, v2
	v_mov_b32_e32 v20, v2
	v_mov_b32_e32 v21, v2
	v_mov_b32_e32 v22, v2
	v_mov_b32_e32 v23, v2
	v_mov_b32_e32 v24, v2
	v_mov_b32_e32 v25, v2
	v_mov_b32_e32 v26, v2
	v_mov_b32_e32 v27, v2
	v_mov_b32_e32 v28, v2
	v_mov_b32_e32 v29, v2
	v_mov_b32_e32 v30, v2
	v_mov_b32_e32 v31, v2
	v_mov_b32_e32 v32, v2
	v_mov_b32_e32 v33, v2
	v_mov_b32_e32 v50, v2
	v_mov_b32_e32 v51, v2
	v_mov_b32_e32 v52, v2
	v_mov_b32_e32 v53, v2
	v_mov_b32_e32 v54, v2
	v_mov_b32_e32 v55, v2
	v_mov_b32_e32 v56, v2
	v_mov_b32_e32 v57, v2
	v_mov_b32_e32 v58, v2
	v_mov_b32_e32 v59, v2
	v_mov_b32_e32 v60, v2
	v_mov_b32_e32 v61, v2
	v_mov_b32_e32 v62, v2
	v_mov_b32_e32 v63, v2
	v_mov_b32_e32 v64, v2
	v_mov_b32_e32 v65, v2
	v_mov_b32_e32 v66, v2
	v_mov_b32_e32 v67, v2
	v_mov_b32_e32 v68, v2
	v_mov_b32_e32 v69, v2
	v_mov_b32_e32 v74, v2
	v_mov_b32_e32 v75, v2
	v_mov_b32_e32 v76, v2
	v_mov_b32_e32 v77, v2
	v_mov_b32_e32 v70, v2
	v_mov_b32_e32 v71, v2
	v_mov_b32_e32 v72, v2
	v_mov_b32_e32 v73, v2
	v_mov_b32_e32 v78, v2
	v_mov_b32_e32 v79, v2
	v_mov_b32_e32 v80, v2
	v_mov_b32_e32 v81, v2
	v_mov_b32_e32 v98, v2
	v_mov_b32_e32 v99, v2
	v_mov_b32_e32 v100, v2
	v_mov_b32_e32 v101, v2
	v_mov_b32_e32 v106, v2
	v_mov_b32_e32 v107, v2
	v_mov_b32_e32 v108, v2
	v_mov_b32_e32 v109, v2
	v_mov_b32_e32 v102, v2
	v_mov_b32_e32 v103, v2
	v_mov_b32_e32 v104, v2
	v_mov_b32_e32 v105, v2
	v_mov_b32_e32 v110, v2
	v_mov_b32_e32 v111, v2
	v_mov_b32_e32 v112, v2
	v_mov_b32_e32 v113, v2
	v_mov_b32_e32 v82, v2
	v_mov_b32_e32 v83, v2
	v_mov_b32_e32 v84, v2
	v_mov_b32_e32 v85, v2
	v_mov_b32_e32 v86, v2
	v_mov_b32_e32 v87, v2
	v_mov_b32_e32 v88, v2
	v_mov_b32_e32 v89, v2
	v_mov_b32_e32 v90, v2
	v_mov_b32_e32 v91, v2
	v_mov_b32_e32 v92, v2
	v_mov_b32_e32 v93, v2
	v_mov_b32_e32 v94, v2
	v_mov_b32_e32 v95, v2
	v_mov_b32_e32 v96, v2
	v_mov_b32_e32 v97, v2
	v_mov_b32_e32 v114, v2
	v_mov_b32_e32 v115, v2
	v_mov_b32_e32 v116, v2
	v_mov_b32_e32 v117, v2
	v_mov_b32_e32 v118, v2
	v_mov_b32_e32 v119, v2
	v_mov_b32_e32 v120, v2
	v_mov_b32_e32 v121, v2
	v_mov_b32_e32 v122, v2
	v_mov_b32_e32 v123, v2
	v_mov_b32_e32 v124, v2
	v_mov_b32_e32 v125, v2
	v_mov_b32_e32 v126, v2
	v_mov_b32_e32 v127, v2
	v_mov_b32_e32 v128, v2
	v_mov_b32_e32 v129, v2
	s_branch .LBB0_696
